# all 7 GEMM K-loops: first iteration peeled so each accumulator's first MFMA takes SrcC = 0; the 128 v_mov accumulator-zeroing pass per unit is gone
# speedup vs baseline: 1.0140x; 1.0140x over previous
; #define PG8_STAGE(bufoff, gbase, voff) do { _Pragma("unroll") for (int _i = 0; _i < 2; ++_i) \
;         __builtin_amdgcn_global_load_lds((const unsigned*)((const char*)(gbase) + (voff)[_i]), (LAS unsigned*)(lds + (bufoff) + ldsw + _i * 8192), 16, 0, 0); } while (0)
; #define PG8_LDA(dst, b, h) do { _Pragma("unroll") for (int m = 0; m < 4; ++m) _Pragma("unroll") for (int k = 0; k < 2; ++k) dst[m][k] = *(const LAS bf16x8*)(lds + PG8_SA(b, h) + aoff + m * 2048 + k * 1024); } while (0)
; #define PG8_LDB(dst, b, h) do { _Pragma("unroll") for (int n = 0; n < 2; ++n) _Pragma("unroll") for (int k = 0; k < 2; ++k) dst[n][k] = *(const LAS bf16x8*)(lds + PG8_SB(b, h) + boff + n * 2048 + k * 1024); } while (0)
; #define PG8_MMA(ai, bj, At, Bt) do { __builtin_amdgcn_s_setprio(1); _Pragma("unroll") for (int m = 0; m < 4; ++m) _Pragma("unroll") for (int n = 0; n < 2; ++n) _Pragma("unroll") for (int k = 0; k < 2; ++k) \
;         acc[ai][bj][m][n] = __builtin_amdgcn_mfma_f32_16x16x32_bf16(Bt[n][k], At[m][k], acc[ai][bj][m][n], 0, 0, 0); __builtin_amdgcn_s_setprio(0); } while (0)
; #define PG8_BAR __builtin_amdgcn_s_barrier()
; template <class Epi, class Sched>
; __device__ __forceinline__ void gemm_phase(LAS unsigned char* lds, const Gemm g, const Sched& S, const Epi& E) {
;     ...
;         const bool has_next = S.next(ui + 1, nxt);
;         const char* nA = has_next ? (const char*)g.A + (size_t)nxt.pm * tstep : cA; const char* nB = has_next ? (const char*)g.Bt + (size_t)nxt.pn * tstep : cB;
;         for (int t = 0; t < nt; t += 2) {
;             const bool last = (t == nt - 2);
;             const char* a1 = cA + (size_t)(t + 1) * kstep;
;             const char* a2 = last ? nA : cA + (size_t)(t + 2) * kstep; const char* b2 = last ? nB : cB + (size_t)(t + 2) * kstep;
;             const char* a3 = a2 + kstep; const char* b3 = b2 + kstep;
;             if (last && has_next) S.a_ready(nxt);
;             PG8_LDB(B0, 0, 0); PG8_SCHED; PG8_LDA(At, 0, 0); PG8_STAGE(PG8_SA(1, 1), a1 + hstep, voffA);
;             PG8_WAIT_L(8); PG8_BAR; PG8_WAIT_L(0); PG8_MMA(0, 0, At, B0); PG8_BAR; PG8_SCHED;
;             PG8_LDB(B1, 0, 1); PG8_STAGE(PG8_SB(0, 0), b2, voffB);
;             PG8_BAR; PG8_WAIT_L(0); PG8_MMA(0, 1, At, B1); PG8_BAR;
;             PG8_LDA(At, 0, 1); PG8_STAGE(PG8_SA(0, 0), a2, voffA);
;             PG8_BAR; PG8_WAIT_L(0); PG8_MMA(1, 0, At, B0); PG8_BAR; PG8_SCHED;
.LBB0_242:
	s_ashr_i32 s15, s14, 31
	v_cmp_lt_i64_e32 vcc, s[16:17], v[142:143]
	s_lshl_b64 s[16:17], s[14:15], 20
	s_add_u32 s16, s29, s16
	s_addc_u32 s17, s30, s17
	s_and_b64 s[18:19], vcc, exec
	s_cselect_b32 s15, s17, s23
	s_cselect_b32 s47, s16, s22
	s_ashr_i32 s9, s8, 31
	s_lshl_b64 s[18:19], s[8:9], 20
	s_add_u32 s18, s50, s18
	s_addc_u32 s19, s51, s19
	s_and_b64 s[26:27], vcc, exec
	s_cselect_b32 s9, s19, s25
	s_cselect_b32 s48, s18, s24
	s_add_u32 s22, s22, 0x80080
	s_addc_u32 s23, s23, 0
	s_add_u32 s49, s24, 0x100
	s_addc_u32 s50, s25, 0
	s_mov_b32 s51, -2
	ds_read_b128 v[152:155], v148
	ds_read_b128 v[156:159], v148 offset:1024
	ds_read_b128 v[160:163], v148 offset:2048
	ds_read_b128 v[164:167], v148 offset:3072
	s_add_u32 s24, s22, 0xfff80080
	s_addc_u32 s25, s23, -1
	s_cmp_eq_u32 s51, 28
	s_cselect_b32 s27, s15, s25
	s_cselect_b32 s26, s47, s24
	s_cselect_b32 s25, s9, s50
	s_cselect_b32 s24, s48, s49
	v_lshl_add_u64 v[200:201], s[22:23], 0, v[138:139]
	s_add_i32 m0, s21, 0xc000
	ds_read_b128 v[168:171], v149
	ds_read_b128 v[172:175], v149 offset:1024
	ds_read_b128 v[176:179], v149 offset:2048
	ds_read_b128 v[180:183], v149 offset:3072
	ds_read_b128 v[184:187], v149 offset:4096
	ds_read_b128 v[188:191], v149 offset:5120
	ds_read_b128 v[192:195], v149 offset:6144
	ds_read_b128 v[196:199], v149 offset:7168
	global_load_lds_dwordx4 v[200:201], off
	v_lshl_add_u64 v[200:201], s[22:23], 0, v[140:141]
	s_add_i32 m0, s21, 0xe000
	s_nop 0
	global_load_lds_dwordx4 v[200:201], off
	s_waitcnt lgkmcnt(8)
	s_barrier
	s_waitcnt lgkmcnt(0)
	s_setprio 1
	s_waitcnt lgkmcnt(0)
	v_mfma_f32_16x16x32_bf16 v[126:129], v[152:155], v[168:171], 0
	v_mfma_f32_16x16x32_bf16 v[118:121], v[160:163], v[168:171], 0
	v_mfma_f32_16x16x32_bf16 v[110:113], v[152:155], v[176:179], 0
	v_mfma_f32_16x16x32_bf16 v[102:105], v[160:163], v[176:179], 0
	v_mfma_f32_16x16x32_bf16 v[94:97], v[152:155], v[184:187], 0
	v_mfma_f32_16x16x32_bf16 v[86:89], v[160:163], v[184:187], 0
	v_mfma_f32_16x16x32_bf16 v[78:81], v[152:155], v[192:195], 0
	v_mfma_f32_16x16x32_bf16 v[70:73], v[160:163], v[192:195], 0
	v_mfma_f32_16x16x32_bf16 v[126:129], v[156:159], v[172:175], v[126:129]
	v_mfma_f32_16x16x32_bf16 v[118:121], v[164:167], v[172:175], v[118:121]
	v_mfma_f32_16x16x32_bf16 v[110:113], v[156:159], v[180:183], v[110:113]
	v_mfma_f32_16x16x32_bf16 v[102:105], v[164:167], v[180:183], v[102:105]
	v_mfma_f32_16x16x32_bf16 v[94:97], v[156:159], v[188:191], v[94:97]
	v_mfma_f32_16x16x32_bf16 v[86:89], v[164:167], v[188:191], v[86:89]
	v_mfma_f32_16x16x32_bf16 v[78:81], v[156:159], v[196:199], v[78:81]
	v_mfma_f32_16x16x32_bf16 v[70:73], v[164:167], v[196:199], v[70:73]
	s_setprio 0
	s_barrier
	s_add_i32 s52, s43, s31
	v_lshl_add_u64 v[204:205], s[24:25], 0, v[132:133]
	s_mov_b32 m0, s52
	ds_read_b128 v[200:203], v150
	ds_read_b128 v[208:211], v150 offset:1024
	ds_read_b128 v[212:215], v150 offset:2048
	ds_read_b128 v[216:219], v150 offset:3072
	global_load_lds_dwordx4 v[204:205], off
	v_lshl_add_u64 v[220:221], s[24:25], 0, v[136:137]
	s_add_i32 m0, s52, 0x2000
	s_nop 0
	global_load_lds_dwordx4 v[220:221], off
	s_barrier
	s_waitcnt lgkmcnt(0)
	s_setprio 1
	s_waitcnt lgkmcnt(0)
	v_mfma_f32_16x16x32_bf16 v[122:125], v[200:203], v[168:171], 0
	v_mfma_f32_16x16x32_bf16 v[114:117], v[212:215], v[168:171], 0
	v_mfma_f32_16x16x32_bf16 v[106:109], v[200:203], v[176:179], 0
	v_mfma_f32_16x16x32_bf16 v[98:101], v[212:215], v[176:179], 0
	v_mfma_f32_16x16x32_bf16 v[90:93], v[200:203], v[184:187], 0
	v_mfma_f32_16x16x32_bf16 v[82:85], v[212:215], v[184:187], 0
	v_mfma_f32_16x16x32_bf16 v[74:77], v[200:203], v[192:195], 0
	v_mfma_f32_16x16x32_bf16 v[66:69], v[212:215], v[192:195], 0
	v_mfma_f32_16x16x32_bf16 v[122:125], v[208:211], v[172:175], v[122:125]
	v_mfma_f32_16x16x32_bf16 v[114:117], v[216:219], v[172:175], v[114:117]
	v_mfma_f32_16x16x32_bf16 v[106:109], v[208:211], v[180:183], v[106:109]
	v_mfma_f32_16x16x32_bf16 v[98:101], v[216:219], v[180:183], v[98:101]
	v_mfma_f32_16x16x32_bf16 v[90:93], v[208:211], v[188:191], v[90:93]
	v_mfma_f32_16x16x32_bf16 v[82:85], v[216:219], v[188:191], v[82:85]
	v_mfma_f32_16x16x32_bf16 v[74:77], v[208:211], v[196:199], v[74:77]
	v_mfma_f32_16x16x32_bf16 v[66:69], v[216:219], v[196:199], v[66:69]
	s_setprio 0
	s_mov_b32 m0, s21
	v_lshl_add_u64 v[222:223], s[26:27], 0, v[130:131]
	s_barrier
	ds_read_b128 v[168:171], v149 offset:16384
	ds_read_b128 v[172:175], v149 offset:17408
	ds_read_b128 v[176:179], v149 offset:18432
	ds_read_b128 v[180:183], v149 offset:19456
	ds_read_b128 v[184:187], v149 offset:20480
	ds_read_b128 v[188:191], v149 offset:21504
	ds_read_b128 v[192:195], v149 offset:22528
	ds_read_b128 v[196:199], v149 offset:23552
	global_load_lds_dwordx4 v[222:223], off
	v_lshl_add_u64 v[224:225], s[26:27], 0, v[134:135]
	s_mov_b32 m0, s35
	s_nop 0
	global_load_lds_dwordx4 v[224:225], off
	s_barrier
	s_waitcnt lgkmcnt(0)
	s_setprio 1
	s_waitcnt lgkmcnt(0)
	v_mfma_f32_16x16x32_bf16 v[62:65], v[152:155], v[168:171], 0
	v_mfma_f32_16x16x32_bf16 v[54:57], v[160:163], v[168:171], 0
	v_mfma_f32_16x16x32_bf16 v[46:49], v[152:155], v[176:179], 0
	v_mfma_f32_16x16x32_bf16 v[38:41], v[160:163], v[176:179], 0
	v_mfma_f32_16x16x32_bf16 v[30:33], v[152:155], v[184:187], 0
	v_mfma_f32_16x16x32_bf16 v[22:25], v[160:163], v[184:187], 0
	v_mfma_f32_16x16x32_bf16 v[14:17], v[152:155], v[192:195], 0
	v_mfma_f32_16x16x32_bf16 v[6:9], v[160:163], v[192:195], 0
	v_mfma_f32_16x16x32_bf16 v[62:65], v[156:159], v[172:175], v[62:65]
	v_mfma_f32_16x16x32_bf16 v[54:57], v[164:167], v[172:175], v[54:57]
	v_mfma_f32_16x16x32_bf16 v[46:49], v[156:159], v[180:183], v[46:49]
	v_mfma_f32_16x16x32_bf16 v[38:41], v[164:167], v[180:183], v[38:41]
	v_mfma_f32_16x16x32_bf16 v[30:33], v[156:159], v[188:191], v[30:33]
	v_mfma_f32_16x16x32_bf16 v[22:25], v[164:167], v[188:191], v[22:25]
	v_mfma_f32_16x16x32_bf16 v[14:17], v[156:159], v[196:199], v[14:17]
	v_mfma_f32_16x16x32_bf16 v[6:9], v[164:167], v[196:199], v[6:9]
	s_setprio 0
	s_barrier
; #define PG8_STAGE(bufoff, gbase, voff) do { _Pragma("unroll") for (int _i = 0; _i < 2; ++_i) \
;         __builtin_amdgcn_global_load_lds((const unsigned*)((const char*)(gbase) + (voff)[_i]), (LAS unsigned*)(lds + (bufoff) + ldsw + _i * 8192), 16, 0, 0); } while (0)
; #define PG8_LDA(dst, b, h) do { _Pragma("unroll") for (int m = 0; m < 4; ++m) _Pragma("unroll") for (int k = 0; k < 2; ++k) dst[m][k] = *(const LAS bf16x8*)(lds + PG8_SA(b, h) + aoff + m * 2048 + k * 1024); } while (0)
; #define PG8_LDB(dst, b, h) do { _Pragma("unroll") for (int n = 0; n < 2; ++n) _Pragma("unroll") for (int k = 0; k < 2; ++k) dst[n][k] = *(const LAS bf16x8*)(lds + PG8_SB(b, h) + boff + n * 2048 + k * 1024); } while (0)
; #define PG8_MMA(ai, bj, At, Bt) do { __builtin_amdgcn_s_setprio(1); _Pragma("unroll") for (int m = 0; m < 4; ++m) _Pragma("unroll") for (int n = 0; n < 2; ++n) _Pragma("unroll") for (int k = 0; k < 2; ++k) \
;         acc[ai][bj][m][n] = __builtin_amdgcn_mfma_f32_16x16x32_bf16(Bt[n][k], At[m][k], acc[ai][bj][m][n], 0, 0, 0); __builtin_amdgcn_s_setprio(0); } while (0)
; #define PG8_WAIT_V(n) asm volatile("s_waitcnt vmcnt(" #n ")" ::: "memory")
; #define PG8_WAIT_L(n) asm volatile("s_waitcnt lgkmcnt(" #n ")" ::: "memory")
; #define PG8_BAR __builtin_amdgcn_s_barrier()
; #define PG8_SCHED __builtin_amdgcn_sched_barrier(0)
; template <class Epi, class Sched>
; __device__ __forceinline__ void gemm_phase(LAS unsigned char* lds, const Gemm g, const Sched& S, const Epi& E) {
;     ...
;             PG8_STAGE(PG8_SB(0, 1), b2 + hstep, voffB);
;             PG8_WAIT_V(6); PG8_BAR; PG8_MMA(1, 1, At, B1); PG8_BAR;
;             PG8_LDB(B0, 1, 0); PG8_SCHED; PG8_LDA(At, 1, 0); PG8_STAGE(PG8_SA(0, 1), a2 + hstep, voffA);
;             PG8_WAIT_L(8); PG8_BAR; PG8_WAIT_L(0); PG8_MMA(0, 0, At, B0); PG8_BAR; PG8_SCHED;
;             PG8_LDB(B1, 1, 1); PG8_STAGE(PG8_SB(1, 0), b3, voffB);
	s_add_u32 s52, s24, 0x80000
	s_addc_u32 s53, s25, 0
	s_add_i32 s54, s44, s31
	v_lshl_add_u64 v[152:153], s[52:53], 0, v[132:133]
	s_mov_b32 m0, s54
	s_nop 0
	global_load_lds_dwordx4 v[152:153], off
	v_lshl_add_u64 v[152:153], s[52:53], 0, v[136:137]
	s_add_i32 m0, s54, 0x2000
	s_nop 0
	global_load_lds_dwordx4 v[152:153], off
	s_waitcnt vmcnt(6)
	s_barrier
	s_setprio 1
	v_mfma_f32_16x16x32_bf16 v[58:61], v[200:203], v[168:171], 0
	v_mfma_f32_16x16x32_bf16 v[50:53], v[212:215], v[168:171], 0
	v_mfma_f32_16x16x32_bf16 v[42:45], v[200:203], v[176:179], 0
	v_mfma_f32_16x16x32_bf16 v[34:37], v[212:215], v[176:179], 0
	v_mfma_f32_16x16x32_bf16 v[26:29], v[200:203], v[184:187], 0
	v_mfma_f32_16x16x32_bf16 v[18:21], v[212:215], v[184:187], 0
	v_mfma_f32_16x16x32_bf16 v[10:13], v[200:203], v[192:195], 0
	v_mfma_f32_16x16x32_bf16 v[2:5], v[212:215], v[192:195], 0
	v_mfma_f32_16x16x32_bf16 v[58:61], v[208:211], v[172:175], v[58:61]
	v_mfma_f32_16x16x32_bf16 v[50:53], v[216:219], v[172:175], v[50:53]
	v_mfma_f32_16x16x32_bf16 v[42:45], v[208:211], v[180:183], v[42:45]
	v_mfma_f32_16x16x32_bf16 v[34:37], v[216:219], v[180:183], v[34:37]
	v_mfma_f32_16x16x32_bf16 v[26:29], v[208:211], v[188:191], v[26:29]
	v_mfma_f32_16x16x32_bf16 v[18:21], v[216:219], v[188:191], v[18:21]
	v_mfma_f32_16x16x32_bf16 v[10:13], v[208:211], v[196:199], v[10:13]
	v_mfma_f32_16x16x32_bf16 v[2:5], v[216:219], v[196:199], v[2:5]
	s_setprio 0
	s_add_i32 s52, 0, 0x18000
	v_add_u32_e32 v151, s52, v146
	s_barrier
	ds_read_b128 v[152:155], v151
	ds_read_b128 v[156:159], v151 offset:1024
	ds_read_b128 v[160:163], v151 offset:2048
	ds_read_b128 v[164:167], v151 offset:3072
	s_add_u32 s26, s26, 0x80000
	s_addc_u32 s27, s27, 0
	s_mov_b32 m0, s36
	v_lshl_add_u64 v[200:201], s[26:27], 0, v[130:131]
	ds_read_b128 v[168:171], v149 offset:32768
	ds_read_b128 v[172:175], v149 offset:33792
	ds_read_b128 v[176:179], v149 offset:34816
	ds_read_b128 v[180:183], v149 offset:35840
	ds_read_b128 v[184:187], v149 offset:36864
	ds_read_b128 v[188:191], v149 offset:37888
	ds_read_b128 v[192:195], v149 offset:38912
	ds_read_b128 v[196:199], v149 offset:39936
	global_load_lds_dwordx4 v[200:201], off
	v_lshl_add_u64 v[200:201], s[26:27], 0, v[134:135]
	s_mov_b32 m0, s37
	s_nop 0
	global_load_lds_dwordx4 v[200:201], off
	s_waitcnt lgkmcnt(8)
	s_barrier
	s_waitcnt lgkmcnt(0)
	s_setprio 1
	s_waitcnt lgkmcnt(0)
	v_mfma_f32_16x16x32_bf16 v[126:129], v[152:155], v[168:171], v[126:129]
	v_mfma_f32_16x16x32_bf16 v[118:121], v[160:163], v[168:171], v[118:121]
	v_mfma_f32_16x16x32_bf16 v[110:113], v[152:155], v[176:179], v[110:113]
	v_mfma_f32_16x16x32_bf16 v[102:105], v[160:163], v[176:179], v[102:105]
	v_mfma_f32_16x16x32_bf16 v[94:97], v[152:155], v[184:187], v[94:97]
	v_mfma_f32_16x16x32_bf16 v[86:89], v[160:163], v[184:187], v[86:89]
	v_mfma_f32_16x16x32_bf16 v[78:81], v[152:155], v[192:195], v[78:81]
	v_mfma_f32_16x16x32_bf16 v[70:73], v[160:163], v[192:195], v[70:73]
	v_mfma_f32_16x16x32_bf16 v[126:129], v[156:159], v[172:175], v[126:129]
	v_mfma_f32_16x16x32_bf16 v[118:121], v[164:167], v[172:175], v[118:121]
	v_mfma_f32_16x16x32_bf16 v[110:113], v[156:159], v[180:183], v[110:113]
	v_mfma_f32_16x16x32_bf16 v[102:105], v[164:167], v[180:183], v[102:105]
	v_mfma_f32_16x16x32_bf16 v[94:97], v[156:159], v[188:191], v[94:97]
	v_mfma_f32_16x16x32_bf16 v[86:89], v[164:167], v[188:191], v[86:89]
	v_mfma_f32_16x16x32_bf16 v[78:81], v[156:159], v[196:199], v[78:81]
	v_mfma_f32_16x16x32_bf16 v[70:73], v[164:167], v[196:199], v[70:73]
	s_setprio 0
	s_barrier
	s_add_i32 s26, 0, 0x1c000
	s_add_i32 s27, s52, s31
	v_add_u32_e32 v151, s26, v146
	v_lshl_add_u64 v[204:205], v[204:205], 0, s[6:7]
	s_mov_b32 m0, s27
	ds_read_b128 v[200:203], v151
	ds_read_b128 v[208:211], v151 offset:1024
	ds_read_b128 v[212:215], v151 offset:2048
	ds_read_b128 v[216:219], v151 offset:3072
	global_load_lds_dwordx4 v[204:205], off
	v_lshl_add_u64 v[204:205], v[220:221], 0, s[6:7]
	s_add_i32 m0, s27, 0x2000
	s_nop 0
	global_load_lds_dwordx4 v[204:205], off
	s_barrier
; #define PG8_STAGE(bufoff, gbase, voff) do { _Pragma("unroll") for (int _i = 0; _i < 2; ++_i) \
;         __builtin_amdgcn_global_load_lds((const unsigned*)((const char*)(gbase) + (voff)[_i]), (LAS unsigned*)(lds + (bufoff) + ldsw + _i * 8192), 16, 0, 0); } while (0)
; #define PG8_LDA(dst, b, h) do { _Pragma("unroll") for (int m = 0; m < 4; ++m) _Pragma("unroll") for (int k = 0; k < 2; ++k) dst[m][k] = *(const LAS bf16x8*)(lds + PG8_SA(b, h) + aoff + m * 2048 + k * 1024); } while (0)
; #define PG8_MMA(ai, bj, At, Bt) do { __builtin_amdgcn_s_setprio(1); _Pragma("unroll") for (int m = 0; m < 4; ++m) _Pragma("unroll") for (int n = 0; n < 2; ++n) _Pragma("unroll") for (int k = 0; k < 2; ++k) \
;         acc[ai][bj][m][n] = __builtin_amdgcn_mfma_f32_16x16x32_bf16(Bt[n][k], At[m][k], acc[ai][bj][m][n], 0, 0, 0); __builtin_amdgcn_s_setprio(0); } while (0)
; #define PG8_WAIT_V(n) asm volatile("s_waitcnt vmcnt(" #n ")" ::: "memory")
; #define PG8_WAIT_L(n) asm volatile("s_waitcnt lgkmcnt(" #n ")" ::: "memory")
; #define PG8_BAR __builtin_amdgcn_s_barrier()
; #define PG8_SCHED __builtin_amdgcn_sched_barrier(0)
; template <class Epi, class Sched>
; __device__ __forceinline__ void gemm_phase(LAS unsigned char* lds, const Gemm g, const Sched& S, const Epi& E) {
;     ...
;             PG8_BAR; PG8_WAIT_L(0); PG8_MMA(0, 1, At, B1); PG8_BAR;
;             PG8_LDA(At, 1, 1); PG8_STAGE(PG8_SA(1, 0), a3, voffA);
;             PG8_BAR; PG8_WAIT_L(0); PG8_MMA(1, 0, At, B0); PG8_BAR; PG8_SCHED;
;             PG8_STAGE(PG8_SB(1, 1), b3 + hstep, voffB);
;             PG8_WAIT_V(6); PG8_BAR; PG8_MMA(1, 1, At, B1); PG8_BAR;
;         }
	s_waitcnt lgkmcnt(0)
	s_setprio 1
	s_waitcnt lgkmcnt(0)
	v_mfma_f32_16x16x32_bf16 v[122:125], v[200:203], v[168:171], v[122:125]
	v_mfma_f32_16x16x32_bf16 v[114:117], v[212:215], v[168:171], v[114:117]
	v_mfma_f32_16x16x32_bf16 v[106:109], v[200:203], v[176:179], v[106:109]
	v_mfma_f32_16x16x32_bf16 v[98:101], v[212:215], v[176:179], v[98:101]
	v_mfma_f32_16x16x32_bf16 v[90:93], v[200:203], v[184:187], v[90:93]
	v_mfma_f32_16x16x32_bf16 v[82:85], v[212:215], v[184:187], v[82:85]
	v_mfma_f32_16x16x32_bf16 v[74:77], v[200:203], v[192:195], v[74:77]
	v_mfma_f32_16x16x32_bf16 v[66:69], v[212:215], v[192:195], v[66:69]
	v_mfma_f32_16x16x32_bf16 v[122:125], v[208:211], v[172:175], v[122:125]
	v_mfma_f32_16x16x32_bf16 v[114:117], v[216:219], v[172:175], v[114:117]
	v_mfma_f32_16x16x32_bf16 v[106:109], v[208:211], v[180:183], v[106:109]
	v_mfma_f32_16x16x32_bf16 v[98:101], v[216:219], v[180:183], v[98:101]
	v_mfma_f32_16x16x32_bf16 v[90:93], v[208:211], v[188:191], v[90:93]
	v_mfma_f32_16x16x32_bf16 v[82:85], v[216:219], v[188:191], v[82:85]
	v_mfma_f32_16x16x32_bf16 v[74:77], v[208:211], v[196:199], v[74:77]
	v_mfma_f32_16x16x32_bf16 v[66:69], v[216:219], v[196:199], v[66:69]
	s_setprio 0
	s_mov_b32 m0, s40
	v_lshl_add_u64 v[204:205], v[222:223], 0, s[6:7]
	s_barrier
	ds_read_b128 v[168:171], v149 offset:49152
	ds_read_b128 v[172:175], v149 offset:50176
	ds_read_b128 v[176:179], v149 offset:51200
	ds_read_b128 v[180:183], v149 offset:52224
	ds_read_b128 v[184:187], v149 offset:53248
	ds_read_b128 v[188:191], v149 offset:54272
	ds_read_b128 v[192:195], v149 offset:55296
	ds_read_b128 v[196:199], v149 offset:56320
	global_load_lds_dwordx4 v[204:205], off
	v_lshl_add_u64 v[204:205], v[224:225], 0, s[6:7]
	s_mov_b32 m0, s41
	s_nop 0
	global_load_lds_dwordx4 v[204:205], off
	s_barrier
	s_waitcnt lgkmcnt(0)
	s_setprio 1
	s_waitcnt lgkmcnt(0)
	v_mfma_f32_16x16x32_bf16 v[62:65], v[152:155], v[168:171], v[62:65]
	v_mfma_f32_16x16x32_bf16 v[54:57], v[160:163], v[168:171], v[54:57]
	v_mfma_f32_16x16x32_bf16 v[46:49], v[152:155], v[176:179], v[46:49]
	v_mfma_f32_16x16x32_bf16 v[38:41], v[160:163], v[176:179], v[38:41]
	v_mfma_f32_16x16x32_bf16 v[30:33], v[152:155], v[184:187], v[30:33]
	v_mfma_f32_16x16x32_bf16 v[22:25], v[160:163], v[184:187], v[22:25]
	v_mfma_f32_16x16x32_bf16 v[14:17], v[152:155], v[192:195], v[14:17]
	v_mfma_f32_16x16x32_bf16 v[6:9], v[160:163], v[192:195], v[6:9]
	v_mfma_f32_16x16x32_bf16 v[62:65], v[156:159], v[172:175], v[62:65]
	v_mfma_f32_16x16x32_bf16 v[54:57], v[164:167], v[172:175], v[54:57]
	v_mfma_f32_16x16x32_bf16 v[46:49], v[156:159], v[180:183], v[46:49]
	v_mfma_f32_16x16x32_bf16 v[38:41], v[164:167], v[180:183], v[38:41]
	v_mfma_f32_16x16x32_bf16 v[30:33], v[156:159], v[188:191], v[30:33]
	v_mfma_f32_16x16x32_bf16 v[22:25], v[164:167], v[188:191], v[22:25]
	v_mfma_f32_16x16x32_bf16 v[14:17], v[156:159], v[196:199], v[14:17]
	v_mfma_f32_16x16x32_bf16 v[6:9], v[164:167], v[196:199], v[6:9]
	s_setprio 0
	s_barrier
	s_add_u32 s24, s24, 0x80080
	s_addc_u32 s25, s25, 0
	s_add_i32 s26, s26, s31
	v_lshl_add_u64 v[152:153], s[24:25], 0, v[132:133]
	s_mov_b32 m0, s26
	s_nop 0
	global_load_lds_dwordx4 v[152:153], off
	v_lshl_add_u64 v[152:153], s[24:25], 0, v[136:137]
	s_add_i32 m0, s26, 0x2000
	s_nop 0
	global_load_lds_dwordx4 v[152:153], off
	s_waitcnt vmcnt(6)
	s_barrier
	s_setprio 1
	v_mfma_f32_16x16x32_bf16 v[58:61], v[200:203], v[168:171], v[58:61]
	v_mfma_f32_16x16x32_bf16 v[50:53], v[212:215], v[168:171], v[50:53]
	v_mfma_f32_16x16x32_bf16 v[42:45], v[200:203], v[176:179], v[42:45]
	v_mfma_f32_16x16x32_bf16 v[34:37], v[212:215], v[176:179], v[34:37]
	v_mfma_f32_16x16x32_bf16 v[26:29], v[200:203], v[184:187], v[26:29]
	v_mfma_f32_16x16x32_bf16 v[18:21], v[212:215], v[184:187], v[18:21]
	v_mfma_f32_16x16x32_bf16 v[10:13], v[200:203], v[192:195], v[10:13]
	v_mfma_f32_16x16x32_bf16 v[2:5], v[212:215], v[192:195], v[2:5]
	v_mfma_f32_16x16x32_bf16 v[58:61], v[208:211], v[172:175], v[58:61]
	v_mfma_f32_16x16x32_bf16 v[50:53], v[216:219], v[172:175], v[50:53]
	v_mfma_f32_16x16x32_bf16 v[42:45], v[208:211], v[180:183], v[42:45]
	v_mfma_f32_16x16x32_bf16 v[34:37], v[216:219], v[180:183], v[34:37]
	v_mfma_f32_16x16x32_bf16 v[26:29], v[208:211], v[188:191], v[26:29]
	v_mfma_f32_16x16x32_bf16 v[18:21], v[216:219], v[188:191], v[18:21]
	v_mfma_f32_16x16x32_bf16 v[10:13], v[208:211], v[196:199], v[10:13]
	v_mfma_f32_16x16x32_bf16 v[2:5], v[216:219], v[196:199], v[2:5]
	s_setprio 0
	s_add_i32 s51, s51, 2
	s_add_u32 s22, s22, 0x100
	s_addc_u32 s23, s23, 0
	s_add_u32 s49, s49, 0x100
	s_addc_u32 s50, s50, 0
	s_cmp_gt_u32 s51, 29
	s_barrier

; #define PG8_STAGE(bufoff, gbase, voff) do { _Pragma("unroll") for (int _i = 0; _i < 2; ++_i) \
;         __builtin_amdgcn_global_load_lds((const unsigned*)((const char*)(gbase) + (voff)[_i]), (LAS unsigned*)(lds + (bufoff) + ldsw + _i * 8192), 16, 0, 0); } while (0)
; #define PG8_LDA(dst, b, h) do { _Pragma("unroll") for (int m = 0; m < 4; ++m) _Pragma("unroll") for (int k = 0; k < 2; ++k) dst[m][k] = *(const LAS bf16x8*)(lds + PG8_SA(b, h) + aoff + m * 2048 + k * 1024); } while (0)
; #define PG8_LDB(dst, b, h) do { _Pragma("unroll") for (int n = 0; n < 2; ++n) _Pragma("unroll") for (int k = 0; k < 2; ++k) dst[n][k] = *(const LAS bf16x8*)(lds + PG8_SB(b, h) + boff + n * 2048 + k * 1024); } while (0)
; #define PG8_MMA(ai, bj, At, Bt) do { __builtin_amdgcn_s_setprio(1); _Pragma("unroll") for (int m = 0; m < 4; ++m) _Pragma("unroll") for (int n = 0; n < 2; ++n) _Pragma("unroll") for (int k = 0; k < 2; ++k) \
;         acc[ai][bj][m][n] = __builtin_amdgcn_mfma_f32_16x16x32_bf16(Bt[n][k], At[m][k], acc[ai][bj][m][n], 0, 0, 0); __builtin_amdgcn_s_setprio(0); } while (0)
; #define PG8_BAR __builtin_amdgcn_s_barrier()
; template <class Epi, class Sched>
; __device__ __forceinline__ void gemm_phase(LAS unsigned char* lds, const Gemm g, const Sched& S, const Epi& E) {
;     ...
;         const bool has_next = S.next(ui + 1, nxt);
;         const char* nA = has_next ? (const char*)g.A + (size_t)nxt.pm * tstep : cA; const char* nB = has_next ? (const char*)g.Bt + (size_t)nxt.pn * tstep : cB;
;         for (int t = 0; t < nt; t += 2) {
;             const bool last = (t == nt - 2);
;             const char* a1 = cA + (size_t)(t + 1) * kstep;
;             const char* a2 = last ? nA : cA + (size_t)(t + 2) * kstep; const char* b2 = last ? nB : cB + (size_t)(t + 2) * kstep;
;             const char* a3 = a2 + kstep; const char* b3 = b2 + kstep;
;             if (last && has_next) S.a_ready(nxt);
;             PG8_LDB(B0, 0, 0); PG8_SCHED; PG8_LDA(At, 0, 0); PG8_STAGE(PG8_SA(1, 1), a1 + hstep, voffA);
;             PG8_WAIT_L(8); PG8_BAR; PG8_WAIT_L(0); PG8_MMA(0, 0, At, B0); PG8_BAR; PG8_SCHED;
;             PG8_LDB(B1, 0, 1); PG8_STAGE(PG8_SB(0, 0), b2, voffB);
;             PG8_BAR; PG8_WAIT_L(0); PG8_MMA(0, 1, At, B1); PG8_BAR;
;             PG8_LDA(At, 0, 1); PG8_STAGE(PG8_SA(0, 0), a2, voffA);
;             PG8_BAR; PG8_WAIT_L(0); PG8_MMA(1, 0, At, B0); PG8_BAR; PG8_SCHED;
.LBB0_334:
	s_add_u32 s18, s18, 0x160080
	s_addc_u32 s19, s19, 0
	s_add_u32 s47, s20, 0x100
	s_addc_u32 s48, s21, 0
	s_mov_b32 s49, -2
	s_waitcnt lgkmcnt(0)
	ds_read_b128 v[130:133], v209
	ds_read_b128 v[134:137], v209 offset:1024
	ds_read_b128 v[138:141], v209 offset:2048
	ds_read_b128 v[142:145], v209 offset:3072
	s_add_u32 s20, s18, 0xffea0080
	s_addc_u32 s21, s19, -1
	s_cmpk_eq_i32 s49, 0x54
	s_cselect_b32 s23, s9, s21
	s_cselect_b32 s22, s8, s20
	s_cselect_b32 s21, s1, s48
	s_cselect_b32 s20, s0, s47
	v_lshl_add_u64 v[194:195], s[18:19], 0, v[186:187]
	s_add_i32 m0, s30, 0xc000
	ds_read_b128 v[146:149], v210
	ds_read_b128 v[150:153], v210 offset:1024
	ds_read_b128 v[154:157], v210 offset:2048
	ds_read_b128 v[158:161], v210 offset:3072
	ds_read_b128 v[162:165], v210 offset:4096
	ds_read_b128 v[166:169], v210 offset:5120
	ds_read_b128 v[170:173], v210 offset:6144
	ds_read_b128 v[174:177], v210 offset:7168
	global_load_lds_dwordx4 v[194:195], off
	v_lshl_add_u64 v[194:195], s[18:19], 0, v[188:189]
	s_add_i32 m0, s30, 0xe000
	s_nop 0
	global_load_lds_dwordx4 v[194:195], off
	s_waitcnt lgkmcnt(8)
	s_barrier
	s_waitcnt lgkmcnt(0)
	s_setprio 1
	s_waitcnt lgkmcnt(0)
	v_mfma_f32_16x16x32_bf16 v[126:129], v[130:133], v[146:149], 0
	v_mfma_f32_16x16x32_bf16 v[122:125], v[138:141], v[146:149], 0
	v_mfma_f32_16x16x32_bf16 v[110:113], v[130:133], v[154:157], 0
	v_mfma_f32_16x16x32_bf16 v[106:109], v[138:141], v[154:157], 0
	v_mfma_f32_16x16x32_bf16 v[94:97], v[130:133], v[162:165], 0
	v_mfma_f32_16x16x32_bf16 v[90:93], v[138:141], v[162:165], 0
	v_mfma_f32_16x16x32_bf16 v[78:81], v[130:133], v[170:173], 0
	v_mfma_f32_16x16x32_bf16 v[74:77], v[138:141], v[170:173], 0
	v_mfma_f32_16x16x32_bf16 v[126:129], v[134:137], v[150:153], v[126:129]
	v_mfma_f32_16x16x32_bf16 v[122:125], v[142:145], v[150:153], v[122:125]
	v_mfma_f32_16x16x32_bf16 v[110:113], v[134:137], v[158:161], v[110:113]
	v_mfma_f32_16x16x32_bf16 v[106:109], v[142:145], v[158:161], v[106:109]
	v_mfma_f32_16x16x32_bf16 v[94:97], v[134:137], v[166:169], v[94:97]
	v_mfma_f32_16x16x32_bf16 v[90:93], v[142:145], v[166:169], v[90:93]
	v_mfma_f32_16x16x32_bf16 v[78:81], v[134:137], v[174:177], v[78:81]
	v_mfma_f32_16x16x32_bf16 v[74:77], v[142:145], v[174:177], v[74:77]
	s_setprio 0
	s_barrier
	s_add_i32 s50, s41, s29
	v_lshl_add_u64 v[218:219], s[20:21], 0, v[180:181]
	s_mov_b32 m0, s50
	ds_read_b128 v[194:197], v211
	ds_read_b128 v[198:201], v211 offset:1024
	ds_read_b128 v[202:205], v211 offset:2048
	ds_read_b128 v[214:217], v211 offset:3072
	global_load_lds_dwordx4 v[218:219], off
	v_lshl_add_u64 v[220:221], s[20:21], 0, v[184:185]
	s_add_i32 m0, s50, 0x2000
	s_nop 0
	global_load_lds_dwordx4 v[220:221], off
	s_barrier
	s_waitcnt lgkmcnt(0)
	s_setprio 1
	s_waitcnt lgkmcnt(0)
	v_mfma_f32_16x16x32_bf16 v[118:121], v[194:197], v[146:149], 0
	v_mfma_f32_16x16x32_bf16 v[114:117], v[202:205], v[146:149], 0
	v_mfma_f32_16x16x32_bf16 v[102:105], v[194:197], v[154:157], 0
	v_mfma_f32_16x16x32_bf16 v[98:101], v[202:205], v[154:157], 0
	v_mfma_f32_16x16x32_bf16 v[86:89], v[194:197], v[162:165], 0
	v_mfma_f32_16x16x32_bf16 v[82:85], v[202:205], v[162:165], 0
	v_mfma_f32_16x16x32_bf16 v[70:73], v[194:197], v[170:173], 0
	v_mfma_f32_16x16x32_bf16 v[66:69], v[202:205], v[170:173], 0
	v_mfma_f32_16x16x32_bf16 v[118:121], v[198:201], v[150:153], v[118:121]
	v_mfma_f32_16x16x32_bf16 v[114:117], v[214:217], v[150:153], v[114:117]
	v_mfma_f32_16x16x32_bf16 v[102:105], v[198:201], v[158:161], v[102:105]
	v_mfma_f32_16x16x32_bf16 v[98:101], v[214:217], v[158:161], v[98:101]
	v_mfma_f32_16x16x32_bf16 v[86:89], v[198:201], v[166:169], v[86:89]
	v_mfma_f32_16x16x32_bf16 v[82:85], v[214:217], v[166:169], v[82:85]
	v_mfma_f32_16x16x32_bf16 v[70:73], v[198:201], v[174:177], v[70:73]
	v_mfma_f32_16x16x32_bf16 v[66:69], v[214:217], v[174:177], v[66:69]
	s_setprio 0
	s_mov_b32 m0, s30
	v_lshl_add_u64 v[222:223], s[22:23], 0, v[178:179]
	s_barrier
	ds_read_b128 v[146:149], v210 offset:16384
	ds_read_b128 v[150:153], v210 offset:17408
	ds_read_b128 v[154:157], v210 offset:18432
	ds_read_b128 v[158:161], v210 offset:19456
	ds_read_b128 v[162:165], v210 offset:20480
	ds_read_b128 v[166:169], v210 offset:21504
	ds_read_b128 v[170:173], v210 offset:22528
	ds_read_b128 v[174:177], v210 offset:23552
	global_load_lds_dwordx4 v[222:223], off
	v_lshl_add_u64 v[224:225], s[22:23], 0, v[182:183]
	s_mov_b32 m0, s31
	s_nop 0
	global_load_lds_dwordx4 v[224:225], off
	s_barrier
	s_waitcnt lgkmcnt(0)
	s_setprio 1
	s_waitcnt lgkmcnt(0)
	v_mfma_f32_16x16x32_bf16 v[62:65], v[130:133], v[146:149], 0
	v_mfma_f32_16x16x32_bf16 v[58:61], v[138:141], v[146:149], 0
	v_mfma_f32_16x16x32_bf16 v[46:49], v[130:133], v[154:157], 0
	v_mfma_f32_16x16x32_bf16 v[42:45], v[138:141], v[154:157], 0
	v_mfma_f32_16x16x32_bf16 v[30:33], v[130:133], v[162:165], 0
	v_mfma_f32_16x16x32_bf16 v[26:29], v[138:141], v[162:165], 0
	v_mfma_f32_16x16x32_bf16 v[14:17], v[130:133], v[170:173], 0
	v_mfma_f32_16x16x32_bf16 v[10:13], v[138:141], v[170:173], 0
	v_mfma_f32_16x16x32_bf16 v[62:65], v[134:137], v[150:153], v[62:65]
	v_mfma_f32_16x16x32_bf16 v[58:61], v[142:145], v[150:153], v[58:61]
	v_mfma_f32_16x16x32_bf16 v[46:49], v[134:137], v[158:161], v[46:49]
	v_mfma_f32_16x16x32_bf16 v[42:45], v[142:145], v[158:161], v[42:45]
	v_mfma_f32_16x16x32_bf16 v[30:33], v[134:137], v[166:169], v[30:33]
	v_mfma_f32_16x16x32_bf16 v[26:29], v[142:145], v[166:169], v[26:29]
	v_mfma_f32_16x16x32_bf16 v[14:17], v[134:137], v[174:177], v[14:17]
	v_mfma_f32_16x16x32_bf16 v[10:13], v[142:145], v[174:177], v[10:13]
	s_setprio 0
	s_barrier
; #define PG8_STAGE(bufoff, gbase, voff) do { _Pragma("unroll") for (int _i = 0; _i < 2; ++_i) \
;         __builtin_amdgcn_global_load_lds((const unsigned*)((const char*)(gbase) + (voff)[_i]), (LAS unsigned*)(lds + (bufoff) + ldsw + _i * 8192), 16, 0, 0); } while (0)
; #define PG8_LDA(dst, b, h) do { _Pragma("unroll") for (int m = 0; m < 4; ++m) _Pragma("unroll") for (int k = 0; k < 2; ++k) dst[m][k] = *(const LAS bf16x8*)(lds + PG8_SA(b, h) + aoff + m * 2048 + k * 1024); } while (0)
; #define PG8_LDB(dst, b, h) do { _Pragma("unroll") for (int n = 0; n < 2; ++n) _Pragma("unroll") for (int k = 0; k < 2; ++k) dst[n][k] = *(const LAS bf16x8*)(lds + PG8_SB(b, h) + boff + n * 2048 + k * 1024); } while (0)
; #define PG8_MMA(ai, bj, At, Bt) do { __builtin_amdgcn_s_setprio(1); _Pragma("unroll") for (int m = 0; m < 4; ++m) _Pragma("unroll") for (int n = 0; n < 2; ++n) _Pragma("unroll") for (int k = 0; k < 2; ++k) \
;         acc[ai][bj][m][n] = __builtin_amdgcn_mfma_f32_16x16x32_bf16(Bt[n][k], At[m][k], acc[ai][bj][m][n], 0, 0, 0); __builtin_amdgcn_s_setprio(0); } while (0)
; #define PG8_WAIT_V(n) asm volatile("s_waitcnt vmcnt(" #n ")" ::: "memory")
; #define PG8_WAIT_L(n) asm volatile("s_waitcnt lgkmcnt(" #n ")" ::: "memory")
; #define PG8_BAR __builtin_amdgcn_s_barrier()
; #define PG8_SCHED __builtin_amdgcn_sched_barrier(0)
; template <class Epi, class Sched>
; __device__ __forceinline__ void gemm_phase(LAS unsigned char* lds, const Gemm g, const Sched& S, const Epi& E) {
;     ...
;             PG8_STAGE(PG8_SB(0, 1), b2 + hstep, voffB);
;             PG8_WAIT_V(6); PG8_BAR; PG8_MMA(1, 1, At, B1); PG8_BAR;
;             PG8_LDB(B0, 1, 0); PG8_SCHED; PG8_LDA(At, 1, 0); PG8_STAGE(PG8_SA(0, 1), a2 + hstep, voffA);
;             PG8_WAIT_L(8); PG8_BAR; PG8_WAIT_L(0); PG8_MMA(0, 0, At, B0); PG8_BAR; PG8_SCHED;
;             PG8_LDB(B1, 1, 1); PG8_STAGE(PG8_SB(1, 0), b3, voffB);
	s_add_u32 s50, s20, 0x160000
	s_addc_u32 s51, s21, 0
	s_add_i32 s52, s42, s29
	v_lshl_add_u64 v[130:131], s[50:51], 0, v[180:181]
	s_mov_b32 m0, s52
	s_nop 0
	global_load_lds_dwordx4 v[130:131], off
	v_lshl_add_u64 v[130:131], s[50:51], 0, v[184:185]
	s_add_i32 m0, s52, 0x2000
	s_nop 0
	global_load_lds_dwordx4 v[130:131], off
	s_waitcnt vmcnt(6)
	s_barrier
	s_setprio 1
	v_mfma_f32_16x16x32_bf16 v[54:57], v[194:197], v[146:149], 0
	v_mfma_f32_16x16x32_bf16 v[50:53], v[202:205], v[146:149], 0
	v_mfma_f32_16x16x32_bf16 v[38:41], v[194:197], v[154:157], 0
	v_mfma_f32_16x16x32_bf16 v[34:37], v[202:205], v[154:157], 0
	v_mfma_f32_16x16x32_bf16 v[22:25], v[194:197], v[162:165], 0
	v_mfma_f32_16x16x32_bf16 v[18:21], v[202:205], v[162:165], 0
	v_mfma_f32_16x16x32_bf16 v[6:9], v[194:197], v[170:173], 0
	v_mfma_f32_16x16x32_bf16 v[2:5], v[202:205], v[170:173], 0
	v_mfma_f32_16x16x32_bf16 v[54:57], v[198:201], v[150:153], v[54:57]
	v_mfma_f32_16x16x32_bf16 v[50:53], v[214:217], v[150:153], v[50:53]
	v_mfma_f32_16x16x32_bf16 v[38:41], v[198:201], v[158:161], v[38:41]
	v_mfma_f32_16x16x32_bf16 v[34:37], v[214:217], v[158:161], v[34:37]
	v_mfma_f32_16x16x32_bf16 v[22:25], v[198:201], v[166:169], v[22:25]
	v_mfma_f32_16x16x32_bf16 v[18:21], v[214:217], v[166:169], v[18:21]
	v_mfma_f32_16x16x32_bf16 v[6:9], v[198:201], v[174:177], v[6:9]
	v_mfma_f32_16x16x32_bf16 v[2:5], v[214:217], v[174:177], v[2:5]
	s_setprio 0
	s_add_i32 s50, 0, 0x18000
	v_add_u32_e32 v142, s50, v207
	s_barrier
	ds_read_b128 v[130:133], v142
	ds_read_b128 v[134:137], v142 offset:1024
	ds_read_b128 v[138:141], v142 offset:2048
	ds_read_b128 v[142:145], v142 offset:3072
	s_add_u32 s22, s22, 0x160000
	s_addc_u32 s23, s23, 0
	s_mov_b32 m0, s33
	v_lshl_add_u64 v[194:195], s[22:23], 0, v[178:179]
	ds_read_b128 v[146:149], v210 offset:32768
	ds_read_b128 v[150:153], v210 offset:33792
	ds_read_b128 v[154:157], v210 offset:34816
	ds_read_b128 v[158:161], v210 offset:35840
	ds_read_b128 v[162:165], v210 offset:36864
	ds_read_b128 v[166:169], v210 offset:37888
	ds_read_b128 v[170:173], v210 offset:38912
	ds_read_b128 v[174:177], v210 offset:39936
	global_load_lds_dwordx4 v[194:195], off
	v_lshl_add_u64 v[194:195], s[22:23], 0, v[182:183]
	s_mov_b32 m0, s34
	s_nop 0
	global_load_lds_dwordx4 v[194:195], off
	s_waitcnt lgkmcnt(8)
	s_barrier
	s_waitcnt lgkmcnt(0)
	s_setprio 1
	s_waitcnt lgkmcnt(0)
	v_mfma_f32_16x16x32_bf16 v[126:129], v[130:133], v[146:149], v[126:129]
	v_mfma_f32_16x16x32_bf16 v[122:125], v[138:141], v[146:149], v[122:125]
	v_mfma_f32_16x16x32_bf16 v[110:113], v[130:133], v[154:157], v[110:113]
	v_mfma_f32_16x16x32_bf16 v[106:109], v[138:141], v[154:157], v[106:109]
	v_mfma_f32_16x16x32_bf16 v[94:97], v[130:133], v[162:165], v[94:97]
	v_mfma_f32_16x16x32_bf16 v[90:93], v[138:141], v[162:165], v[90:93]
	v_mfma_f32_16x16x32_bf16 v[78:81], v[130:133], v[170:173], v[78:81]
	v_mfma_f32_16x16x32_bf16 v[74:77], v[138:141], v[170:173], v[74:77]
	v_mfma_f32_16x16x32_bf16 v[126:129], v[134:137], v[150:153], v[126:129]
	v_mfma_f32_16x16x32_bf16 v[122:125], v[142:145], v[150:153], v[122:125]
	v_mfma_f32_16x16x32_bf16 v[110:113], v[134:137], v[158:161], v[110:113]
	v_mfma_f32_16x16x32_bf16 v[106:109], v[142:145], v[158:161], v[106:109]
	v_mfma_f32_16x16x32_bf16 v[94:97], v[134:137], v[166:169], v[94:97]
	v_mfma_f32_16x16x32_bf16 v[90:93], v[142:145], v[166:169], v[90:93]
	v_mfma_f32_16x16x32_bf16 v[78:81], v[134:137], v[174:177], v[78:81]
	v_mfma_f32_16x16x32_bf16 v[74:77], v[142:145], v[174:177], v[74:77]
	s_setprio 0
	s_barrier
	s_add_i32 s22, 0, 0x1c000
	s_add_i32 s23, s50, s29
	v_add_u32_e32 v213, s22, v207
	v_lshl_add_u64 v[218:219], v[218:219], 0, s[16:17]
	s_mov_b32 m0, s23
	ds_read_b128 v[194:197], v213
	ds_read_b128 v[198:201], v213 offset:1024
	ds_read_b128 v[202:205], v213 offset:2048
	ds_read_b128 v[214:217], v213 offset:3072
	global_load_lds_dwordx4 v[218:219], off
	v_lshl_add_u64 v[218:219], v[220:221], 0, s[16:17]
	s_add_i32 m0, s23, 0x2000
	s_nop 0
	global_load_lds_dwordx4 v[218:219], off
	s_barrier
; #define PG8_STAGE(bufoff, gbase, voff) do { _Pragma("unroll") for (int _i = 0; _i < 2; ++_i) \
;         __builtin_amdgcn_global_load_lds((const unsigned*)((const char*)(gbase) + (voff)[_i]), (LAS unsigned*)(lds + (bufoff) + ldsw + _i * 8192), 16, 0, 0); } while (0)
; #define PG8_LDA(dst, b, h) do { _Pragma("unroll") for (int m = 0; m < 4; ++m) _Pragma("unroll") for (int k = 0; k < 2; ++k) dst[m][k] = *(const LAS bf16x8*)(lds + PG8_SA(b, h) + aoff + m * 2048 + k * 1024); } while (0)
; #define PG8_MMA(ai, bj, At, Bt) do { __builtin_amdgcn_s_setprio(1); _Pragma("unroll") for (int m = 0; m < 4; ++m) _Pragma("unroll") for (int n = 0; n < 2; ++n) _Pragma("unroll") for (int k = 0; k < 2; ++k) \
;         acc[ai][bj][m][n] = __builtin_amdgcn_mfma_f32_16x16x32_bf16(Bt[n][k], At[m][k], acc[ai][bj][m][n], 0, 0, 0); __builtin_amdgcn_s_setprio(0); } while (0)
; #define PG8_WAIT_V(n) asm volatile("s_waitcnt vmcnt(" #n ")" ::: "memory")
; #define PG8_WAIT_L(n) asm volatile("s_waitcnt lgkmcnt(" #n ")" ::: "memory")
; #define PG8_BAR __builtin_amdgcn_s_barrier()
; #define PG8_SCHED __builtin_amdgcn_sched_barrier(0)
; template <class Epi, class Sched>
; __device__ __forceinline__ void gemm_phase(LAS unsigned char* lds, const Gemm g, const Sched& S, const Epi& E) {
;     ...
;             PG8_BAR; PG8_WAIT_L(0); PG8_MMA(0, 1, At, B1); PG8_BAR;
;             PG8_LDA(At, 1, 1); PG8_STAGE(PG8_SA(1, 0), a3, voffA);
;             PG8_BAR; PG8_WAIT_L(0); PG8_MMA(1, 0, At, B0); PG8_BAR; PG8_SCHED;
;             PG8_STAGE(PG8_SB(1, 1), b3 + hstep, voffB);
;             PG8_WAIT_V(6); PG8_BAR; PG8_MMA(1, 1, At, B1); PG8_BAR;
;         }
	s_waitcnt lgkmcnt(0)
	s_setprio 1
	s_waitcnt lgkmcnt(0)
	v_mfma_f32_16x16x32_bf16 v[118:121], v[194:197], v[146:149], v[118:121]
	v_mfma_f32_16x16x32_bf16 v[114:117], v[202:205], v[146:149], v[114:117]
	v_mfma_f32_16x16x32_bf16 v[102:105], v[194:197], v[154:157], v[102:105]
	v_mfma_f32_16x16x32_bf16 v[98:101], v[202:205], v[154:157], v[98:101]
	v_mfma_f32_16x16x32_bf16 v[86:89], v[194:197], v[162:165], v[86:89]
	v_mfma_f32_16x16x32_bf16 v[82:85], v[202:205], v[162:165], v[82:85]
	v_mfma_f32_16x16x32_bf16 v[70:73], v[194:197], v[170:173], v[70:73]
	v_mfma_f32_16x16x32_bf16 v[66:69], v[202:205], v[170:173], v[66:69]
	v_mfma_f32_16x16x32_bf16 v[118:121], v[198:201], v[150:153], v[118:121]
	v_mfma_f32_16x16x32_bf16 v[114:117], v[214:217], v[150:153], v[114:117]
	v_mfma_f32_16x16x32_bf16 v[102:105], v[198:201], v[158:161], v[102:105]
	v_mfma_f32_16x16x32_bf16 v[98:101], v[214:217], v[158:161], v[98:101]
	v_mfma_f32_16x16x32_bf16 v[86:89], v[198:201], v[166:169], v[86:89]
	v_mfma_f32_16x16x32_bf16 v[82:85], v[214:217], v[166:169], v[82:85]
	v_mfma_f32_16x16x32_bf16 v[70:73], v[198:201], v[174:177], v[70:73]
	v_mfma_f32_16x16x32_bf16 v[66:69], v[214:217], v[174:177], v[66:69]
	s_setprio 0
	s_mov_b32 m0, s38
	v_lshl_add_u64 v[218:219], v[222:223], 0, s[16:17]
	s_barrier
	ds_read_b128 v[146:149], v210 offset:49152
	ds_read_b128 v[150:153], v210 offset:50176
	ds_read_b128 v[154:157], v210 offset:51200
	ds_read_b128 v[158:161], v210 offset:52224
	ds_read_b128 v[162:165], v210 offset:53248
	ds_read_b128 v[166:169], v210 offset:54272
	ds_read_b128 v[170:173], v210 offset:55296
	ds_read_b128 v[174:177], v210 offset:56320
	global_load_lds_dwordx4 v[218:219], off
	v_lshl_add_u64 v[218:219], v[224:225], 0, s[16:17]
	s_mov_b32 m0, s39
	s_nop 0
	global_load_lds_dwordx4 v[218:219], off
	s_barrier
	s_waitcnt lgkmcnt(0)
	s_setprio 1
	s_waitcnt lgkmcnt(0)
	v_mfma_f32_16x16x32_bf16 v[62:65], v[130:133], v[146:149], v[62:65]
	v_mfma_f32_16x16x32_bf16 v[58:61], v[138:141], v[146:149], v[58:61]
	v_mfma_f32_16x16x32_bf16 v[46:49], v[130:133], v[154:157], v[46:49]
	v_mfma_f32_16x16x32_bf16 v[42:45], v[138:141], v[154:157], v[42:45]
	v_mfma_f32_16x16x32_bf16 v[30:33], v[130:133], v[162:165], v[30:33]
	v_mfma_f32_16x16x32_bf16 v[26:29], v[138:141], v[162:165], v[26:29]
	v_mfma_f32_16x16x32_bf16 v[14:17], v[130:133], v[170:173], v[14:17]
	v_mfma_f32_16x16x32_bf16 v[10:13], v[138:141], v[170:173], v[10:13]
	v_mfma_f32_16x16x32_bf16 v[62:65], v[134:137], v[150:153], v[62:65]
	v_mfma_f32_16x16x32_bf16 v[58:61], v[142:145], v[150:153], v[58:61]
	v_mfma_f32_16x16x32_bf16 v[46:49], v[134:137], v[158:161], v[46:49]
	v_mfma_f32_16x16x32_bf16 v[42:45], v[142:145], v[158:161], v[42:45]
	v_mfma_f32_16x16x32_bf16 v[30:33], v[134:137], v[166:169], v[30:33]
	v_mfma_f32_16x16x32_bf16 v[26:29], v[142:145], v[166:169], v[26:29]
	v_mfma_f32_16x16x32_bf16 v[14:17], v[134:137], v[174:177], v[14:17]
	v_mfma_f32_16x16x32_bf16 v[10:13], v[142:145], v[174:177], v[10:13]
	s_setprio 0
	s_barrier
	s_add_u32 s20, s20, 0x160080
	s_addc_u32 s21, s21, 0
	s_add_i32 s22, s22, s29
	v_lshl_add_u64 v[130:131], s[20:21], 0, v[180:181]
	s_mov_b32 m0, s22
	s_nop 0
	global_load_lds_dwordx4 v[130:131], off
	v_lshl_add_u64 v[130:131], s[20:21], 0, v[184:185]
	s_add_i32 m0, s22, 0x2000
	s_nop 0
	global_load_lds_dwordx4 v[130:131], off
	s_waitcnt vmcnt(6)
	s_barrier
	s_setprio 1
	v_mfma_f32_16x16x32_bf16 v[54:57], v[194:197], v[146:149], v[54:57]
	v_mfma_f32_16x16x32_bf16 v[50:53], v[202:205], v[146:149], v[50:53]
	v_mfma_f32_16x16x32_bf16 v[38:41], v[194:197], v[154:157], v[38:41]
	v_mfma_f32_16x16x32_bf16 v[34:37], v[202:205], v[154:157], v[34:37]
	v_mfma_f32_16x16x32_bf16 v[22:25], v[194:197], v[162:165], v[22:25]
	v_mfma_f32_16x16x32_bf16 v[18:21], v[202:205], v[162:165], v[18:21]
	v_mfma_f32_16x16x32_bf16 v[6:9], v[194:197], v[170:173], v[6:9]
	v_mfma_f32_16x16x32_bf16 v[2:5], v[202:205], v[170:173], v[2:5]
	v_mfma_f32_16x16x32_bf16 v[54:57], v[198:201], v[150:153], v[54:57]
	v_mfma_f32_16x16x32_bf16 v[50:53], v[214:217], v[150:153], v[50:53]
	v_mfma_f32_16x16x32_bf16 v[38:41], v[198:201], v[158:161], v[38:41]
	v_mfma_f32_16x16x32_bf16 v[34:37], v[214:217], v[158:161], v[34:37]
	v_mfma_f32_16x16x32_bf16 v[22:25], v[198:201], v[166:169], v[22:25]
	v_mfma_f32_16x16x32_bf16 v[18:21], v[214:217], v[166:169], v[18:21]
	v_mfma_f32_16x16x32_bf16 v[6:9], v[198:201], v[174:177], v[6:9]
	v_mfma_f32_16x16x32_bf16 v[2:5], v[214:217], v[174:177], v[2:5]
	s_setprio 0
	s_add_i32 s49, s49, 2
	s_add_u32 s18, s18, 0x100
	s_addc_u32 s19, s19, 0
	s_add_u32 s47, s47, 0x100
	s_addc_u32 s48, s48, 0
	s_cmpk_gt_u32 s49, 0x55
	s_barrier

; #define PG8_STAGE(bufoff, gbase, voff) do { _Pragma("unroll") for (int _i = 0; _i < 2; ++_i) \
;         __builtin_amdgcn_global_load_lds((const unsigned*)((const char*)(gbase) + (voff)[_i]), (LAS unsigned*)(lds + (bufoff) + ldsw + _i * 8192), 16, 0, 0); } while (0)
; #define PG8_LDA(dst, b, h) do { _Pragma("unroll") for (int m = 0; m < 4; ++m) _Pragma("unroll") for (int k = 0; k < 2; ++k) dst[m][k] = *(const LAS bf16x8*)(lds + PG8_SA(b, h) + aoff + m * 2048 + k * 1024); } while (0)
; #define PG8_LDB(dst, b, h) do { _Pragma("unroll") for (int n = 0; n < 2; ++n) _Pragma("unroll") for (int k = 0; k < 2; ++k) dst[n][k] = *(const LAS bf16x8*)(lds + PG8_SB(b, h) + boff + n * 2048 + k * 1024); } while (0)
; #define PG8_MMA(ai, bj, At, Bt) do { __builtin_amdgcn_s_setprio(1); _Pragma("unroll") for (int m = 0; m < 4; ++m) _Pragma("unroll") for (int n = 0; n < 2; ++n) _Pragma("unroll") for (int k = 0; k < 2; ++k) \
;         acc[ai][bj][m][n] = __builtin_amdgcn_mfma_f32_16x16x32_bf16(Bt[n][k], At[m][k], acc[ai][bj][m][n], 0, 0, 0); __builtin_amdgcn_s_setprio(0); } while (0)
; #define PG8_BAR __builtin_amdgcn_s_barrier()
; template <class Epi, class Sched>
; __device__ __forceinline__ void gemm_phase(LAS unsigned char* lds, const Gemm g, const Sched& S, const Epi& E) {
;     ...
;         const bool has_next = S.next(ui + 1, nxt);
;         const char* nA = has_next ? (const char*)g.A + (size_t)nxt.pm * tstep : cA; const char* nB = has_next ? (const char*)g.Bt + (size_t)nxt.pn * tstep : cB;
;         for (int t = 0; t < nt; t += 2) {
;             const bool last = (t == nt - 2);
;             const char* a1 = cA + (size_t)(t + 1) * kstep;
;             const char* a2 = last ? nA : cA + (size_t)(t + 2) * kstep; const char* b2 = last ? nB : cB + (size_t)(t + 2) * kstep;
;             const char* a3 = a2 + kstep; const char* b3 = b2 + kstep;
;             if (last && has_next) S.a_ready(nxt);
;             PG8_LDB(B0, 0, 0); PG8_SCHED; PG8_LDA(At, 0, 0); PG8_STAGE(PG8_SA(1, 1), a1 + hstep, voffA);
;             PG8_WAIT_L(8); PG8_BAR; PG8_WAIT_L(0); PG8_MMA(0, 0, At, B0); PG8_BAR; PG8_SCHED;
;             PG8_LDB(B1, 0, 1); PG8_STAGE(PG8_SB(0, 0), b2, voffB);
;             PG8_BAR; PG8_WAIT_L(0); PG8_MMA(0, 1, At, B1); PG8_BAR;
;             PG8_LDA(At, 0, 1); PG8_STAGE(PG8_SA(0, 0), a2, voffA);
;             PG8_BAR; PG8_WAIT_L(0); PG8_MMA(1, 0, At, B0); PG8_BAR; PG8_SCHED;
.LBB0_429:
	s_ashr_i32 s15, s14, 31
	v_cmp_lt_i64_e32 vcc, s[16:17], v[146:147]
	s_lshl_b64 s[16:17], s[14:15], 20
	v_readlane_b32 s68, v245, 5
	v_readlane_b32 s69, v245, 6
	s_add_u32 s16, s68, s16
	s_addc_u32 s17, s69, s17
	s_and_b64 s[18:19], vcc, exec
	s_cselect_b32 s15, s17, s21
	s_cselect_b32 s28, s16, s20
	s_ashr_i32 s13, s12, 31
	s_lshl_b64 s[18:19], s[12:13], 20
	s_add_u32 s18, s35, s18
	s_addc_u32 s19, s36, s19
	s_and_b64 s[26:27], vcc, exec
	s_cselect_b32 s13, s19, s25
	s_cselect_b32 s29, s18, s24
	s_add_u32 s20, s20, 0x80080
	s_addc_u32 s21, s21, 0
	s_add_u32 s58, s24, 0x100
	s_addc_u32 s59, s25, 0
	s_mov_b32 s60, -2
	v_readlane_b32 s70, v245, 7
	v_readlane_b32 s71, v245, 8
	v_readlane_b32 s72, v245, 9
	v_readlane_b32 s73, v245, 10
	v_readlane_b32 s74, v245, 11
	v_readlane_b32 s75, v245, 12
	ds_read_b128 v[150:153], v159
	ds_read_b128 v[164:167], v159 offset:1024
	ds_read_b128 v[168:171], v159 offset:2048
	ds_read_b128 v[172:175], v159 offset:3072
	s_add_u32 s24, s20, 0xfff80080
	s_addc_u32 s25, s21, -1
	s_cmp_eq_u32 s60, 28
	s_cselect_b32 s27, s15, s25
	s_cselect_b32 s26, s28, s24
	s_cselect_b32 s25, s13, s59
	s_cselect_b32 s24, s29, s58
	v_lshl_add_u64 v[154:155], s[20:21], 0, v[142:143]
	s_add_i32 m0, s1, 0xc000
	ds_read_b128 v[176:179], v160
	ds_read_b128 v[180:183], v160 offset:1024
	ds_read_b128 v[184:187], v160 offset:2048
	ds_read_b128 v[188:191], v160 offset:3072
	ds_read_b128 v[192:195], v160 offset:4096
	ds_read_b128 v[196:199], v160 offset:5120
	ds_read_b128 v[200:203], v160 offset:6144
	ds_read_b128 v[208:211], v160 offset:7168
	global_load_lds_dwordx4 v[154:155], off
	v_lshl_add_u64 v[154:155], s[20:21], 0, v[144:145]
	s_add_i32 m0, s1, 0xe000
	s_nop 0
	global_load_lds_dwordx4 v[154:155], off
	s_waitcnt lgkmcnt(8)
	s_barrier
	s_waitcnt lgkmcnt(0)
	s_setprio 1
	s_waitcnt lgkmcnt(0)
	v_mfma_f32_16x16x32_bf16 v[126:129], v[150:153], v[176:179], 0
	v_mfma_f32_16x16x32_bf16 v[122:125], v[168:171], v[176:179], 0
	v_mfma_f32_16x16x32_bf16 v[110:113], v[150:153], v[184:187], 0
	v_mfma_f32_16x16x32_bf16 v[106:109], v[168:171], v[184:187], 0
	v_mfma_f32_16x16x32_bf16 v[94:97], v[150:153], v[192:195], 0
	v_mfma_f32_16x16x32_bf16 v[90:93], v[168:171], v[192:195], 0
	v_mfma_f32_16x16x32_bf16 v[78:81], v[150:153], v[200:203], 0
	v_mfma_f32_16x16x32_bf16 v[74:77], v[168:171], v[200:203], 0
	v_mfma_f32_16x16x32_bf16 v[126:129], v[164:167], v[180:183], v[126:129]
	v_mfma_f32_16x16x32_bf16 v[122:125], v[172:175], v[180:183], v[122:125]
	v_mfma_f32_16x16x32_bf16 v[110:113], v[164:167], v[188:191], v[110:113]
	v_mfma_f32_16x16x32_bf16 v[106:109], v[172:175], v[188:191], v[106:109]
	v_mfma_f32_16x16x32_bf16 v[94:97], v[164:167], v[196:199], v[94:97]
	v_mfma_f32_16x16x32_bf16 v[90:93], v[172:175], v[196:199], v[90:93]
	v_mfma_f32_16x16x32_bf16 v[78:81], v[164:167], v[208:211], v[78:81]
	v_mfma_f32_16x16x32_bf16 v[74:77], v[172:175], v[208:211], v[74:77]
	s_setprio 0
	s_barrier
	s_add_i32 s61, s50, s34
	v_lshl_add_u64 v[154:155], s[24:25], 0, v[132:133]
	s_mov_b32 m0, s61
	ds_read_b128 v[212:215], v161
	ds_read_b128 v[216:219], v161 offset:1024
	ds_read_b128 v[220:223], v161 offset:2048
	ds_read_b128 v[224:227], v161 offset:3072
	global_load_lds_dwordx4 v[154:155], off
	v_lshl_add_u64 v[204:205], s[24:25], 0, v[136:137]
	s_add_i32 m0, s61, 0x2000
	s_nop 0
	global_load_lds_dwordx4 v[204:205], off
	s_barrier
	s_waitcnt lgkmcnt(0)
	s_setprio 1
	s_waitcnt lgkmcnt(0)
	v_mfma_f32_16x16x32_bf16 v[118:121], v[212:215], v[176:179], 0
	v_mfma_f32_16x16x32_bf16 v[114:117], v[220:223], v[176:179], 0
	v_mfma_f32_16x16x32_bf16 v[102:105], v[212:215], v[184:187], 0
	v_mfma_f32_16x16x32_bf16 v[98:101], v[220:223], v[184:187], 0
	v_mfma_f32_16x16x32_bf16 v[86:89], v[212:215], v[192:195], 0
	v_mfma_f32_16x16x32_bf16 v[82:85], v[220:223], v[192:195], 0
	v_mfma_f32_16x16x32_bf16 v[70:73], v[212:215], v[200:203], 0
	v_mfma_f32_16x16x32_bf16 v[66:69], v[220:223], v[200:203], 0
	v_mfma_f32_16x16x32_bf16 v[118:121], v[216:219], v[180:183], v[118:121]
	v_mfma_f32_16x16x32_bf16 v[114:117], v[224:227], v[180:183], v[114:117]
	v_mfma_f32_16x16x32_bf16 v[102:105], v[216:219], v[188:191], v[102:105]
	v_mfma_f32_16x16x32_bf16 v[98:101], v[224:227], v[188:191], v[98:101]
	v_mfma_f32_16x16x32_bf16 v[86:89], v[216:219], v[196:199], v[86:89]
	v_mfma_f32_16x16x32_bf16 v[82:85], v[224:227], v[196:199], v[82:85]
	v_mfma_f32_16x16x32_bf16 v[70:73], v[216:219], v[208:211], v[70:73]
	v_mfma_f32_16x16x32_bf16 v[66:69], v[224:227], v[208:211], v[66:69]
	s_setprio 0
	s_mov_b32 m0, s1
	v_lshl_add_u64 v[228:229], s[26:27], 0, v[130:131]
	s_barrier
	ds_read_b128 v[176:179], v160 offset:16384
	ds_read_b128 v[180:183], v160 offset:17408
	ds_read_b128 v[184:187], v160 offset:18432
	ds_read_b128 v[188:191], v160 offset:19456
	ds_read_b128 v[192:195], v160 offset:20480
	ds_read_b128 v[196:199], v160 offset:21504
	ds_read_b128 v[200:203], v160 offset:22528
	ds_read_b128 v[208:211], v160 offset:23552
	global_load_lds_dwordx4 v[228:229], off
	v_lshl_add_u64 v[230:231], s[26:27], 0, v[134:135]
	s_mov_b32 m0, s37
	s_nop 0
	global_load_lds_dwordx4 v[230:231], off
	s_barrier
; #define PG8_STAGE(bufoff, gbase, voff) do { _Pragma("unroll") for (int _i = 0; _i < 2; ++_i) \
;         __builtin_amdgcn_global_load_lds((const unsigned*)((const char*)(gbase) + (voff)[_i]), (LAS unsigned*)(lds + (bufoff) + ldsw + _i * 8192), 16, 0, 0); } while (0)
; #define PG8_LDA(dst, b, h) do { _Pragma("unroll") for (int m = 0; m < 4; ++m) _Pragma("unroll") for (int k = 0; k < 2; ++k) dst[m][k] = *(const LAS bf16x8*)(lds + PG8_SA(b, h) + aoff + m * 2048 + k * 1024); } while (0)
; #define PG8_LDB(dst, b, h) do { _Pragma("unroll") for (int n = 0; n < 2; ++n) _Pragma("unroll") for (int k = 0; k < 2; ++k) dst[n][k] = *(const LAS bf16x8*)(lds + PG8_SB(b, h) + boff + n * 2048 + k * 1024); } while (0)
; #define PG8_MMA(ai, bj, At, Bt) do { __builtin_amdgcn_s_setprio(1); _Pragma("unroll") for (int m = 0; m < 4; ++m) _Pragma("unroll") for (int n = 0; n < 2; ++n) _Pragma("unroll") for (int k = 0; k < 2; ++k) \
;         acc[ai][bj][m][n] = __builtin_amdgcn_mfma_f32_16x16x32_bf16(Bt[n][k], At[m][k], acc[ai][bj][m][n], 0, 0, 0); __builtin_amdgcn_s_setprio(0); } while (0)
; #define PG8_WAIT_V(n) asm volatile("s_waitcnt vmcnt(" #n ")" ::: "memory")
; #define PG8_WAIT_L(n) asm volatile("s_waitcnt lgkmcnt(" #n ")" ::: "memory")
; #define PG8_BAR __builtin_amdgcn_s_barrier()
; #define PG8_SCHED __builtin_amdgcn_sched_barrier(0)
; template <class Epi, class Sched>
; __device__ __forceinline__ void gemm_phase(LAS unsigned char* lds, const Gemm g, const Sched& S, const Epi& E) {
;     ...
;             PG8_STAGE(PG8_SB(0, 1), b2 + hstep, voffB);
;             PG8_WAIT_V(6); PG8_BAR; PG8_MMA(1, 1, At, B1); PG8_BAR;
;             PG8_LDB(B0, 1, 0); PG8_SCHED; PG8_LDA(At, 1, 0); PG8_STAGE(PG8_SA(0, 1), a2 + hstep, voffA);
;             PG8_WAIT_L(8); PG8_BAR; PG8_WAIT_L(0); PG8_MMA(0, 0, At, B0); PG8_BAR; PG8_SCHED;
;             PG8_LDB(B1, 1, 1); PG8_STAGE(PG8_SB(1, 0), b3, voffB);
	s_waitcnt lgkmcnt(0)
	s_setprio 1
	s_waitcnt lgkmcnt(0)
	v_mfma_f32_16x16x32_bf16 v[62:65], v[150:153], v[176:179], 0
	v_mfma_f32_16x16x32_bf16 v[58:61], v[168:171], v[176:179], 0
	v_mfma_f32_16x16x32_bf16 v[46:49], v[150:153], v[184:187], 0
	v_mfma_f32_16x16x32_bf16 v[42:45], v[168:171], v[184:187], 0
	v_mfma_f32_16x16x32_bf16 v[30:33], v[150:153], v[192:195], 0
	v_mfma_f32_16x16x32_bf16 v[26:29], v[168:171], v[192:195], 0
	v_mfma_f32_16x16x32_bf16 v[14:17], v[150:153], v[200:203], 0
	v_mfma_f32_16x16x32_bf16 v[10:13], v[168:171], v[200:203], 0
	v_mfma_f32_16x16x32_bf16 v[62:65], v[164:167], v[180:183], v[62:65]
	v_mfma_f32_16x16x32_bf16 v[58:61], v[172:175], v[180:183], v[58:61]
	v_mfma_f32_16x16x32_bf16 v[46:49], v[164:167], v[188:191], v[46:49]
	v_mfma_f32_16x16x32_bf16 v[42:45], v[172:175], v[188:191], v[42:45]
	v_mfma_f32_16x16x32_bf16 v[30:33], v[164:167], v[196:199], v[30:33]
	v_mfma_f32_16x16x32_bf16 v[26:29], v[172:175], v[196:199], v[26:29]
	v_mfma_f32_16x16x32_bf16 v[14:17], v[164:167], v[208:211], v[14:17]
	v_mfma_f32_16x16x32_bf16 v[10:13], v[172:175], v[208:211], v[10:13]
	s_setprio 0
	s_barrier
	s_add_u32 s68, s24, 0x80000
	s_addc_u32 s69, s25, 0
	s_add_i32 s61, s51, s34
	v_lshl_add_u64 v[150:151], s[68:69], 0, v[132:133]
	s_mov_b32 m0, s61
	s_nop 0
	global_load_lds_dwordx4 v[150:151], off
	v_lshl_add_u64 v[150:151], s[68:69], 0, v[136:137]
	s_add_i32 m0, s61, 0x2000
	s_nop 0
	global_load_lds_dwordx4 v[150:151], off
	s_waitcnt vmcnt(6)
	s_barrier
	s_setprio 1
	v_mfma_f32_16x16x32_bf16 v[54:57], v[212:215], v[176:179], 0
	v_mfma_f32_16x16x32_bf16 v[50:53], v[220:223], v[176:179], 0
	v_mfma_f32_16x16x32_bf16 v[38:41], v[212:215], v[184:187], 0
	v_mfma_f32_16x16x32_bf16 v[34:37], v[220:223], v[184:187], 0
	v_mfma_f32_16x16x32_bf16 v[22:25], v[212:215], v[192:195], 0
	v_mfma_f32_16x16x32_bf16 v[18:21], v[220:223], v[192:195], 0
	v_mfma_f32_16x16x32_bf16 v[6:9], v[212:215], v[200:203], 0
	v_mfma_f32_16x16x32_bf16 v[2:5], v[220:223], v[200:203], 0
	v_mfma_f32_16x16x32_bf16 v[54:57], v[216:219], v[180:183], v[54:57]
	v_mfma_f32_16x16x32_bf16 v[50:53], v[224:227], v[180:183], v[50:53]
	v_mfma_f32_16x16x32_bf16 v[38:41], v[216:219], v[188:191], v[38:41]
	v_mfma_f32_16x16x32_bf16 v[34:37], v[224:227], v[188:191], v[34:37]
	v_mfma_f32_16x16x32_bf16 v[22:25], v[216:219], v[196:199], v[22:25]
	v_mfma_f32_16x16x32_bf16 v[18:21], v[224:227], v[196:199], v[18:21]
	v_mfma_f32_16x16x32_bf16 v[6:9], v[216:219], v[208:211], v[6:9]
	v_mfma_f32_16x16x32_bf16 v[2:5], v[224:227], v[208:211], v[2:5]
	s_setprio 0
	s_add_i32 s61, 0, 0x18000
	v_add_u32_e32 v138, s61, v156
	s_barrier
	ds_read_b128 v[150:153], v138
	ds_read_b128 v[164:167], v138 offset:1024
	ds_read_b128 v[168:171], v138 offset:2048
	ds_read_b128 v[172:175], v138 offset:3072
	s_add_u32 s26, s26, 0x80000
	s_addc_u32 s27, s27, 0
	s_mov_b32 m0, s38
	v_lshl_add_u64 v[212:213], s[26:27], 0, v[130:131]
	ds_read_b128 v[176:179], v160 offset:32768
	ds_read_b128 v[180:183], v160 offset:33792
	ds_read_b128 v[184:187], v160 offset:34816
	ds_read_b128 v[188:191], v160 offset:35840
	ds_read_b128 v[192:195], v160 offset:36864
	ds_read_b128 v[196:199], v160 offset:37888
	ds_read_b128 v[200:203], v160 offset:38912
	ds_read_b128 v[208:211], v160 offset:39936
	global_load_lds_dwordx4 v[212:213], off
	v_lshl_add_u64 v[212:213], s[26:27], 0, v[134:135]
	s_mov_b32 m0, s39
	s_nop 0
	global_load_lds_dwordx4 v[212:213], off
	s_waitcnt lgkmcnt(8)
	s_barrier
	s_waitcnt lgkmcnt(0)
	s_setprio 1
	s_waitcnt lgkmcnt(0)
	v_mfma_f32_16x16x32_bf16 v[126:129], v[150:153], v[176:179], v[126:129]
	v_mfma_f32_16x16x32_bf16 v[122:125], v[168:171], v[176:179], v[122:125]
	v_mfma_f32_16x16x32_bf16 v[110:113], v[150:153], v[184:187], v[110:113]
	v_mfma_f32_16x16x32_bf16 v[106:109], v[168:171], v[184:187], v[106:109]
	v_mfma_f32_16x16x32_bf16 v[94:97], v[150:153], v[192:195], v[94:97]
	v_mfma_f32_16x16x32_bf16 v[90:93], v[168:171], v[192:195], v[90:93]
	v_mfma_f32_16x16x32_bf16 v[78:81], v[150:153], v[200:203], v[78:81]
	v_mfma_f32_16x16x32_bf16 v[74:77], v[168:171], v[200:203], v[74:77]
	v_mfma_f32_16x16x32_bf16 v[126:129], v[164:167], v[180:183], v[126:129]
	v_mfma_f32_16x16x32_bf16 v[122:125], v[172:175], v[180:183], v[122:125]
	v_mfma_f32_16x16x32_bf16 v[110:113], v[164:167], v[188:191], v[110:113]
	v_mfma_f32_16x16x32_bf16 v[106:109], v[172:175], v[188:191], v[106:109]
	v_mfma_f32_16x16x32_bf16 v[94:97], v[164:167], v[196:199], v[94:97]
	v_mfma_f32_16x16x32_bf16 v[90:93], v[172:175], v[196:199], v[90:93]
	v_mfma_f32_16x16x32_bf16 v[78:81], v[164:167], v[208:211], v[78:81]
	v_mfma_f32_16x16x32_bf16 v[74:77], v[172:175], v[208:211], v[74:77]
	s_setprio 0
	s_barrier
; #define PG8_STAGE(bufoff, gbase, voff) do { _Pragma("unroll") for (int _i = 0; _i < 2; ++_i) \
;         __builtin_amdgcn_global_load_lds((const unsigned*)((const char*)(gbase) + (voff)[_i]), (LAS unsigned*)(lds + (bufoff) + ldsw + _i * 8192), 16, 0, 0); } while (0)
; #define PG8_LDA(dst, b, h) do { _Pragma("unroll") for (int m = 0; m < 4; ++m) _Pragma("unroll") for (int k = 0; k < 2; ++k) dst[m][k] = *(const LAS bf16x8*)(lds + PG8_SA(b, h) + aoff + m * 2048 + k * 1024); } while (0)
; #define PG8_LDB(dst, b, h) do { _Pragma("unroll") for (int n = 0; n < 2; ++n) _Pragma("unroll") for (int k = 0; k < 2; ++k) dst[n][k] = *(const LAS bf16x8*)(lds + PG8_SB(b, h) + boff + n * 2048 + k * 1024); } while (0)
; #define PG8_MMA(ai, bj, At, Bt) do { __builtin_amdgcn_s_setprio(1); _Pragma("unroll") for (int m = 0; m < 4; ++m) _Pragma("unroll") for (int n = 0; n < 2; ++n) _Pragma("unroll") for (int k = 0; k < 2; ++k) \
;         acc[ai][bj][m][n] = __builtin_amdgcn_mfma_f32_16x16x32_bf16(Bt[n][k], At[m][k], acc[ai][bj][m][n], 0, 0, 0); __builtin_amdgcn_s_setprio(0); } while (0)
; #define PG8_WAIT_V(n) asm volatile("s_waitcnt vmcnt(" #n ")" ::: "memory")
; #define PG8_WAIT_L(n) asm volatile("s_waitcnt lgkmcnt(" #n ")" ::: "memory")
; #define PG8_BAR __builtin_amdgcn_s_barrier()
; #define PG8_SCHED __builtin_amdgcn_sched_barrier(0)
; template <class Epi, class Sched>
; __device__ __forceinline__ void gemm_phase(LAS unsigned char* lds, const Gemm g, const Sched& S, const Epi& E) {
;     ...
;             PG8_STAGE(PG8_SB(0, 1), b2 + hstep, voffB);
;             PG8_WAIT_V(6); PG8_BAR; PG8_MMA(1, 1, At, B1); PG8_BAR;
;             PG8_LDB(B0, 1, 0); PG8_SCHED; PG8_LDA(At, 1, 0); PG8_STAGE(PG8_SA(0, 1), a2 + hstep, voffA);
;             PG8_WAIT_L(8); PG8_BAR; PG8_WAIT_L(0); PG8_MMA(0, 0, At, B0); PG8_BAR; PG8_SCHED;
;             PG8_LDB(B1, 1, 1); PG8_STAGE(PG8_SB(1, 0), b3, voffB);
;             PG8_BAR; PG8_WAIT_L(0); PG8_MMA(0, 1, At, B1); PG8_BAR;
;             PG8_LDA(At, 1, 1); PG8_STAGE(PG8_SA(1, 0), a3, voffA);
;             PG8_BAR; PG8_WAIT_L(0); PG8_MMA(1, 0, At, B0); PG8_BAR; PG8_SCHED;
;             PG8_STAGE(PG8_SB(1, 1), b3 + hstep, voffB);
;             PG8_WAIT_V(6); PG8_BAR; PG8_MMA(1, 1, At, B1); PG8_BAR;
;         }
	s_add_i32 s26, 0, 0x1c000
	s_add_i32 s27, s61, s34
	v_add_u32_e32 v138, s26, v156
	v_lshl_add_u64 v[154:155], v[154:155], 0, s[8:9]
	s_mov_b32 m0, s27
	ds_read_b128 v[212:215], v138
	ds_read_b128 v[216:219], v138 offset:1024
	ds_read_b128 v[220:223], v138 offset:2048
	ds_read_b128 v[224:227], v138 offset:3072
	global_load_lds_dwordx4 v[154:155], off
	v_lshl_add_u64 v[154:155], v[204:205], 0, s[8:9]
	s_add_i32 m0, s27, 0x2000
	s_nop 0
	global_load_lds_dwordx4 v[154:155], off
	s_barrier
	s_waitcnt lgkmcnt(0)
	s_setprio 1
	s_waitcnt lgkmcnt(0)
	v_mfma_f32_16x16x32_bf16 v[118:121], v[212:215], v[176:179], v[118:121]
	v_mfma_f32_16x16x32_bf16 v[114:117], v[220:223], v[176:179], v[114:117]
	v_mfma_f32_16x16x32_bf16 v[102:105], v[212:215], v[184:187], v[102:105]
	v_mfma_f32_16x16x32_bf16 v[98:101], v[220:223], v[184:187], v[98:101]
	v_mfma_f32_16x16x32_bf16 v[86:89], v[212:215], v[192:195], v[86:89]
	v_mfma_f32_16x16x32_bf16 v[82:85], v[220:223], v[192:195], v[82:85]
	v_mfma_f32_16x16x32_bf16 v[70:73], v[212:215], v[200:203], v[70:73]
	v_mfma_f32_16x16x32_bf16 v[66:69], v[220:223], v[200:203], v[66:69]
	v_mfma_f32_16x16x32_bf16 v[118:121], v[216:219], v[180:183], v[118:121]
	v_mfma_f32_16x16x32_bf16 v[114:117], v[224:227], v[180:183], v[114:117]
	v_mfma_f32_16x16x32_bf16 v[102:105], v[216:219], v[188:191], v[102:105]
	v_mfma_f32_16x16x32_bf16 v[98:101], v[224:227], v[188:191], v[98:101]
	v_mfma_f32_16x16x32_bf16 v[86:89], v[216:219], v[196:199], v[86:89]
	v_mfma_f32_16x16x32_bf16 v[82:85], v[224:227], v[196:199], v[82:85]
	v_mfma_f32_16x16x32_bf16 v[70:73], v[216:219], v[208:211], v[70:73]
	v_mfma_f32_16x16x32_bf16 v[66:69], v[224:227], v[208:211], v[66:69]
	s_setprio 0
	s_mov_b32 m0, s47
	v_lshl_add_u64 v[154:155], v[228:229], 0, s[8:9]
	s_barrier
	ds_read_b128 v[176:179], v160 offset:49152
	ds_read_b128 v[180:183], v160 offset:50176
	ds_read_b128 v[184:187], v160 offset:51200
	ds_read_b128 v[188:191], v160 offset:52224
	ds_read_b128 v[192:195], v160 offset:53248
	ds_read_b128 v[196:199], v160 offset:54272
	ds_read_b128 v[200:203], v160 offset:55296
	ds_read_b128 v[208:211], v160 offset:56320
	global_load_lds_dwordx4 v[154:155], off
	v_lshl_add_u64 v[154:155], v[230:231], 0, s[8:9]
	s_mov_b32 m0, s48
	s_nop 0
	global_load_lds_dwordx4 v[154:155], off
	s_barrier
	s_waitcnt lgkmcnt(0)
	s_setprio 1
	s_waitcnt lgkmcnt(0)
	v_mfma_f32_16x16x32_bf16 v[62:65], v[150:153], v[176:179], v[62:65]
	v_mfma_f32_16x16x32_bf16 v[58:61], v[168:171], v[176:179], v[58:61]
	v_mfma_f32_16x16x32_bf16 v[46:49], v[150:153], v[184:187], v[46:49]
	v_mfma_f32_16x16x32_bf16 v[42:45], v[168:171], v[184:187], v[42:45]
	v_mfma_f32_16x16x32_bf16 v[30:33], v[150:153], v[192:195], v[30:33]
	v_mfma_f32_16x16x32_bf16 v[26:29], v[168:171], v[192:195], v[26:29]
	v_mfma_f32_16x16x32_bf16 v[14:17], v[150:153], v[200:203], v[14:17]
	v_mfma_f32_16x16x32_bf16 v[10:13], v[168:171], v[200:203], v[10:13]
	v_mfma_f32_16x16x32_bf16 v[62:65], v[164:167], v[180:183], v[62:65]
	v_mfma_f32_16x16x32_bf16 v[58:61], v[172:175], v[180:183], v[58:61]
	v_mfma_f32_16x16x32_bf16 v[46:49], v[164:167], v[188:191], v[46:49]
	v_mfma_f32_16x16x32_bf16 v[42:45], v[172:175], v[188:191], v[42:45]
	v_mfma_f32_16x16x32_bf16 v[30:33], v[164:167], v[196:199], v[30:33]
	v_mfma_f32_16x16x32_bf16 v[26:29], v[172:175], v[196:199], v[26:29]
	v_mfma_f32_16x16x32_bf16 v[14:17], v[164:167], v[208:211], v[14:17]
	v_mfma_f32_16x16x32_bf16 v[10:13], v[172:175], v[208:211], v[10:13]
	s_setprio 0
	s_barrier
	s_add_u32 s24, s24, 0x80080
	s_addc_u32 s25, s25, 0
	s_add_i32 s26, s26, s34
	v_lshl_add_u64 v[150:151], s[24:25], 0, v[132:133]
	s_mov_b32 m0, s26
	s_nop 0
	global_load_lds_dwordx4 v[150:151], off
	v_lshl_add_u64 v[150:151], s[24:25], 0, v[136:137]
	s_add_i32 m0, s26, 0x2000
	s_nop 0
	global_load_lds_dwordx4 v[150:151], off
	s_waitcnt vmcnt(6)
	s_barrier
	s_setprio 1
	v_mfma_f32_16x16x32_bf16 v[54:57], v[212:215], v[176:179], v[54:57]
	v_mfma_f32_16x16x32_bf16 v[50:53], v[220:223], v[176:179], v[50:53]
	v_mfma_f32_16x16x32_bf16 v[38:41], v[212:215], v[184:187], v[38:41]
	v_mfma_f32_16x16x32_bf16 v[34:37], v[220:223], v[184:187], v[34:37]
	v_mfma_f32_16x16x32_bf16 v[22:25], v[212:215], v[192:195], v[22:25]
	v_mfma_f32_16x16x32_bf16 v[18:21], v[220:223], v[192:195], v[18:21]
	v_mfma_f32_16x16x32_bf16 v[6:9], v[212:215], v[200:203], v[6:9]
	v_mfma_f32_16x16x32_bf16 v[2:5], v[220:223], v[200:203], v[2:5]
	v_mfma_f32_16x16x32_bf16 v[54:57], v[216:219], v[180:183], v[54:57]
	v_mfma_f32_16x16x32_bf16 v[50:53], v[224:227], v[180:183], v[50:53]
	v_mfma_f32_16x16x32_bf16 v[38:41], v[216:219], v[188:191], v[38:41]
	v_mfma_f32_16x16x32_bf16 v[34:37], v[224:227], v[188:191], v[34:37]
	v_mfma_f32_16x16x32_bf16 v[22:25], v[216:219], v[196:199], v[22:25]
	v_mfma_f32_16x16x32_bf16 v[18:21], v[224:227], v[196:199], v[18:21]
	v_mfma_f32_16x16x32_bf16 v[6:9], v[216:219], v[208:211], v[6:9]
	v_mfma_f32_16x16x32_bf16 v[2:5], v[224:227], v[208:211], v[2:5]
	s_setprio 0
	s_add_i32 s60, s60, 2
	s_add_u32 s20, s20, 0x100
	s_addc_u32 s21, s21, 0
	s_add_u32 s58, s58, 0x100
	s_addc_u32 s59, s59, 0
	s_cmp_gt_u32 s60, 29
	s_barrier

; #define PG8_STAGE(bufoff, gbase, voff) do { _Pragma("unroll") for (int _i = 0; _i < 2; ++_i) \
;         __builtin_amdgcn_global_load_lds((const unsigned*)((const char*)(gbase) + (voff)[_i]), (LAS unsigned*)(lds + (bufoff) + ldsw + _i * 8192), 16, 0, 0); } while (0)
; #define PG8_LDA(dst, b, h) do { _Pragma("unroll") for (int m = 0; m < 4; ++m) _Pragma("unroll") for (int k = 0; k < 2; ++k) dst[m][k] = *(const LAS bf16x8*)(lds + PG8_SA(b, h) + aoff + m * 2048 + k * 1024); } while (0)
; #define PG8_LDB(dst, b, h) do { _Pragma("unroll") for (int n = 0; n < 2; ++n) _Pragma("unroll") for (int k = 0; k < 2; ++k) dst[n][k] = *(const LAS bf16x8*)(lds + PG8_SB(b, h) + boff + n * 2048 + k * 1024); } while (0)
; #define PG8_MMA(ai, bj, At, Bt) do { __builtin_amdgcn_s_setprio(1); _Pragma("unroll") for (int m = 0; m < 4; ++m) _Pragma("unroll") for (int n = 0; n < 2; ++n) _Pragma("unroll") for (int k = 0; k < 2; ++k) \
;         acc[ai][bj][m][n] = __builtin_amdgcn_mfma_f32_16x16x32_bf16(Bt[n][k], At[m][k], acc[ai][bj][m][n], 0, 0, 0); __builtin_amdgcn_s_setprio(0); } while (0)
; #define PG8_BAR __builtin_amdgcn_s_barrier()
; template <class Epi, class Sched>
; __device__ __forceinline__ void gemm_phase(LAS unsigned char* lds, const Gemm g, const Sched& S, const Epi& E) {
;     ...
;         const bool has_next = S.next(ui + 1, nxt);
;         const char* nA = has_next ? (const char*)g.A + (size_t)nxt.pm * tstep : cA; const char* nB = has_next ? (const char*)g.Bt + (size_t)nxt.pn * tstep : cB;
;         for (int t = 0; t < nt; t += 2) {
;             const bool last = (t == nt - 2);
;             const char* a1 = cA + (size_t)(t + 1) * kstep;
;             const char* a2 = last ? nA : cA + (size_t)(t + 2) * kstep; const char* b2 = last ? nB : cB + (size_t)(t + 2) * kstep;
;             const char* a3 = a2 + kstep; const char* b3 = b2 + kstep;
;             if (last && has_next) S.a_ready(nxt);
;             PG8_LDB(B0, 0, 0); PG8_SCHED; PG8_LDA(At, 0, 0); PG8_STAGE(PG8_SA(1, 1), a1 + hstep, voffA);
;             PG8_WAIT_L(8); PG8_BAR; PG8_WAIT_L(0); PG8_MMA(0, 0, At, B0); PG8_BAR; PG8_SCHED;
;             PG8_LDB(B1, 0, 1); PG8_STAGE(PG8_SB(0, 0), b2, voffB);
;             PG8_BAR; PG8_WAIT_L(0); PG8_MMA(0, 1, At, B1); PG8_BAR;
;             PG8_LDA(At, 0, 1); PG8_STAGE(PG8_SA(0, 0), a2, voffA);
;             PG8_BAR; PG8_WAIT_L(0); PG8_MMA(1, 0, At, B0); PG8_BAR; PG8_SCHED;
.LBB0_914:
	s_ashr_i32 s13, s12, 31
	v_cmp_lt_i64_e32 vcc, s[14:15], v[182:183]
	s_lshl_b64 s[14:15], s[12:13], 19
	s_add_u32 s14, s2, s14
	s_addc_u32 s15, s3, s15
	s_and_b64 s[16:17], vcc, exec
	s_cselect_b32 s13, s15, s21
	s_cselect_b32 s43, s14, s20
	s_ashr_i32 s11, s10, 31
	s_lshl_b64 s[16:17], s[10:11], 19
	s_add_u32 s16, s27, s16
	s_addc_u32 s17, s28, s17
	s_and_b64 s[24:25], vcc, exec
	s_cselect_b32 s11, s17, s23
	s_cselect_b32 s44, s16, s22
	s_add_u32 s20, s20, 0x40080
	s_addc_u32 s21, s21, 0
	s_add_u32 s45, s22, 0x100
	s_addc_u32 s46, s23, 0
	s_mov_b32 s47, -2
	ds_read_b128 v[66:69], v198
	ds_read_b128 v[74:77], v198 offset:1024
	ds_read_b128 v[82:85], v198 offset:2048
	ds_read_b128 v[86:89], v198 offset:3072
	s_add_u32 s22, s20, 0xfffc0080
	s_addc_u32 s23, s21, -1
	s_cmp_eq_u32 s47, 12
	s_cselect_b32 s25, s13, s23
	s_cselect_b32 s24, s43, s22
	s_cselect_b32 s23, s11, s46
	s_cselect_b32 s22, s44, s45
	v_lshl_add_u64 v[194:195], s[20:21], 0, v[178:179]
	s_add_i32 m0, s19, 0xc000
	ds_read_b128 v[146:149], v199
	ds_read_b128 v[150:153], v199 offset:1024
	ds_read_b128 v[154:157], v199 offset:2048
	ds_read_b128 v[158:161], v199 offset:3072
	ds_read_b128 v[162:165], v199 offset:4096
	ds_read_b128 v[166:169], v199 offset:5120
	ds_read_b128 v[186:189], v199 offset:6144
	ds_read_b128 v[190:193], v199 offset:7168
	global_load_lds_dwordx4 v[194:195], off
	v_lshl_add_u64 v[194:195], s[20:21], 0, v[180:181]
	s_add_i32 m0, s19, 0xe000
	s_nop 0
	global_load_lds_dwordx4 v[194:195], off
	s_waitcnt lgkmcnt(8)
	s_barrier
	s_waitcnt lgkmcnt(0)
	s_setprio 1
	s_waitcnt lgkmcnt(0)
	v_mfma_f32_16x16x32_bf16 v[142:145], v[66:69], v[146:149], 0
	v_mfma_f32_16x16x32_bf16 v[138:141], v[82:85], v[146:149], 0
	v_mfma_f32_16x16x32_bf16 v[126:129], v[66:69], v[154:157], 0
	v_mfma_f32_16x16x32_bf16 v[122:125], v[82:85], v[154:157], 0
	v_mfma_f32_16x16x32_bf16 v[110:113], v[66:69], v[162:165], 0
	v_mfma_f32_16x16x32_bf16 v[106:109], v[82:85], v[162:165], 0
	v_mfma_f32_16x16x32_bf16 v[94:97], v[66:69], v[186:189], 0
	v_mfma_f32_16x16x32_bf16 v[90:93], v[82:85], v[186:189], 0
	v_mfma_f32_16x16x32_bf16 v[142:145], v[74:77], v[150:153], v[142:145]
	v_mfma_f32_16x16x32_bf16 v[138:141], v[86:89], v[150:153], v[138:141]
	v_mfma_f32_16x16x32_bf16 v[126:129], v[74:77], v[158:161], v[126:129]
	v_mfma_f32_16x16x32_bf16 v[122:125], v[86:89], v[158:161], v[122:125]
	v_mfma_f32_16x16x32_bf16 v[110:113], v[74:77], v[166:169], v[110:113]
	v_mfma_f32_16x16x32_bf16 v[106:109], v[86:89], v[166:169], v[106:109]
	v_mfma_f32_16x16x32_bf16 v[94:97], v[74:77], v[190:193], v[94:97]
	v_mfma_f32_16x16x32_bf16 v[90:93], v[86:89], v[190:193], v[90:93]
	s_setprio 0
	s_barrier
	s_add_i32 s48, s40, s29
	v_lshl_add_u64 v[194:195], s[22:23], 0, v[172:173]
	s_mov_b32 m0, s48
	ds_read_b128 v[202:205], v200
	ds_read_b128 v[208:211], v200 offset:1024
	ds_read_b128 v[212:215], v200 offset:2048
	ds_read_b128 v[216:219], v200 offset:3072
	global_load_lds_dwordx4 v[194:195], off
	v_lshl_add_u64 v[220:221], s[22:23], 0, v[176:177]
	s_add_i32 m0, s48, 0x2000
	s_nop 0
	global_load_lds_dwordx4 v[220:221], off
	s_barrier
	s_waitcnt lgkmcnt(0)
	s_setprio 1
	s_waitcnt lgkmcnt(0)
	v_mfma_f32_16x16x32_bf16 v[134:137], v[202:205], v[146:149], 0
	v_mfma_f32_16x16x32_bf16 v[130:133], v[212:215], v[146:149], 0
	v_mfma_f32_16x16x32_bf16 v[118:121], v[202:205], v[154:157], 0
	v_mfma_f32_16x16x32_bf16 v[114:117], v[212:215], v[154:157], 0
	v_mfma_f32_16x16x32_bf16 v[102:105], v[202:205], v[162:165], 0
	v_mfma_f32_16x16x32_bf16 v[98:101], v[212:215], v[162:165], 0
	v_mfma_f32_16x16x32_bf16 v[78:81], v[202:205], v[186:189], 0
	v_mfma_f32_16x16x32_bf16 v[70:73], v[212:215], v[186:189], 0
	v_mfma_f32_16x16x32_bf16 v[134:137], v[208:211], v[150:153], v[134:137]
	v_mfma_f32_16x16x32_bf16 v[130:133], v[216:219], v[150:153], v[130:133]
	v_mfma_f32_16x16x32_bf16 v[118:121], v[208:211], v[158:161], v[118:121]
	v_mfma_f32_16x16x32_bf16 v[114:117], v[216:219], v[158:161], v[114:117]
	v_mfma_f32_16x16x32_bf16 v[102:105], v[208:211], v[166:169], v[102:105]
	v_mfma_f32_16x16x32_bf16 v[98:101], v[216:219], v[166:169], v[98:101]
	v_mfma_f32_16x16x32_bf16 v[78:81], v[208:211], v[190:193], v[78:81]
	v_mfma_f32_16x16x32_bf16 v[70:73], v[216:219], v[190:193], v[70:73]
	s_setprio 0
	s_mov_b32 m0, s19
	v_lshl_add_u64 v[222:223], s[24:25], 0, v[170:171]
	s_barrier
	ds_read_b128 v[146:149], v199 offset:16384
	ds_read_b128 v[150:153], v199 offset:17408
	ds_read_b128 v[154:157], v199 offset:18432
	ds_read_b128 v[158:161], v199 offset:19456
	ds_read_b128 v[162:165], v199 offset:20480
	ds_read_b128 v[166:169], v199 offset:21504
	ds_read_b128 v[186:189], v199 offset:22528
	ds_read_b128 v[190:193], v199 offset:23552
	global_load_lds_dwordx4 v[222:223], off
	v_lshl_add_u64 v[224:225], s[24:25], 0, v[174:175]
	s_mov_b32 m0, s31
	s_nop 0
	global_load_lds_dwordx4 v[224:225], off
	s_barrier
	s_waitcnt lgkmcnt(0)
	s_setprio 1
	s_waitcnt lgkmcnt(0)
	v_mfma_f32_16x16x32_bf16 v[62:65], v[66:69], v[146:149], 0
	v_mfma_f32_16x16x32_bf16 v[58:61], v[82:85], v[146:149], 0
	v_mfma_f32_16x16x32_bf16 v[46:49], v[66:69], v[154:157], 0
	v_mfma_f32_16x16x32_bf16 v[42:45], v[82:85], v[154:157], 0
	v_mfma_f32_16x16x32_bf16 v[30:33], v[66:69], v[162:165], 0
	v_mfma_f32_16x16x32_bf16 v[26:29], v[82:85], v[162:165], 0
	v_mfma_f32_16x16x32_bf16 v[14:17], v[66:69], v[186:189], 0
	v_mfma_f32_16x16x32_bf16 v[10:13], v[82:85], v[186:189], 0
	v_mfma_f32_16x16x32_bf16 v[62:65], v[74:77], v[150:153], v[62:65]
	v_mfma_f32_16x16x32_bf16 v[58:61], v[86:89], v[150:153], v[58:61]
	v_mfma_f32_16x16x32_bf16 v[46:49], v[74:77], v[158:161], v[46:49]
	v_mfma_f32_16x16x32_bf16 v[42:45], v[86:89], v[158:161], v[42:45]
	v_mfma_f32_16x16x32_bf16 v[30:33], v[74:77], v[166:169], v[30:33]
	v_mfma_f32_16x16x32_bf16 v[26:29], v[86:89], v[166:169], v[26:29]
	v_mfma_f32_16x16x32_bf16 v[14:17], v[74:77], v[190:193], v[14:17]
	v_mfma_f32_16x16x32_bf16 v[10:13], v[86:89], v[190:193], v[10:13]
	s_setprio 0
	s_barrier
; #define PG8_STAGE(bufoff, gbase, voff) do { _Pragma("unroll") for (int _i = 0; _i < 2; ++_i) \
;         __builtin_amdgcn_global_load_lds((const unsigned*)((const char*)(gbase) + (voff)[_i]), (LAS unsigned*)(lds + (bufoff) + ldsw + _i * 8192), 16, 0, 0); } while (0)
; #define PG8_LDA(dst, b, h) do { _Pragma("unroll") for (int m = 0; m < 4; ++m) _Pragma("unroll") for (int k = 0; k < 2; ++k) dst[m][k] = *(const LAS bf16x8*)(lds + PG8_SA(b, h) + aoff + m * 2048 + k * 1024); } while (0)
; #define PG8_LDB(dst, b, h) do { _Pragma("unroll") for (int n = 0; n < 2; ++n) _Pragma("unroll") for (int k = 0; k < 2; ++k) dst[n][k] = *(const LAS bf16x8*)(lds + PG8_SB(b, h) + boff + n * 2048 + k * 1024); } while (0)
; #define PG8_MMA(ai, bj, At, Bt) do { __builtin_amdgcn_s_setprio(1); _Pragma("unroll") for (int m = 0; m < 4; ++m) _Pragma("unroll") for (int n = 0; n < 2; ++n) _Pragma("unroll") for (int k = 0; k < 2; ++k) \
;         acc[ai][bj][m][n] = __builtin_amdgcn_mfma_f32_16x16x32_bf16(Bt[n][k], At[m][k], acc[ai][bj][m][n], 0, 0, 0); __builtin_amdgcn_s_setprio(0); } while (0)
; #define PG8_WAIT_V(n) asm volatile("s_waitcnt vmcnt(" #n ")" ::: "memory")
; #define PG8_WAIT_L(n) asm volatile("s_waitcnt lgkmcnt(" #n ")" ::: "memory")
; #define PG8_BAR __builtin_amdgcn_s_barrier()
; #define PG8_SCHED __builtin_amdgcn_sched_barrier(0)
; template <class Epi, class Sched>
; __device__ __forceinline__ void gemm_phase(LAS unsigned char* lds, const Gemm g, const Sched& S, const Epi& E) {
;     ...
;             PG8_STAGE(PG8_SB(0, 1), b2 + hstep, voffB);
;             PG8_WAIT_V(6); PG8_BAR; PG8_MMA(1, 1, At, B1); PG8_BAR;
;             PG8_LDB(B0, 1, 0); PG8_SCHED; PG8_LDA(At, 1, 0); PG8_STAGE(PG8_SA(0, 1), a2 + hstep, voffA);
;             PG8_WAIT_L(8); PG8_BAR; PG8_WAIT_L(0); PG8_MMA(0, 0, At, B0); PG8_BAR; PG8_SCHED;
;             PG8_LDB(B1, 1, 1); PG8_STAGE(PG8_SB(1, 0), b3, voffB);
	s_add_u32 s48, s22, 0x40000
	s_addc_u32 s49, s23, 0
	s_add_i32 s50, s41, s29
	v_lshl_add_u64 v[66:67], s[48:49], 0, v[172:173]
	s_mov_b32 m0, s50
	s_nop 0
	global_load_lds_dwordx4 v[66:67], off
	v_lshl_add_u64 v[66:67], s[48:49], 0, v[176:177]
	s_add_i32 m0, s50, 0x2000
	s_nop 0
	global_load_lds_dwordx4 v[66:67], off
	s_waitcnt vmcnt(6)
	s_barrier
	s_setprio 1
	v_mfma_f32_16x16x32_bf16 v[54:57], v[202:205], v[146:149], 0
	v_mfma_f32_16x16x32_bf16 v[50:53], v[212:215], v[146:149], 0
	v_mfma_f32_16x16x32_bf16 v[38:41], v[202:205], v[154:157], 0
	v_mfma_f32_16x16x32_bf16 v[34:37], v[212:215], v[154:157], 0
	v_mfma_f32_16x16x32_bf16 v[22:25], v[202:205], v[162:165], 0
	v_mfma_f32_16x16x32_bf16 v[18:21], v[212:215], v[162:165], 0
	v_mfma_f32_16x16x32_bf16 v[6:9], v[202:205], v[186:189], 0
	v_mfma_f32_16x16x32_bf16 v[2:5], v[212:215], v[186:189], 0
	v_mfma_f32_16x16x32_bf16 v[54:57], v[208:211], v[150:153], v[54:57]
	v_mfma_f32_16x16x32_bf16 v[50:53], v[216:219], v[150:153], v[50:53]
	v_mfma_f32_16x16x32_bf16 v[38:41], v[208:211], v[158:161], v[38:41]
	v_mfma_f32_16x16x32_bf16 v[34:37], v[216:219], v[158:161], v[34:37]
	v_mfma_f32_16x16x32_bf16 v[22:25], v[208:211], v[166:169], v[22:25]
	v_mfma_f32_16x16x32_bf16 v[18:21], v[216:219], v[166:169], v[18:21]
	v_mfma_f32_16x16x32_bf16 v[6:9], v[208:211], v[190:193], v[6:9]
	v_mfma_f32_16x16x32_bf16 v[2:5], v[216:219], v[190:193], v[2:5]
	s_setprio 0
	s_add_i32 s48, 0, 0x18000
	v_add_u32_e32 v86, s48, v196
	s_barrier
	ds_read_b128 v[66:69], v86
	ds_read_b128 v[74:77], v86 offset:1024
	ds_read_b128 v[82:85], v86 offset:2048
	ds_read_b128 v[86:89], v86 offset:3072
	s_add_u32 s24, s24, 0x40000
	s_addc_u32 s25, s25, 0
	s_mov_b32 m0, s33
	v_lshl_add_u64 v[202:203], s[24:25], 0, v[170:171]
	ds_read_b128 v[146:149], v199 offset:32768
	ds_read_b128 v[150:153], v199 offset:33792
	ds_read_b128 v[154:157], v199 offset:34816
	ds_read_b128 v[158:161], v199 offset:35840
	ds_read_b128 v[162:165], v199 offset:36864
	ds_read_b128 v[166:169], v199 offset:37888
	ds_read_b128 v[186:189], v199 offset:38912
	ds_read_b128 v[190:193], v199 offset:39936
	global_load_lds_dwordx4 v[202:203], off
	v_lshl_add_u64 v[202:203], s[24:25], 0, v[174:175]
	s_mov_b32 m0, s34
	s_nop 0
	global_load_lds_dwordx4 v[202:203], off
	s_waitcnt lgkmcnt(8)
	s_barrier
	s_waitcnt lgkmcnt(0)
	s_setprio 1
	s_waitcnt lgkmcnt(0)
	v_mfma_f32_16x16x32_bf16 v[142:145], v[66:69], v[146:149], v[142:145]
	v_mfma_f32_16x16x32_bf16 v[138:141], v[82:85], v[146:149], v[138:141]
	v_mfma_f32_16x16x32_bf16 v[126:129], v[66:69], v[154:157], v[126:129]
	v_mfma_f32_16x16x32_bf16 v[122:125], v[82:85], v[154:157], v[122:125]
	v_mfma_f32_16x16x32_bf16 v[110:113], v[66:69], v[162:165], v[110:113]
	v_mfma_f32_16x16x32_bf16 v[106:109], v[82:85], v[162:165], v[106:109]
	v_mfma_f32_16x16x32_bf16 v[94:97], v[66:69], v[186:189], v[94:97]
	v_mfma_f32_16x16x32_bf16 v[90:93], v[82:85], v[186:189], v[90:93]
	v_mfma_f32_16x16x32_bf16 v[142:145], v[74:77], v[150:153], v[142:145]
	v_mfma_f32_16x16x32_bf16 v[138:141], v[86:89], v[150:153], v[138:141]
	v_mfma_f32_16x16x32_bf16 v[126:129], v[74:77], v[158:161], v[126:129]
	v_mfma_f32_16x16x32_bf16 v[122:125], v[86:89], v[158:161], v[122:125]
	v_mfma_f32_16x16x32_bf16 v[110:113], v[74:77], v[166:169], v[110:113]
	v_mfma_f32_16x16x32_bf16 v[106:109], v[86:89], v[166:169], v[106:109]
	v_mfma_f32_16x16x32_bf16 v[94:97], v[74:77], v[190:193], v[94:97]
	v_mfma_f32_16x16x32_bf16 v[90:93], v[86:89], v[190:193], v[90:93]
	s_setprio 0
	s_barrier
	s_add_i32 s24, 0, 0x1c000
	s_add_i32 s25, s48, s29
	v_add_u32_e32 v201, s24, v196
	v_lshl_add_u64 v[194:195], v[194:195], 0, s[8:9]
	s_mov_b32 m0, s25
	ds_read_b128 v[202:205], v201
	ds_read_b128 v[208:211], v201 offset:1024
	ds_read_b128 v[212:215], v201 offset:2048
	ds_read_b128 v[216:219], v201 offset:3072
	global_load_lds_dwordx4 v[194:195], off
	v_lshl_add_u64 v[194:195], v[220:221], 0, s[8:9]
	s_add_i32 m0, s25, 0x2000
	s_nop 0
	global_load_lds_dwordx4 v[194:195], off
	s_barrier
; #define PG8_STAGE(bufoff, gbase, voff) do { _Pragma("unroll") for (int _i = 0; _i < 2; ++_i) \
;         __builtin_amdgcn_global_load_lds((const unsigned*)((const char*)(gbase) + (voff)[_i]), (LAS unsigned*)(lds + (bufoff) + ldsw + _i * 8192), 16, 0, 0); } while (0)
; #define PG8_LDA(dst, b, h) do { _Pragma("unroll") for (int m = 0; m < 4; ++m) _Pragma("unroll") for (int k = 0; k < 2; ++k) dst[m][k] = *(const LAS bf16x8*)(lds + PG8_SA(b, h) + aoff + m * 2048 + k * 1024); } while (0)
; #define PG8_MMA(ai, bj, At, Bt) do { __builtin_amdgcn_s_setprio(1); _Pragma("unroll") for (int m = 0; m < 4; ++m) _Pragma("unroll") for (int n = 0; n < 2; ++n) _Pragma("unroll") for (int k = 0; k < 2; ++k) \
;         acc[ai][bj][m][n] = __builtin_amdgcn_mfma_f32_16x16x32_bf16(Bt[n][k], At[m][k], acc[ai][bj][m][n], 0, 0, 0); __builtin_amdgcn_s_setprio(0); } while (0)
; #define PG8_WAIT_V(n) asm volatile("s_waitcnt vmcnt(" #n ")" ::: "memory")
; #define PG8_WAIT_L(n) asm volatile("s_waitcnt lgkmcnt(" #n ")" ::: "memory")
; #define PG8_BAR __builtin_amdgcn_s_barrier()
; #define PG8_SCHED __builtin_amdgcn_sched_barrier(0)
; template <class Epi, class Sched>
; __device__ __forceinline__ void gemm_phase(LAS unsigned char* lds, const Gemm g, const Sched& S, const Epi& E) {
;     ...
;             PG8_BAR; PG8_WAIT_L(0); PG8_MMA(0, 1, At, B1); PG8_BAR;
;             PG8_LDA(At, 1, 1); PG8_STAGE(PG8_SA(1, 0), a3, voffA);
;             PG8_BAR; PG8_WAIT_L(0); PG8_MMA(1, 0, At, B0); PG8_BAR; PG8_SCHED;
;             PG8_STAGE(PG8_SB(1, 1), b3 + hstep, voffB);
;             PG8_WAIT_V(6); PG8_BAR; PG8_MMA(1, 1, At, B1); PG8_BAR;
;         }
	s_waitcnt lgkmcnt(0)
	s_setprio 1
	s_waitcnt lgkmcnt(0)
	v_mfma_f32_16x16x32_bf16 v[134:137], v[202:205], v[146:149], v[134:137]
	v_mfma_f32_16x16x32_bf16 v[130:133], v[212:215], v[146:149], v[130:133]
	v_mfma_f32_16x16x32_bf16 v[118:121], v[202:205], v[154:157], v[118:121]
	v_mfma_f32_16x16x32_bf16 v[114:117], v[212:215], v[154:157], v[114:117]
	v_mfma_f32_16x16x32_bf16 v[102:105], v[202:205], v[162:165], v[102:105]
	v_mfma_f32_16x16x32_bf16 v[98:101], v[212:215], v[162:165], v[98:101]
	v_mfma_f32_16x16x32_bf16 v[78:81], v[202:205], v[186:189], v[78:81]
	v_mfma_f32_16x16x32_bf16 v[70:73], v[212:215], v[186:189], v[70:73]
	v_mfma_f32_16x16x32_bf16 v[134:137], v[208:211], v[150:153], v[134:137]
	v_mfma_f32_16x16x32_bf16 v[130:133], v[216:219], v[150:153], v[130:133]
	v_mfma_f32_16x16x32_bf16 v[118:121], v[208:211], v[158:161], v[118:121]
	v_mfma_f32_16x16x32_bf16 v[114:117], v[216:219], v[158:161], v[114:117]
	v_mfma_f32_16x16x32_bf16 v[102:105], v[208:211], v[166:169], v[102:105]
	v_mfma_f32_16x16x32_bf16 v[98:101], v[216:219], v[166:169], v[98:101]
	v_mfma_f32_16x16x32_bf16 v[78:81], v[208:211], v[190:193], v[78:81]
	v_mfma_f32_16x16x32_bf16 v[70:73], v[216:219], v[190:193], v[70:73]
	s_setprio 0
	s_mov_b32 m0, s37
	v_lshl_add_u64 v[194:195], v[222:223], 0, s[8:9]
	s_barrier
	ds_read_b128 v[146:149], v199 offset:49152
	ds_read_b128 v[150:153], v199 offset:50176
	ds_read_b128 v[154:157], v199 offset:51200
	ds_read_b128 v[158:161], v199 offset:52224
	ds_read_b128 v[162:165], v199 offset:53248
	ds_read_b128 v[166:169], v199 offset:54272
	ds_read_b128 v[186:189], v199 offset:55296
	ds_read_b128 v[190:193], v199 offset:56320
	global_load_lds_dwordx4 v[194:195], off
	v_lshl_add_u64 v[194:195], v[224:225], 0, s[8:9]
	s_mov_b32 m0, s38
	s_nop 0
	global_load_lds_dwordx4 v[194:195], off
	s_barrier
	s_waitcnt lgkmcnt(0)
	s_setprio 1
	s_waitcnt lgkmcnt(0)
	v_mfma_f32_16x16x32_bf16 v[62:65], v[66:69], v[146:149], v[62:65]
	v_mfma_f32_16x16x32_bf16 v[58:61], v[82:85], v[146:149], v[58:61]
	v_mfma_f32_16x16x32_bf16 v[46:49], v[66:69], v[154:157], v[46:49]
	v_mfma_f32_16x16x32_bf16 v[42:45], v[82:85], v[154:157], v[42:45]
	v_mfma_f32_16x16x32_bf16 v[30:33], v[66:69], v[162:165], v[30:33]
	v_mfma_f32_16x16x32_bf16 v[26:29], v[82:85], v[162:165], v[26:29]
	v_mfma_f32_16x16x32_bf16 v[14:17], v[66:69], v[186:189], v[14:17]
	v_mfma_f32_16x16x32_bf16 v[10:13], v[82:85], v[186:189], v[10:13]
	v_mfma_f32_16x16x32_bf16 v[62:65], v[74:77], v[150:153], v[62:65]
	v_mfma_f32_16x16x32_bf16 v[58:61], v[86:89], v[150:153], v[58:61]
	v_mfma_f32_16x16x32_bf16 v[46:49], v[74:77], v[158:161], v[46:49]
	v_mfma_f32_16x16x32_bf16 v[42:45], v[86:89], v[158:161], v[42:45]
	v_mfma_f32_16x16x32_bf16 v[30:33], v[74:77], v[166:169], v[30:33]
	v_mfma_f32_16x16x32_bf16 v[26:29], v[86:89], v[166:169], v[26:29]
	v_mfma_f32_16x16x32_bf16 v[14:17], v[74:77], v[190:193], v[14:17]
	v_mfma_f32_16x16x32_bf16 v[10:13], v[86:89], v[190:193], v[10:13]
	s_setprio 0
	s_barrier
	s_add_u32 s22, s22, 0x40080
	s_addc_u32 s23, s23, 0
	s_add_i32 s24, s24, s29
	v_lshl_add_u64 v[66:67], s[22:23], 0, v[172:173]
	s_mov_b32 m0, s24
	s_nop 0
	global_load_lds_dwordx4 v[66:67], off
	v_lshl_add_u64 v[66:67], s[22:23], 0, v[176:177]
	s_add_i32 m0, s24, 0x2000
	s_nop 0
	global_load_lds_dwordx4 v[66:67], off
	s_waitcnt vmcnt(6)
	s_barrier
	s_setprio 1
	v_mfma_f32_16x16x32_bf16 v[54:57], v[202:205], v[146:149], v[54:57]
	v_mfma_f32_16x16x32_bf16 v[50:53], v[212:215], v[146:149], v[50:53]
	v_mfma_f32_16x16x32_bf16 v[38:41], v[202:205], v[154:157], v[38:41]
	v_mfma_f32_16x16x32_bf16 v[34:37], v[212:215], v[154:157], v[34:37]
	v_mfma_f32_16x16x32_bf16 v[22:25], v[202:205], v[162:165], v[22:25]
	v_mfma_f32_16x16x32_bf16 v[18:21], v[212:215], v[162:165], v[18:21]
	v_mfma_f32_16x16x32_bf16 v[6:9], v[202:205], v[186:189], v[6:9]
	v_mfma_f32_16x16x32_bf16 v[2:5], v[212:215], v[186:189], v[2:5]
	v_mfma_f32_16x16x32_bf16 v[54:57], v[208:211], v[150:153], v[54:57]
	v_mfma_f32_16x16x32_bf16 v[50:53], v[216:219], v[150:153], v[50:53]
	v_mfma_f32_16x16x32_bf16 v[38:41], v[208:211], v[158:161], v[38:41]
	v_mfma_f32_16x16x32_bf16 v[34:37], v[216:219], v[158:161], v[34:37]
	v_mfma_f32_16x16x32_bf16 v[22:25], v[208:211], v[166:169], v[22:25]
	v_mfma_f32_16x16x32_bf16 v[18:21], v[216:219], v[166:169], v[18:21]
	v_mfma_f32_16x16x32_bf16 v[6:9], v[208:211], v[190:193], v[6:9]
	v_mfma_f32_16x16x32_bf16 v[2:5], v[216:219], v[190:193], v[2:5]
	s_setprio 0
	s_add_i32 s47, s47, 2
	s_add_u32 s20, s20, 0x100
	s_addc_u32 s21, s21, 0
	s_add_u32 s45, s45, 0x100
	s_addc_u32 s46, s46, 0
	s_cmp_gt_u32 s47, 13
	s_barrier

; #define PG8_STAGE(bufoff, gbase, voff) do { _Pragma("unroll") for (int _i = 0; _i < 2; ++_i) \
;         __builtin_amdgcn_global_load_lds((const unsigned*)((const char*)(gbase) + (voff)[_i]), (LAS unsigned*)(lds + (bufoff) + ldsw + _i * 8192), 16, 0, 0); } while (0)
; #define PG8_LDA(dst, b, h) do { _Pragma("unroll") for (int m = 0; m < 4; ++m) _Pragma("unroll") for (int k = 0; k < 2; ++k) dst[m][k] = *(const LAS bf16x8*)(lds + PG8_SA(b, h) + aoff + m * 2048 + k * 1024); } while (0)
; #define PG8_LDB(dst, b, h) do { _Pragma("unroll") for (int n = 0; n < 2; ++n) _Pragma("unroll") for (int k = 0; k < 2; ++k) dst[n][k] = *(const LAS bf16x8*)(lds + PG8_SB(b, h) + boff + n * 2048 + k * 1024); } while (0)
; #define PG8_MMA(ai, bj, At, Bt) do { __builtin_amdgcn_s_setprio(1); _Pragma("unroll") for (int m = 0; m < 4; ++m) _Pragma("unroll") for (int n = 0; n < 2; ++n) _Pragma("unroll") for (int k = 0; k < 2; ++k) \
;         acc[ai][bj][m][n] = __builtin_amdgcn_mfma_f32_16x16x32_bf16(Bt[n][k], At[m][k], acc[ai][bj][m][n], 0, 0, 0); __builtin_amdgcn_s_setprio(0); } while (0)
; #define PG8_BAR __builtin_amdgcn_s_barrier()
; template <class Epi, class Sched>
; __device__ __forceinline__ void gemm_phase(LAS unsigned char* lds, const Gemm g, const Sched& S, const Epi& E) {
;     ...
;         const bool has_next = S.next(ui + 1, nxt);
;         const char* nA = has_next ? (const char*)g.A + (size_t)nxt.pm * tstep : cA; const char* nB = has_next ? (const char*)g.Bt + (size_t)nxt.pn * tstep : cB;
;         for (int t = 0; t < nt; t += 2) {
;             const bool last = (t == nt - 2);
;             const char* a1 = cA + (size_t)(t + 1) * kstep;
;             const char* a2 = last ? nA : cA + (size_t)(t + 2) * kstep; const char* b2 = last ? nB : cB + (size_t)(t + 2) * kstep;
;             const char* a3 = a2 + kstep; const char* b3 = b2 + kstep;
;             if (last && has_next) S.a_ready(nxt);
;             PG8_LDB(B0, 0, 0); PG8_SCHED; PG8_LDA(At, 0, 0); PG8_STAGE(PG8_SA(1, 1), a1 + hstep, voffA);
;             PG8_WAIT_L(8); PG8_BAR; PG8_WAIT_L(0); PG8_MMA(0, 0, At, B0); PG8_BAR; PG8_SCHED;
;             PG8_LDB(B1, 0, 1); PG8_STAGE(PG8_SB(0, 0), b2, voffB);
;             PG8_BAR; PG8_WAIT_L(0); PG8_MMA(0, 1, At, B1); PG8_BAR;
;             PG8_LDA(At, 0, 1); PG8_STAGE(PG8_SA(0, 0), a2, voffA);
;             PG8_BAR; PG8_WAIT_L(0); PG8_MMA(1, 0, At, B0); PG8_BAR; PG8_SCHED;
.LBB0_1002:
	s_ashr_i32 s15, s14, 31
	v_cmp_lt_i64_e32 vcc, s[16:17], v[166:167]
	s_lshl_b64 s[16:17], s[14:15], 20
	s_add_u32 s16, s31, s16
	s_addc_u32 s17, s33, s17
	s_and_b64 s[18:19], vcc, exec
	s_cselect_b32 s15, s17, s25
	s_cselect_b32 s21, s16, s24
	s_ashr_i32 s13, s12, 31
	s_lshl_b64 s[18:19], s[12:13], 20
	s_add_u32 s18, s34, s18
	s_addc_u32 s19, s35, s19
	s_and_b64 s[28:29], vcc, exec
	s_cselect_b32 s13, s19, s27
	s_cselect_b32 s48, s18, s26
	s_add_u32 s24, s24, 0x80080
	s_addc_u32 s25, s25, 0
	s_add_u32 s49, s26, 0x100
	s_addc_u32 s50, s27, 0
	s_mov_b32 s51, -2
	s_waitcnt lgkmcnt(0)
	ds_read_b128 v[130:133], v190
	ds_read_b128 v[134:137], v190 offset:1024
	ds_read_b128 v[138:141], v190 offset:2048
	ds_read_b128 v[142:145], v190 offset:3072
	s_add_u32 s26, s24, 0xfff80080
	s_addc_u32 s27, s25, -1
	s_cmp_eq_u32 s51, 28
	s_cselect_b32 s29, s15, s27
	s_cselect_b32 s28, s21, s26
	s_cselect_b32 s27, s13, s50
	s_cselect_b32 s26, s48, s49
	v_lshl_add_u64 v[186:187], s[24:25], 0, v[162:163]
	s_add_i32 m0, s23, 0xc000
	ds_read_b128 v[146:149], v191
	ds_read_b128 v[150:153], v191 offset:1024
	ds_read_b128 v[170:173], v191 offset:2048
	ds_read_b128 v[174:177], v191 offset:3072
	ds_read_b128 v[178:181], v191 offset:4096
	ds_read_b128 v[182:185], v191 offset:5120
	ds_read_b128 v[194:197], v191 offset:6144
	ds_read_b128 v[198:201], v191 offset:7168
	global_load_lds_dwordx4 v[186:187], off
	v_lshl_add_u64 v[186:187], s[24:25], 0, v[164:165]
	s_add_i32 m0, s23, 0xe000
	s_nop 0
	global_load_lds_dwordx4 v[186:187], off
	s_waitcnt lgkmcnt(8)
	s_barrier
	s_waitcnt lgkmcnt(0)
	s_setprio 1
	s_waitcnt lgkmcnt(0)
	v_mfma_f32_16x16x32_bf16 v[126:129], v[130:133], v[146:149], 0
	v_mfma_f32_16x16x32_bf16 v[122:125], v[138:141], v[146:149], 0
	v_mfma_f32_16x16x32_bf16 v[110:113], v[130:133], v[170:173], 0
	v_mfma_f32_16x16x32_bf16 v[106:109], v[138:141], v[170:173], 0
	v_mfma_f32_16x16x32_bf16 v[94:97], v[130:133], v[178:181], 0
	v_mfma_f32_16x16x32_bf16 v[90:93], v[138:141], v[178:181], 0
	v_mfma_f32_16x16x32_bf16 v[78:81], v[130:133], v[194:197], 0
	v_mfma_f32_16x16x32_bf16 v[74:77], v[138:141], v[194:197], 0
	v_mfma_f32_16x16x32_bf16 v[126:129], v[134:137], v[150:153], v[126:129]
	v_mfma_f32_16x16x32_bf16 v[122:125], v[142:145], v[150:153], v[122:125]
	v_mfma_f32_16x16x32_bf16 v[110:113], v[134:137], v[174:177], v[110:113]
	v_mfma_f32_16x16x32_bf16 v[106:109], v[142:145], v[174:177], v[106:109]
	v_mfma_f32_16x16x32_bf16 v[94:97], v[134:137], v[182:185], v[94:97]
	v_mfma_f32_16x16x32_bf16 v[90:93], v[142:145], v[182:185], v[90:93]
	v_mfma_f32_16x16x32_bf16 v[78:81], v[134:137], v[198:201], v[78:81]
	v_mfma_f32_16x16x32_bf16 v[74:77], v[142:145], v[198:201], v[74:77]
	s_setprio 0
	s_barrier
	s_add_i32 s52, s46, s36
	v_lshl_add_u64 v[186:187], s[26:27], 0, v[156:157]
	s_mov_b32 m0, s52
	ds_read_b128 v[202:205], v192
	ds_read_b128 v[208:211], v192 offset:1024
	ds_read_b128 v[212:215], v192 offset:2048
	ds_read_b128 v[216:219], v192 offset:3072
	global_load_lds_dwordx4 v[186:187], off
	v_lshl_add_u64 v[220:221], s[26:27], 0, v[160:161]
	s_add_i32 m0, s52, 0x2000
	s_nop 0
	global_load_lds_dwordx4 v[220:221], off
	s_barrier
	s_waitcnt lgkmcnt(0)
	s_setprio 1
	s_waitcnt lgkmcnt(0)
	v_mfma_f32_16x16x32_bf16 v[118:121], v[202:205], v[146:149], 0
	v_mfma_f32_16x16x32_bf16 v[114:117], v[212:215], v[146:149], 0
	v_mfma_f32_16x16x32_bf16 v[102:105], v[202:205], v[170:173], 0
	v_mfma_f32_16x16x32_bf16 v[98:101], v[212:215], v[170:173], 0
	v_mfma_f32_16x16x32_bf16 v[86:89], v[202:205], v[178:181], 0
	v_mfma_f32_16x16x32_bf16 v[82:85], v[212:215], v[178:181], 0
	v_mfma_f32_16x16x32_bf16 v[70:73], v[202:205], v[194:197], 0
	v_mfma_f32_16x16x32_bf16 v[66:69], v[212:215], v[194:197], 0
	v_mfma_f32_16x16x32_bf16 v[118:121], v[208:211], v[150:153], v[118:121]
	v_mfma_f32_16x16x32_bf16 v[114:117], v[216:219], v[150:153], v[114:117]
	v_mfma_f32_16x16x32_bf16 v[102:105], v[208:211], v[174:177], v[102:105]
	v_mfma_f32_16x16x32_bf16 v[98:101], v[216:219], v[174:177], v[98:101]
	v_mfma_f32_16x16x32_bf16 v[86:89], v[208:211], v[182:185], v[86:89]
	v_mfma_f32_16x16x32_bf16 v[82:85], v[216:219], v[182:185], v[82:85]
	v_mfma_f32_16x16x32_bf16 v[70:73], v[208:211], v[198:201], v[70:73]
	v_mfma_f32_16x16x32_bf16 v[66:69], v[216:219], v[198:201], v[66:69]
	s_setprio 0
	s_mov_b32 m0, s23
	v_lshl_add_u64 v[222:223], s[28:29], 0, v[154:155]
	s_barrier
	ds_read_b128 v[146:149], v191 offset:16384
	ds_read_b128 v[150:153], v191 offset:17408
	ds_read_b128 v[170:173], v191 offset:18432
	ds_read_b128 v[174:177], v191 offset:19456
	ds_read_b128 v[178:181], v191 offset:20480
	ds_read_b128 v[182:185], v191 offset:21504
	ds_read_b128 v[194:197], v191 offset:22528
	ds_read_b128 v[198:201], v191 offset:23552
	global_load_lds_dwordx4 v[222:223], off
	v_lshl_add_u64 v[224:225], s[28:29], 0, v[158:159]
	s_mov_b32 m0, s37
	s_nop 0
	global_load_lds_dwordx4 v[224:225], off
	s_barrier
	s_waitcnt lgkmcnt(0)
	s_setprio 1
	s_waitcnt lgkmcnt(0)
	v_mfma_f32_16x16x32_bf16 v[62:65], v[130:133], v[146:149], 0
	v_mfma_f32_16x16x32_bf16 v[58:61], v[138:141], v[146:149], 0
	v_mfma_f32_16x16x32_bf16 v[46:49], v[130:133], v[170:173], 0
	v_mfma_f32_16x16x32_bf16 v[42:45], v[138:141], v[170:173], 0
	v_mfma_f32_16x16x32_bf16 v[30:33], v[130:133], v[178:181], 0
	v_mfma_f32_16x16x32_bf16 v[26:29], v[138:141], v[178:181], 0
	v_mfma_f32_16x16x32_bf16 v[14:17], v[130:133], v[194:197], 0
	v_mfma_f32_16x16x32_bf16 v[10:13], v[138:141], v[194:197], 0
	v_mfma_f32_16x16x32_bf16 v[62:65], v[134:137], v[150:153], v[62:65]
	v_mfma_f32_16x16x32_bf16 v[58:61], v[142:145], v[150:153], v[58:61]
	v_mfma_f32_16x16x32_bf16 v[46:49], v[134:137], v[174:177], v[46:49]
	v_mfma_f32_16x16x32_bf16 v[42:45], v[142:145], v[174:177], v[42:45]
	v_mfma_f32_16x16x32_bf16 v[30:33], v[134:137], v[182:185], v[30:33]
	v_mfma_f32_16x16x32_bf16 v[26:29], v[142:145], v[182:185], v[26:29]
	v_mfma_f32_16x16x32_bf16 v[14:17], v[134:137], v[198:201], v[14:17]
	v_mfma_f32_16x16x32_bf16 v[10:13], v[142:145], v[198:201], v[10:13]
	s_setprio 0
	s_barrier
; #define PG8_STAGE(bufoff, gbase, voff) do { _Pragma("unroll") for (int _i = 0; _i < 2; ++_i) \
;         __builtin_amdgcn_global_load_lds((const unsigned*)((const char*)(gbase) + (voff)[_i]), (LAS unsigned*)(lds + (bufoff) + ldsw + _i * 8192), 16, 0, 0); } while (0)
; #define PG8_LDA(dst, b, h) do { _Pragma("unroll") for (int m = 0; m < 4; ++m) _Pragma("unroll") for (int k = 0; k < 2; ++k) dst[m][k] = *(const LAS bf16x8*)(lds + PG8_SA(b, h) + aoff + m * 2048 + k * 1024); } while (0)
; #define PG8_LDB(dst, b, h) do { _Pragma("unroll") for (int n = 0; n < 2; ++n) _Pragma("unroll") for (int k = 0; k < 2; ++k) dst[n][k] = *(const LAS bf16x8*)(lds + PG8_SB(b, h) + boff + n * 2048 + k * 1024); } while (0)
; #define PG8_MMA(ai, bj, At, Bt) do { __builtin_amdgcn_s_setprio(1); _Pragma("unroll") for (int m = 0; m < 4; ++m) _Pragma("unroll") for (int n = 0; n < 2; ++n) _Pragma("unroll") for (int k = 0; k < 2; ++k) \
;         acc[ai][bj][m][n] = __builtin_amdgcn_mfma_f32_16x16x32_bf16(Bt[n][k], At[m][k], acc[ai][bj][m][n], 0, 0, 0); __builtin_amdgcn_s_setprio(0); } while (0)
; #define PG8_WAIT_V(n) asm volatile("s_waitcnt vmcnt(" #n ")" ::: "memory")
; #define PG8_WAIT_L(n) asm volatile("s_waitcnt lgkmcnt(" #n ")" ::: "memory")
; #define PG8_BAR __builtin_amdgcn_s_barrier()
; #define PG8_SCHED __builtin_amdgcn_sched_barrier(0)
; template <class Epi, class Sched>
; __device__ __forceinline__ void gemm_phase(LAS unsigned char* lds, const Gemm g, const Sched& S, const Epi& E) {
;     ...
;             PG8_STAGE(PG8_SB(0, 1), b2 + hstep, voffB);
;             PG8_WAIT_V(6); PG8_BAR; PG8_MMA(1, 1, At, B1); PG8_BAR;
;             PG8_LDB(B0, 1, 0); PG8_SCHED; PG8_LDA(At, 1, 0); PG8_STAGE(PG8_SA(0, 1), a2 + hstep, voffA);
;             PG8_WAIT_L(8); PG8_BAR; PG8_WAIT_L(0); PG8_MMA(0, 0, At, B0); PG8_BAR; PG8_SCHED;
;             PG8_LDB(B1, 1, 1); PG8_STAGE(PG8_SB(1, 0), b3, voffB);
	s_add_u32 s52, s26, 0x80000
	s_addc_u32 s53, s27, 0
	s_add_i32 s54, s47, s36
	v_lshl_add_u64 v[130:131], s[52:53], 0, v[156:157]
	s_mov_b32 m0, s54
	s_nop 0
	global_load_lds_dwordx4 v[130:131], off
	v_lshl_add_u64 v[130:131], s[52:53], 0, v[160:161]
	s_add_i32 m0, s54, 0x2000
	s_nop 0
	global_load_lds_dwordx4 v[130:131], off
	s_waitcnt vmcnt(6)
	s_barrier
	s_setprio 1
	v_mfma_f32_16x16x32_bf16 v[54:57], v[202:205], v[146:149], 0
	v_mfma_f32_16x16x32_bf16 v[50:53], v[212:215], v[146:149], 0
	v_mfma_f32_16x16x32_bf16 v[38:41], v[202:205], v[170:173], 0
	v_mfma_f32_16x16x32_bf16 v[34:37], v[212:215], v[170:173], 0
	v_mfma_f32_16x16x32_bf16 v[22:25], v[202:205], v[178:181], 0
	v_mfma_f32_16x16x32_bf16 v[18:21], v[212:215], v[178:181], 0
	v_mfma_f32_16x16x32_bf16 v[6:9], v[202:205], v[194:197], 0
	v_mfma_f32_16x16x32_bf16 v[2:5], v[212:215], v[194:197], 0
	v_mfma_f32_16x16x32_bf16 v[54:57], v[208:211], v[150:153], v[54:57]
	v_mfma_f32_16x16x32_bf16 v[50:53], v[216:219], v[150:153], v[50:53]
	v_mfma_f32_16x16x32_bf16 v[38:41], v[208:211], v[174:177], v[38:41]
	v_mfma_f32_16x16x32_bf16 v[34:37], v[216:219], v[174:177], v[34:37]
	v_mfma_f32_16x16x32_bf16 v[22:25], v[208:211], v[182:185], v[22:25]
	v_mfma_f32_16x16x32_bf16 v[18:21], v[216:219], v[182:185], v[18:21]
	v_mfma_f32_16x16x32_bf16 v[6:9], v[208:211], v[198:201], v[6:9]
	v_mfma_f32_16x16x32_bf16 v[2:5], v[216:219], v[198:201], v[2:5]
	s_setprio 0
	s_add_i32 s52, 0, 0x18000
	v_add_u32_e32 v142, s52, v188
	s_barrier
	ds_read_b128 v[130:133], v142
	ds_read_b128 v[134:137], v142 offset:1024
	ds_read_b128 v[138:141], v142 offset:2048
	ds_read_b128 v[142:145], v142 offset:3072
	s_add_u32 s28, s28, 0x80000
	s_addc_u32 s29, s29, 0
	s_mov_b32 m0, s38
	v_lshl_add_u64 v[202:203], s[28:29], 0, v[154:155]
	ds_read_b128 v[146:149], v191 offset:32768
	ds_read_b128 v[150:153], v191 offset:33792
	ds_read_b128 v[170:173], v191 offset:34816
	ds_read_b128 v[174:177], v191 offset:35840
	ds_read_b128 v[178:181], v191 offset:36864
	ds_read_b128 v[182:185], v191 offset:37888
	ds_read_b128 v[194:197], v191 offset:38912
	ds_read_b128 v[198:201], v191 offset:39936
	global_load_lds_dwordx4 v[202:203], off
	v_lshl_add_u64 v[202:203], s[28:29], 0, v[158:159]
	s_mov_b32 m0, s39
	s_nop 0
	global_load_lds_dwordx4 v[202:203], off
	s_waitcnt lgkmcnt(8)
	s_barrier
	s_waitcnt lgkmcnt(0)
	s_setprio 1
	s_waitcnt lgkmcnt(0)
	v_mfma_f32_16x16x32_bf16 v[126:129], v[130:133], v[146:149], v[126:129]
	v_mfma_f32_16x16x32_bf16 v[122:125], v[138:141], v[146:149], v[122:125]
	v_mfma_f32_16x16x32_bf16 v[110:113], v[130:133], v[170:173], v[110:113]
	v_mfma_f32_16x16x32_bf16 v[106:109], v[138:141], v[170:173], v[106:109]
	v_mfma_f32_16x16x32_bf16 v[94:97], v[130:133], v[178:181], v[94:97]
	v_mfma_f32_16x16x32_bf16 v[90:93], v[138:141], v[178:181], v[90:93]
	v_mfma_f32_16x16x32_bf16 v[78:81], v[130:133], v[194:197], v[78:81]
	v_mfma_f32_16x16x32_bf16 v[74:77], v[138:141], v[194:197], v[74:77]
	v_mfma_f32_16x16x32_bf16 v[126:129], v[134:137], v[150:153], v[126:129]
	v_mfma_f32_16x16x32_bf16 v[122:125], v[142:145], v[150:153], v[122:125]
	v_mfma_f32_16x16x32_bf16 v[110:113], v[134:137], v[174:177], v[110:113]
	v_mfma_f32_16x16x32_bf16 v[106:109], v[142:145], v[174:177], v[106:109]
	v_mfma_f32_16x16x32_bf16 v[94:97], v[134:137], v[182:185], v[94:97]
	v_mfma_f32_16x16x32_bf16 v[90:93], v[142:145], v[182:185], v[90:93]
	v_mfma_f32_16x16x32_bf16 v[78:81], v[134:137], v[198:201], v[78:81]
	v_mfma_f32_16x16x32_bf16 v[74:77], v[142:145], v[198:201], v[74:77]
	s_setprio 0
	s_barrier
	s_add_i32 s28, 0, 0x1c000
	s_add_i32 s29, s52, s36
	v_add_u32_e32 v207, s28, v188
	v_lshl_add_u64 v[186:187], v[186:187], 0, s[10:11]
	s_mov_b32 m0, s29
	ds_read_b128 v[202:205], v207
	ds_read_b128 v[208:211], v207 offset:1024
	ds_read_b128 v[212:215], v207 offset:2048
	ds_read_b128 v[216:219], v207 offset:3072
	global_load_lds_dwordx4 v[186:187], off
	v_lshl_add_u64 v[186:187], v[220:221], 0, s[10:11]
	s_add_i32 m0, s29, 0x2000
	s_nop 0
	global_load_lds_dwordx4 v[186:187], off
	s_barrier
; #define PG8_STAGE(bufoff, gbase, voff) do { _Pragma("unroll") for (int _i = 0; _i < 2; ++_i) \
;         __builtin_amdgcn_global_load_lds((const unsigned*)((const char*)(gbase) + (voff)[_i]), (LAS unsigned*)(lds + (bufoff) + ldsw + _i * 8192), 16, 0, 0); } while (0)
; #define PG8_LDA(dst, b, h) do { _Pragma("unroll") for (int m = 0; m < 4; ++m) _Pragma("unroll") for (int k = 0; k < 2; ++k) dst[m][k] = *(const LAS bf16x8*)(lds + PG8_SA(b, h) + aoff + m * 2048 + k * 1024); } while (0)
; #define PG8_MMA(ai, bj, At, Bt) do { __builtin_amdgcn_s_setprio(1); _Pragma("unroll") for (int m = 0; m < 4; ++m) _Pragma("unroll") for (int n = 0; n < 2; ++n) _Pragma("unroll") for (int k = 0; k < 2; ++k) \
;         acc[ai][bj][m][n] = __builtin_amdgcn_mfma_f32_16x16x32_bf16(Bt[n][k], At[m][k], acc[ai][bj][m][n], 0, 0, 0); __builtin_amdgcn_s_setprio(0); } while (0)
; #define PG8_WAIT_V(n) asm volatile("s_waitcnt vmcnt(" #n ")" ::: "memory")
; #define PG8_WAIT_L(n) asm volatile("s_waitcnt lgkmcnt(" #n ")" ::: "memory")
; #define PG8_BAR __builtin_amdgcn_s_barrier()
; #define PG8_SCHED __builtin_amdgcn_sched_barrier(0)
; template <class Epi, class Sched>
; __device__ __forceinline__ void gemm_phase(LAS unsigned char* lds, const Gemm g, const Sched& S, const Epi& E) {
;     ...
;             PG8_BAR; PG8_WAIT_L(0); PG8_MMA(0, 1, At, B1); PG8_BAR;
;             PG8_LDA(At, 1, 1); PG8_STAGE(PG8_SA(1, 0), a3, voffA);
;             PG8_BAR; PG8_WAIT_L(0); PG8_MMA(1, 0, At, B0); PG8_BAR; PG8_SCHED;
;             PG8_STAGE(PG8_SB(1, 1), b3 + hstep, voffB);
;             PG8_WAIT_V(6); PG8_BAR; PG8_MMA(1, 1, At, B1); PG8_BAR;
;         }
	s_waitcnt lgkmcnt(0)
	s_setprio 1
	s_waitcnt lgkmcnt(0)
	v_mfma_f32_16x16x32_bf16 v[118:121], v[202:205], v[146:149], v[118:121]
	v_mfma_f32_16x16x32_bf16 v[114:117], v[212:215], v[146:149], v[114:117]
	v_mfma_f32_16x16x32_bf16 v[102:105], v[202:205], v[170:173], v[102:105]
	v_mfma_f32_16x16x32_bf16 v[98:101], v[212:215], v[170:173], v[98:101]
	v_mfma_f32_16x16x32_bf16 v[86:89], v[202:205], v[178:181], v[86:89]
	v_mfma_f32_16x16x32_bf16 v[82:85], v[212:215], v[178:181], v[82:85]
	v_mfma_f32_16x16x32_bf16 v[70:73], v[202:205], v[194:197], v[70:73]
	v_mfma_f32_16x16x32_bf16 v[66:69], v[212:215], v[194:197], v[66:69]
	v_mfma_f32_16x16x32_bf16 v[118:121], v[208:211], v[150:153], v[118:121]
	v_mfma_f32_16x16x32_bf16 v[114:117], v[216:219], v[150:153], v[114:117]
	v_mfma_f32_16x16x32_bf16 v[102:105], v[208:211], v[174:177], v[102:105]
	v_mfma_f32_16x16x32_bf16 v[98:101], v[216:219], v[174:177], v[98:101]
	v_mfma_f32_16x16x32_bf16 v[86:89], v[208:211], v[182:185], v[86:89]
	v_mfma_f32_16x16x32_bf16 v[82:85], v[216:219], v[182:185], v[82:85]
	v_mfma_f32_16x16x32_bf16 v[70:73], v[208:211], v[198:201], v[70:73]
	v_mfma_f32_16x16x32_bf16 v[66:69], v[216:219], v[198:201], v[66:69]
	s_setprio 0
	s_mov_b32 m0, s43
	v_lshl_add_u64 v[186:187], v[222:223], 0, s[10:11]
	s_barrier
	ds_read_b128 v[146:149], v191 offset:49152
	ds_read_b128 v[150:153], v191 offset:50176
	ds_read_b128 v[170:173], v191 offset:51200
	ds_read_b128 v[174:177], v191 offset:52224
	ds_read_b128 v[178:181], v191 offset:53248
	ds_read_b128 v[182:185], v191 offset:54272
	ds_read_b128 v[194:197], v191 offset:55296
	ds_read_b128 v[198:201], v191 offset:56320
	global_load_lds_dwordx4 v[186:187], off
	v_lshl_add_u64 v[186:187], v[224:225], 0, s[10:11]
	s_mov_b32 m0, s44
	s_nop 0
	global_load_lds_dwordx4 v[186:187], off
	s_barrier
	s_waitcnt lgkmcnt(0)
	s_setprio 1
	s_waitcnt lgkmcnt(0)
	v_mfma_f32_16x16x32_bf16 v[62:65], v[130:133], v[146:149], v[62:65]
	v_mfma_f32_16x16x32_bf16 v[58:61], v[138:141], v[146:149], v[58:61]
	v_mfma_f32_16x16x32_bf16 v[46:49], v[130:133], v[170:173], v[46:49]
	v_mfma_f32_16x16x32_bf16 v[42:45], v[138:141], v[170:173], v[42:45]
	v_mfma_f32_16x16x32_bf16 v[30:33], v[130:133], v[178:181], v[30:33]
	v_mfma_f32_16x16x32_bf16 v[26:29], v[138:141], v[178:181], v[26:29]
	v_mfma_f32_16x16x32_bf16 v[14:17], v[130:133], v[194:197], v[14:17]
	v_mfma_f32_16x16x32_bf16 v[10:13], v[138:141], v[194:197], v[10:13]
	v_mfma_f32_16x16x32_bf16 v[62:65], v[134:137], v[150:153], v[62:65]
	v_mfma_f32_16x16x32_bf16 v[58:61], v[142:145], v[150:153], v[58:61]
	v_mfma_f32_16x16x32_bf16 v[46:49], v[134:137], v[174:177], v[46:49]
	v_mfma_f32_16x16x32_bf16 v[42:45], v[142:145], v[174:177], v[42:45]
	v_mfma_f32_16x16x32_bf16 v[30:33], v[134:137], v[182:185], v[30:33]
	v_mfma_f32_16x16x32_bf16 v[26:29], v[142:145], v[182:185], v[26:29]
	v_mfma_f32_16x16x32_bf16 v[14:17], v[134:137], v[198:201], v[14:17]
	v_mfma_f32_16x16x32_bf16 v[10:13], v[142:145], v[198:201], v[10:13]
	s_setprio 0
	s_barrier
	s_add_u32 s26, s26, 0x80080
	s_addc_u32 s27, s27, 0
	s_add_i32 s28, s28, s36
	v_lshl_add_u64 v[130:131], s[26:27], 0, v[156:157]
	s_mov_b32 m0, s28
	s_nop 0
	global_load_lds_dwordx4 v[130:131], off
	v_lshl_add_u64 v[130:131], s[26:27], 0, v[160:161]
	s_add_i32 m0, s28, 0x2000
	s_nop 0
	global_load_lds_dwordx4 v[130:131], off
	s_waitcnt vmcnt(6)
	s_barrier
	s_setprio 1
	v_mfma_f32_16x16x32_bf16 v[54:57], v[202:205], v[146:149], v[54:57]
	v_mfma_f32_16x16x32_bf16 v[50:53], v[212:215], v[146:149], v[50:53]
	v_mfma_f32_16x16x32_bf16 v[38:41], v[202:205], v[170:173], v[38:41]
	v_mfma_f32_16x16x32_bf16 v[34:37], v[212:215], v[170:173], v[34:37]
	v_mfma_f32_16x16x32_bf16 v[22:25], v[202:205], v[178:181], v[22:25]
	v_mfma_f32_16x16x32_bf16 v[18:21], v[212:215], v[178:181], v[18:21]
	v_mfma_f32_16x16x32_bf16 v[6:9], v[202:205], v[194:197], v[6:9]
	v_mfma_f32_16x16x32_bf16 v[2:5], v[212:215], v[194:197], v[2:5]
	v_mfma_f32_16x16x32_bf16 v[54:57], v[208:211], v[150:153], v[54:57]
	v_mfma_f32_16x16x32_bf16 v[50:53], v[216:219], v[150:153], v[50:53]
	v_mfma_f32_16x16x32_bf16 v[38:41], v[208:211], v[174:177], v[38:41]
	v_mfma_f32_16x16x32_bf16 v[34:37], v[216:219], v[174:177], v[34:37]
	v_mfma_f32_16x16x32_bf16 v[22:25], v[208:211], v[182:185], v[22:25]
	v_mfma_f32_16x16x32_bf16 v[18:21], v[216:219], v[182:185], v[18:21]
	v_mfma_f32_16x16x32_bf16 v[6:9], v[208:211], v[198:201], v[6:9]
	v_mfma_f32_16x16x32_bf16 v[2:5], v[216:219], v[198:201], v[2:5]
	s_setprio 0
	s_add_i32 s51, s51, 2
	s_add_u32 s24, s24, 0x100
	s_addc_u32 s25, s25, 0
	s_add_u32 s49, s49, 0x100
	s_addc_u32 s50, s50, 0
	s_cmp_gt_u32 s51, 29
	s_barrier

; #define PG8_STAGE(bufoff, gbase, voff) do { _Pragma("unroll") for (int _i = 0; _i < 2; ++_i) \
;         __builtin_amdgcn_global_load_lds((const unsigned*)((const char*)(gbase) + (voff)[_i]), (LAS unsigned*)(lds + (bufoff) + ldsw + _i * 8192), 16, 0, 0); } while (0)
; #define PG8_LDA(dst, b, h) do { _Pragma("unroll") for (int m = 0; m < 4; ++m) _Pragma("unroll") for (int k = 0; k < 2; ++k) dst[m][k] = *(const LAS bf16x8*)(lds + PG8_SA(b, h) + aoff + m * 2048 + k * 1024); } while (0)
; #define PG8_LDB(dst, b, h) do { _Pragma("unroll") for (int n = 0; n < 2; ++n) _Pragma("unroll") for (int k = 0; k < 2; ++k) dst[n][k] = *(const LAS bf16x8*)(lds + PG8_SB(b, h) + boff + n * 2048 + k * 1024); } while (0)
; #define PG8_MMA(ai, bj, At, Bt) do { __builtin_amdgcn_s_setprio(1); _Pragma("unroll") for (int m = 0; m < 4; ++m) _Pragma("unroll") for (int n = 0; n < 2; ++n) _Pragma("unroll") for (int k = 0; k < 2; ++k) \
;         acc[ai][bj][m][n] = __builtin_amdgcn_mfma_f32_16x16x32_bf16(Bt[n][k], At[m][k], acc[ai][bj][m][n], 0, 0, 0); __builtin_amdgcn_s_setprio(0); } while (0)
; #define PG8_BAR __builtin_amdgcn_s_barrier()
; template <class Epi, class Sched>
; __device__ __forceinline__ void gemm_phase(LAS unsigned char* lds, const Gemm g, const Sched& S, const Epi& E) {
;     ...
;         const bool has_next = S.next(ui + 1, nxt);
;         const char* nA = has_next ? (const char*)g.A + (size_t)nxt.pm * tstep : cA; const char* nB = has_next ? (const char*)g.Bt + (size_t)nxt.pn * tstep : cB;
;         for (int t = 0; t < nt; t += 2) {
;             const bool last = (t == nt - 2);
;             const char* a1 = cA + (size_t)(t + 1) * kstep;
;             const char* a2 = last ? nA : cA + (size_t)(t + 2) * kstep; const char* b2 = last ? nB : cB + (size_t)(t + 2) * kstep;
;             const char* a3 = a2 + kstep; const char* b3 = b2 + kstep;
;             if (last && has_next) S.a_ready(nxt);
;             PG8_LDB(B0, 0, 0); PG8_SCHED; PG8_LDA(At, 0, 0); PG8_STAGE(PG8_SA(1, 1), a1 + hstep, voffA);
;             PG8_WAIT_L(8); PG8_BAR; PG8_WAIT_L(0); PG8_MMA(0, 0, At, B0); PG8_BAR; PG8_SCHED;
;             PG8_LDB(B1, 0, 1); PG8_STAGE(PG8_SB(0, 0), b2, voffB);
;             PG8_BAR; PG8_WAIT_L(0); PG8_MMA(0, 1, At, B1); PG8_BAR;
;             PG8_LDA(At, 0, 1); PG8_STAGE(PG8_SA(0, 0), a2, voffA);
;             PG8_BAR; PG8_WAIT_L(0); PG8_MMA(1, 0, At, B0); PG8_BAR; PG8_SCHED;
.LBB0_1090:
	s_ashr_i32 s11, s10, 31
	v_cmp_lt_i64_e32 vcc, s[12:13], v[142:143]
	s_lshl_b64 s[12:13], s[10:11], 20
	s_add_u32 s12, s28, s12
	s_addc_u32 s13, s29, s13
	s_and_b64 s[14:15], vcc, exec
	s_cselect_b32 s11, s13, s19
	s_cselect_b32 s45, s12, s18
	s_ashr_i32 s9, s8, 31
	s_lshl_b64 s[14:15], s[8:9], 20
	s_add_u32 s14, s30, s14
	s_addc_u32 s15, s31, s15
	s_and_b64 s[22:23], vcc, exec
	s_cselect_b32 s9, s15, s21
	s_cselect_b32 s46, s14, s20
	s_add_u32 s18, s18, 0x80080
	s_addc_u32 s19, s19, 0
	s_add_u32 s47, s20, 0x100
	s_addc_u32 s48, s21, 0
	s_mov_b32 s49, -2
	ds_read_b128 v[152:155], v149
	ds_read_b128 v[156:159], v149 offset:1024
	ds_read_b128 v[160:163], v149 offset:2048
	ds_read_b128 v[164:167], v149 offset:3072
	s_add_u32 s20, s18, 0xfff80080
	s_addc_u32 s21, s19, -1
	s_cmp_eq_u32 s49, 28
	s_cselect_b32 s23, s11, s21
	s_cselect_b32 s22, s45, s20
	s_cselect_b32 s21, s9, s48
	s_cselect_b32 s20, s46, s47
	v_lshl_add_u64 v[200:201], s[18:19], 0, v[138:139]
	s_add_i32 m0, s17, 0xc000
	ds_read_b128 v[168:171], v150
	ds_read_b128 v[172:175], v150 offset:1024
	ds_read_b128 v[176:179], v150 offset:2048
	ds_read_b128 v[180:183], v150 offset:3072
	ds_read_b128 v[184:187], v150 offset:4096
	ds_read_b128 v[188:191], v150 offset:5120
	ds_read_b128 v[192:195], v150 offset:6144
	ds_read_b128 v[196:199], v150 offset:7168
	global_load_lds_dwordx4 v[200:201], off
	v_lshl_add_u64 v[200:201], s[18:19], 0, v[140:141]
	s_add_i32 m0, s17, 0xe000
	s_nop 0
	global_load_lds_dwordx4 v[200:201], off
	s_waitcnt lgkmcnt(8)
	s_barrier
	s_waitcnt lgkmcnt(0)
	s_setprio 1
	s_waitcnt lgkmcnt(0)
	v_mfma_f32_16x16x32_bf16 v[126:129], v[152:155], v[168:171], 0
	v_mfma_f32_16x16x32_bf16 v[122:125], v[160:163], v[168:171], 0
	v_mfma_f32_16x16x32_bf16 v[110:113], v[152:155], v[176:179], 0
	v_mfma_f32_16x16x32_bf16 v[106:109], v[160:163], v[176:179], 0
	v_mfma_f32_16x16x32_bf16 v[94:97], v[152:155], v[184:187], 0
	v_mfma_f32_16x16x32_bf16 v[90:93], v[160:163], v[184:187], 0
	v_mfma_f32_16x16x32_bf16 v[78:81], v[152:155], v[192:195], 0
	v_mfma_f32_16x16x32_bf16 v[74:77], v[160:163], v[192:195], 0
	v_mfma_f32_16x16x32_bf16 v[126:129], v[156:159], v[172:175], v[126:129]
	v_mfma_f32_16x16x32_bf16 v[122:125], v[164:167], v[172:175], v[122:125]
	v_mfma_f32_16x16x32_bf16 v[110:113], v[156:159], v[180:183], v[110:113]
	v_mfma_f32_16x16x32_bf16 v[106:109], v[164:167], v[180:183], v[106:109]
	v_mfma_f32_16x16x32_bf16 v[94:97], v[156:159], v[188:191], v[94:97]
	v_mfma_f32_16x16x32_bf16 v[90:93], v[164:167], v[188:191], v[90:93]
	v_mfma_f32_16x16x32_bf16 v[78:81], v[156:159], v[196:199], v[78:81]
	v_mfma_f32_16x16x32_bf16 v[74:77], v[164:167], v[196:199], v[74:77]
	s_setprio 0
	s_barrier
	s_add_i32 s50, s39, s27
	v_lshl_add_u64 v[204:205], s[20:21], 0, v[132:133]
	s_mov_b32 m0, s50
	ds_read_b128 v[200:203], v151
	ds_read_b128 v[208:211], v151 offset:1024
	ds_read_b128 v[212:215], v151 offset:2048
	ds_read_b128 v[216:219], v151 offset:3072
	global_load_lds_dwordx4 v[204:205], off
	v_lshl_add_u64 v[220:221], s[20:21], 0, v[136:137]
	s_add_i32 m0, s50, 0x2000
	s_nop 0
	global_load_lds_dwordx4 v[220:221], off
	s_barrier
	s_waitcnt lgkmcnt(0)
	s_setprio 1
	s_waitcnt lgkmcnt(0)
	v_mfma_f32_16x16x32_bf16 v[118:121], v[200:203], v[168:171], 0
	v_mfma_f32_16x16x32_bf16 v[114:117], v[212:215], v[168:171], 0
	v_mfma_f32_16x16x32_bf16 v[102:105], v[200:203], v[176:179], 0
	v_mfma_f32_16x16x32_bf16 v[98:101], v[212:215], v[176:179], 0
	v_mfma_f32_16x16x32_bf16 v[86:89], v[200:203], v[184:187], 0
	v_mfma_f32_16x16x32_bf16 v[82:85], v[212:215], v[184:187], 0
	v_mfma_f32_16x16x32_bf16 v[70:73], v[200:203], v[192:195], 0
	v_mfma_f32_16x16x32_bf16 v[66:69], v[212:215], v[192:195], 0
	v_mfma_f32_16x16x32_bf16 v[118:121], v[208:211], v[172:175], v[118:121]
	v_mfma_f32_16x16x32_bf16 v[114:117], v[216:219], v[172:175], v[114:117]
	v_mfma_f32_16x16x32_bf16 v[102:105], v[208:211], v[180:183], v[102:105]
	v_mfma_f32_16x16x32_bf16 v[98:101], v[216:219], v[180:183], v[98:101]
	v_mfma_f32_16x16x32_bf16 v[86:89], v[208:211], v[188:191], v[86:89]
	v_mfma_f32_16x16x32_bf16 v[82:85], v[216:219], v[188:191], v[82:85]
	v_mfma_f32_16x16x32_bf16 v[70:73], v[208:211], v[196:199], v[70:73]
	v_mfma_f32_16x16x32_bf16 v[66:69], v[216:219], v[196:199], v[66:69]
	s_setprio 0
	s_mov_b32 m0, s17
	v_lshl_add_u64 v[222:223], s[22:23], 0, v[130:131]
	s_barrier
	ds_read_b128 v[168:171], v150 offset:16384
	ds_read_b128 v[172:175], v150 offset:17408
	ds_read_b128 v[176:179], v150 offset:18432
	ds_read_b128 v[180:183], v150 offset:19456
	ds_read_b128 v[184:187], v150 offset:20480
	ds_read_b128 v[188:191], v150 offset:21504
	ds_read_b128 v[192:195], v150 offset:22528
	ds_read_b128 v[196:199], v150 offset:23552
	global_load_lds_dwordx4 v[222:223], off
	v_lshl_add_u64 v[224:225], s[22:23], 0, v[134:135]
	s_mov_b32 m0, s34
	s_nop 0
	global_load_lds_dwordx4 v[224:225], off
	s_barrier
	s_waitcnt lgkmcnt(0)
	s_setprio 1
	s_waitcnt lgkmcnt(0)
	v_mfma_f32_16x16x32_bf16 v[62:65], v[152:155], v[168:171], 0
	v_mfma_f32_16x16x32_bf16 v[58:61], v[160:163], v[168:171], 0
	v_mfma_f32_16x16x32_bf16 v[46:49], v[152:155], v[176:179], 0
	v_mfma_f32_16x16x32_bf16 v[42:45], v[160:163], v[176:179], 0
	v_mfma_f32_16x16x32_bf16 v[30:33], v[152:155], v[184:187], 0
	v_mfma_f32_16x16x32_bf16 v[26:29], v[160:163], v[184:187], 0
	v_mfma_f32_16x16x32_bf16 v[14:17], v[152:155], v[192:195], 0
	v_mfma_f32_16x16x32_bf16 v[10:13], v[160:163], v[192:195], 0
	v_mfma_f32_16x16x32_bf16 v[62:65], v[156:159], v[172:175], v[62:65]
	v_mfma_f32_16x16x32_bf16 v[58:61], v[164:167], v[172:175], v[58:61]
	v_mfma_f32_16x16x32_bf16 v[46:49], v[156:159], v[180:183], v[46:49]
	v_mfma_f32_16x16x32_bf16 v[42:45], v[164:167], v[180:183], v[42:45]
	v_mfma_f32_16x16x32_bf16 v[30:33], v[156:159], v[188:191], v[30:33]
	v_mfma_f32_16x16x32_bf16 v[26:29], v[164:167], v[188:191], v[26:29]
	v_mfma_f32_16x16x32_bf16 v[14:17], v[156:159], v[196:199], v[14:17]
	v_mfma_f32_16x16x32_bf16 v[10:13], v[164:167], v[196:199], v[10:13]
	s_setprio 0
	s_barrier
; #define PG8_STAGE(bufoff, gbase, voff) do { _Pragma("unroll") for (int _i = 0; _i < 2; ++_i) \
;         __builtin_amdgcn_global_load_lds((const unsigned*)((const char*)(gbase) + (voff)[_i]), (LAS unsigned*)(lds + (bufoff) + ldsw + _i * 8192), 16, 0, 0); } while (0)
; #define PG8_LDA(dst, b, h) do { _Pragma("unroll") for (int m = 0; m < 4; ++m) _Pragma("unroll") for (int k = 0; k < 2; ++k) dst[m][k] = *(const LAS bf16x8*)(lds + PG8_SA(b, h) + aoff + m * 2048 + k * 1024); } while (0)
; #define PG8_LDB(dst, b, h) do { _Pragma("unroll") for (int n = 0; n < 2; ++n) _Pragma("unroll") for (int k = 0; k < 2; ++k) dst[n][k] = *(const LAS bf16x8*)(lds + PG8_SB(b, h) + boff + n * 2048 + k * 1024); } while (0)
; #define PG8_MMA(ai, bj, At, Bt) do { __builtin_amdgcn_s_setprio(1); _Pragma("unroll") for (int m = 0; m < 4; ++m) _Pragma("unroll") for (int n = 0; n < 2; ++n) _Pragma("unroll") for (int k = 0; k < 2; ++k) \
;         acc[ai][bj][m][n] = __builtin_amdgcn_mfma_f32_16x16x32_bf16(Bt[n][k], At[m][k], acc[ai][bj][m][n], 0, 0, 0); __builtin_amdgcn_s_setprio(0); } while (0)
; #define PG8_WAIT_V(n) asm volatile("s_waitcnt vmcnt(" #n ")" ::: "memory")
; #define PG8_WAIT_L(n) asm volatile("s_waitcnt lgkmcnt(" #n ")" ::: "memory")
; #define PG8_BAR __builtin_amdgcn_s_barrier()
; #define PG8_SCHED __builtin_amdgcn_sched_barrier(0)
; template <class Epi, class Sched>
; __device__ __forceinline__ void gemm_phase(LAS unsigned char* lds, const Gemm g, const Sched& S, const Epi& E) {
;     ...
;             PG8_STAGE(PG8_SB(0, 1), b2 + hstep, voffB);
;             PG8_WAIT_V(6); PG8_BAR; PG8_MMA(1, 1, At, B1); PG8_BAR;
;             PG8_LDB(B0, 1, 0); PG8_SCHED; PG8_LDA(At, 1, 0); PG8_STAGE(PG8_SA(0, 1), a2 + hstep, voffA);
;             PG8_WAIT_L(8); PG8_BAR; PG8_WAIT_L(0); PG8_MMA(0, 0, At, B0); PG8_BAR; PG8_SCHED;
;             PG8_LDB(B1, 1, 1); PG8_STAGE(PG8_SB(1, 0), b3, voffB);
	s_add_u32 s50, s20, 0x80000
	s_addc_u32 s51, s21, 0
	s_add_i32 s52, s40, s27
	v_lshl_add_u64 v[152:153], s[50:51], 0, v[132:133]
	s_mov_b32 m0, s52
	s_nop 0
	global_load_lds_dwordx4 v[152:153], off
	v_lshl_add_u64 v[152:153], s[50:51], 0, v[136:137]
	s_add_i32 m0, s52, 0x2000
	s_nop 0
	global_load_lds_dwordx4 v[152:153], off
	s_waitcnt vmcnt(6)
	s_barrier
	s_setprio 1
	v_mfma_f32_16x16x32_bf16 v[54:57], v[200:203], v[168:171], 0
	v_mfma_f32_16x16x32_bf16 v[50:53], v[212:215], v[168:171], 0
	v_mfma_f32_16x16x32_bf16 v[38:41], v[200:203], v[176:179], 0
	v_mfma_f32_16x16x32_bf16 v[34:37], v[212:215], v[176:179], 0
	v_mfma_f32_16x16x32_bf16 v[22:25], v[200:203], v[184:187], 0
	v_mfma_f32_16x16x32_bf16 v[18:21], v[212:215], v[184:187], 0
	v_mfma_f32_16x16x32_bf16 v[6:9], v[200:203], v[192:195], 0
	v_mfma_f32_16x16x32_bf16 v[2:5], v[212:215], v[192:195], 0
	v_mfma_f32_16x16x32_bf16 v[54:57], v[208:211], v[172:175], v[54:57]
	v_mfma_f32_16x16x32_bf16 v[50:53], v[216:219], v[172:175], v[50:53]
	v_mfma_f32_16x16x32_bf16 v[38:41], v[208:211], v[180:183], v[38:41]
	v_mfma_f32_16x16x32_bf16 v[34:37], v[216:219], v[180:183], v[34:37]
	v_mfma_f32_16x16x32_bf16 v[22:25], v[208:211], v[188:191], v[22:25]
	v_mfma_f32_16x16x32_bf16 v[18:21], v[216:219], v[188:191], v[18:21]
	v_mfma_f32_16x16x32_bf16 v[6:9], v[208:211], v[196:199], v[6:9]
	v_mfma_f32_16x16x32_bf16 v[2:5], v[216:219], v[196:199], v[2:5]
	s_setprio 0
	s_add_i32 s50, 0, 0x18000
	v_add_u32_e32 v164, s50, v146
	s_barrier
	ds_read_b128 v[152:155], v164
	ds_read_b128 v[156:159], v164 offset:1024
	ds_read_b128 v[160:163], v164 offset:2048
	ds_read_b128 v[164:167], v164 offset:3072
	s_add_u32 s22, s22, 0x80000
	s_addc_u32 s23, s23, 0
	s_mov_b32 m0, s35
	v_lshl_add_u64 v[200:201], s[22:23], 0, v[130:131]
	ds_read_b128 v[168:171], v150 offset:32768
	ds_read_b128 v[172:175], v150 offset:33792
	ds_read_b128 v[176:179], v150 offset:34816
	ds_read_b128 v[180:183], v150 offset:35840
	ds_read_b128 v[184:187], v150 offset:36864
	ds_read_b128 v[188:191], v150 offset:37888
	ds_read_b128 v[192:195], v150 offset:38912
	ds_read_b128 v[196:199], v150 offset:39936
	global_load_lds_dwordx4 v[200:201], off
	v_lshl_add_u64 v[200:201], s[22:23], 0, v[134:135]
	s_mov_b32 m0, s36
	s_nop 0
	global_load_lds_dwordx4 v[200:201], off
	s_waitcnt lgkmcnt(8)
	s_barrier
	s_waitcnt lgkmcnt(0)
	s_setprio 1
	s_waitcnt lgkmcnt(0)
	v_mfma_f32_16x16x32_bf16 v[126:129], v[152:155], v[168:171], v[126:129]
	v_mfma_f32_16x16x32_bf16 v[122:125], v[160:163], v[168:171], v[122:125]
	v_mfma_f32_16x16x32_bf16 v[110:113], v[152:155], v[176:179], v[110:113]
	v_mfma_f32_16x16x32_bf16 v[106:109], v[160:163], v[176:179], v[106:109]
	v_mfma_f32_16x16x32_bf16 v[94:97], v[152:155], v[184:187], v[94:97]
	v_mfma_f32_16x16x32_bf16 v[90:93], v[160:163], v[184:187], v[90:93]
	v_mfma_f32_16x16x32_bf16 v[78:81], v[152:155], v[192:195], v[78:81]
	v_mfma_f32_16x16x32_bf16 v[74:77], v[160:163], v[192:195], v[74:77]
	v_mfma_f32_16x16x32_bf16 v[126:129], v[156:159], v[172:175], v[126:129]
	v_mfma_f32_16x16x32_bf16 v[122:125], v[164:167], v[172:175], v[122:125]
	v_mfma_f32_16x16x32_bf16 v[110:113], v[156:159], v[180:183], v[110:113]
	v_mfma_f32_16x16x32_bf16 v[106:109], v[164:167], v[180:183], v[106:109]
	v_mfma_f32_16x16x32_bf16 v[94:97], v[156:159], v[188:191], v[94:97]
	v_mfma_f32_16x16x32_bf16 v[90:93], v[164:167], v[188:191], v[90:93]
	v_mfma_f32_16x16x32_bf16 v[78:81], v[156:159], v[196:199], v[78:81]
	v_mfma_f32_16x16x32_bf16 v[74:77], v[164:167], v[196:199], v[74:77]
	s_setprio 0
	s_barrier
	s_add_i32 s22, 0, 0x1c000
	s_add_i32 s23, s50, s27
	v_add_u32_e32 v207, s22, v146
	v_lshl_add_u64 v[204:205], v[204:205], 0, s[6:7]
	s_mov_b32 m0, s23
	ds_read_b128 v[200:203], v207
	ds_read_b128 v[208:211], v207 offset:1024
	ds_read_b128 v[212:215], v207 offset:2048
	ds_read_b128 v[216:219], v207 offset:3072
	global_load_lds_dwordx4 v[204:205], off
	v_lshl_add_u64 v[204:205], v[220:221], 0, s[6:7]
	s_add_i32 m0, s23, 0x2000
	s_nop 0
	global_load_lds_dwordx4 v[204:205], off
	s_barrier
; #define PG8_STAGE(bufoff, gbase, voff) do { _Pragma("unroll") for (int _i = 0; _i < 2; ++_i) \
;         __builtin_amdgcn_global_load_lds((const unsigned*)((const char*)(gbase) + (voff)[_i]), (LAS unsigned*)(lds + (bufoff) + ldsw + _i * 8192), 16, 0, 0); } while (0)
; #define PG8_LDA(dst, b, h) do { _Pragma("unroll") for (int m = 0; m < 4; ++m) _Pragma("unroll") for (int k = 0; k < 2; ++k) dst[m][k] = *(const LAS bf16x8*)(lds + PG8_SA(b, h) + aoff + m * 2048 + k * 1024); } while (0)
; #define PG8_MMA(ai, bj, At, Bt) do { __builtin_amdgcn_s_setprio(1); _Pragma("unroll") for (int m = 0; m < 4; ++m) _Pragma("unroll") for (int n = 0; n < 2; ++n) _Pragma("unroll") for (int k = 0; k < 2; ++k) \
;         acc[ai][bj][m][n] = __builtin_amdgcn_mfma_f32_16x16x32_bf16(Bt[n][k], At[m][k], acc[ai][bj][m][n], 0, 0, 0); __builtin_amdgcn_s_setprio(0); } while (0)
; #define PG8_WAIT_V(n) asm volatile("s_waitcnt vmcnt(" #n ")" ::: "memory")
; #define PG8_WAIT_L(n) asm volatile("s_waitcnt lgkmcnt(" #n ")" ::: "memory")
; #define PG8_BAR __builtin_amdgcn_s_barrier()
; #define PG8_SCHED __builtin_amdgcn_sched_barrier(0)
; template <class Epi, class Sched>
; __device__ __forceinline__ void gemm_phase(LAS unsigned char* lds, const Gemm g, const Sched& S, const Epi& E) {
;     ...
;             PG8_BAR; PG8_WAIT_L(0); PG8_MMA(0, 1, At, B1); PG8_BAR;
;             PG8_LDA(At, 1, 1); PG8_STAGE(PG8_SA(1, 0), a3, voffA);
;             PG8_BAR; PG8_WAIT_L(0); PG8_MMA(1, 0, At, B0); PG8_BAR; PG8_SCHED;
;             PG8_STAGE(PG8_SB(1, 1), b3 + hstep, voffB);
;             PG8_WAIT_V(6); PG8_BAR; PG8_MMA(1, 1, At, B1); PG8_BAR;
;         }
	s_waitcnt lgkmcnt(0)
	s_setprio 1
	s_waitcnt lgkmcnt(0)
	v_mfma_f32_16x16x32_bf16 v[118:121], v[200:203], v[168:171], v[118:121]
	v_mfma_f32_16x16x32_bf16 v[114:117], v[212:215], v[168:171], v[114:117]
	v_mfma_f32_16x16x32_bf16 v[102:105], v[200:203], v[176:179], v[102:105]
	v_mfma_f32_16x16x32_bf16 v[98:101], v[212:215], v[176:179], v[98:101]
	v_mfma_f32_16x16x32_bf16 v[86:89], v[200:203], v[184:187], v[86:89]
	v_mfma_f32_16x16x32_bf16 v[82:85], v[212:215], v[184:187], v[82:85]
	v_mfma_f32_16x16x32_bf16 v[70:73], v[200:203], v[192:195], v[70:73]
	v_mfma_f32_16x16x32_bf16 v[66:69], v[212:215], v[192:195], v[66:69]
	v_mfma_f32_16x16x32_bf16 v[118:121], v[208:211], v[172:175], v[118:121]
	v_mfma_f32_16x16x32_bf16 v[114:117], v[216:219], v[172:175], v[114:117]
	v_mfma_f32_16x16x32_bf16 v[102:105], v[208:211], v[180:183], v[102:105]
	v_mfma_f32_16x16x32_bf16 v[98:101], v[216:219], v[180:183], v[98:101]
	v_mfma_f32_16x16x32_bf16 v[86:89], v[208:211], v[188:191], v[86:89]
	v_mfma_f32_16x16x32_bf16 v[82:85], v[216:219], v[188:191], v[82:85]
	v_mfma_f32_16x16x32_bf16 v[70:73], v[208:211], v[196:199], v[70:73]
	v_mfma_f32_16x16x32_bf16 v[66:69], v[216:219], v[196:199], v[66:69]
	s_setprio 0
	s_mov_b32 m0, s37
	v_lshl_add_u64 v[204:205], v[222:223], 0, s[6:7]
	s_barrier
	ds_read_b128 v[168:171], v150 offset:49152
	ds_read_b128 v[172:175], v150 offset:50176
	ds_read_b128 v[176:179], v150 offset:51200
	ds_read_b128 v[180:183], v150 offset:52224
	ds_read_b128 v[184:187], v150 offset:53248
	ds_read_b128 v[188:191], v150 offset:54272
	ds_read_b128 v[192:195], v150 offset:55296
	ds_read_b128 v[196:199], v150 offset:56320
	global_load_lds_dwordx4 v[204:205], off
	v_lshl_add_u64 v[204:205], v[224:225], 0, s[6:7]
	s_mov_b32 m0, s38
	s_nop 0
	global_load_lds_dwordx4 v[204:205], off
	s_barrier
	s_waitcnt lgkmcnt(0)
	s_setprio 1
	s_waitcnt lgkmcnt(0)
	v_mfma_f32_16x16x32_bf16 v[62:65], v[152:155], v[168:171], v[62:65]
	v_mfma_f32_16x16x32_bf16 v[58:61], v[160:163], v[168:171], v[58:61]
	v_mfma_f32_16x16x32_bf16 v[46:49], v[152:155], v[176:179], v[46:49]
	v_mfma_f32_16x16x32_bf16 v[42:45], v[160:163], v[176:179], v[42:45]
	v_mfma_f32_16x16x32_bf16 v[30:33], v[152:155], v[184:187], v[30:33]
	v_mfma_f32_16x16x32_bf16 v[26:29], v[160:163], v[184:187], v[26:29]
	v_mfma_f32_16x16x32_bf16 v[14:17], v[152:155], v[192:195], v[14:17]
	v_mfma_f32_16x16x32_bf16 v[10:13], v[160:163], v[192:195], v[10:13]
	v_mfma_f32_16x16x32_bf16 v[62:65], v[156:159], v[172:175], v[62:65]
	v_mfma_f32_16x16x32_bf16 v[58:61], v[164:167], v[172:175], v[58:61]
	v_mfma_f32_16x16x32_bf16 v[46:49], v[156:159], v[180:183], v[46:49]
	v_mfma_f32_16x16x32_bf16 v[42:45], v[164:167], v[180:183], v[42:45]
	v_mfma_f32_16x16x32_bf16 v[30:33], v[156:159], v[188:191], v[30:33]
	v_mfma_f32_16x16x32_bf16 v[26:29], v[164:167], v[188:191], v[26:29]
	v_mfma_f32_16x16x32_bf16 v[14:17], v[156:159], v[196:199], v[14:17]
	v_mfma_f32_16x16x32_bf16 v[10:13], v[164:167], v[196:199], v[10:13]
	s_setprio 0
	s_barrier
	s_add_u32 s20, s20, 0x80080
	s_addc_u32 s21, s21, 0
	s_add_i32 s22, s22, s27
	v_lshl_add_u64 v[152:153], s[20:21], 0, v[132:133]
	s_mov_b32 m0, s22
	s_nop 0
	global_load_lds_dwordx4 v[152:153], off
	v_lshl_add_u64 v[152:153], s[20:21], 0, v[136:137]
	s_add_i32 m0, s22, 0x2000
	s_nop 0
	global_load_lds_dwordx4 v[152:153], off
	s_waitcnt vmcnt(6)
	s_barrier
	s_setprio 1
	v_mfma_f32_16x16x32_bf16 v[54:57], v[200:203], v[168:171], v[54:57]
	v_mfma_f32_16x16x32_bf16 v[50:53], v[212:215], v[168:171], v[50:53]
	v_mfma_f32_16x16x32_bf16 v[38:41], v[200:203], v[176:179], v[38:41]
	v_mfma_f32_16x16x32_bf16 v[34:37], v[212:215], v[176:179], v[34:37]
	v_mfma_f32_16x16x32_bf16 v[22:25], v[200:203], v[184:187], v[22:25]
	v_mfma_f32_16x16x32_bf16 v[18:21], v[212:215], v[184:187], v[18:21]
	v_mfma_f32_16x16x32_bf16 v[6:9], v[200:203], v[192:195], v[6:9]
	v_mfma_f32_16x16x32_bf16 v[2:5], v[212:215], v[192:195], v[2:5]
	v_mfma_f32_16x16x32_bf16 v[54:57], v[208:211], v[172:175], v[54:57]
	v_mfma_f32_16x16x32_bf16 v[50:53], v[216:219], v[172:175], v[50:53]
	v_mfma_f32_16x16x32_bf16 v[38:41], v[208:211], v[180:183], v[38:41]
	v_mfma_f32_16x16x32_bf16 v[34:37], v[216:219], v[180:183], v[34:37]
	v_mfma_f32_16x16x32_bf16 v[22:25], v[208:211], v[188:191], v[22:25]
	v_mfma_f32_16x16x32_bf16 v[18:21], v[216:219], v[188:191], v[18:21]
	v_mfma_f32_16x16x32_bf16 v[6:9], v[208:211], v[196:199], v[6:9]
	v_mfma_f32_16x16x32_bf16 v[2:5], v[216:219], v[196:199], v[2:5]
	s_setprio 0
	s_add_i32 s49, s49, 2
	s_add_u32 s18, s18, 0x100
	s_addc_u32 s19, s19, 0
	s_add_u32 s47, s47, 0x100
	s_addc_u32 s48, s48, 0
	s_cmp_gt_u32 s49, 29
	s_barrier

; #define PG8_STAGE(bufoff, gbase, voff) do { _Pragma("unroll") for (int _i = 0; _i < 2; ++_i) \
;         __builtin_amdgcn_global_load_lds((const unsigned*)((const char*)(gbase) + (voff)[_i]), (LAS unsigned*)(lds + (bufoff) + ldsw + _i * 8192), 16, 0, 0); } while (0)
; #define PG8_LDA(dst, b, h) do { _Pragma("unroll") for (int m = 0; m < 4; ++m) _Pragma("unroll") for (int k = 0; k < 2; ++k) dst[m][k] = *(const LAS bf16x8*)(lds + PG8_SA(b, h) + aoff + m * 2048 + k * 1024); } while (0)
; #define PG8_LDB(dst, b, h) do { _Pragma("unroll") for (int n = 0; n < 2; ++n) _Pragma("unroll") for (int k = 0; k < 2; ++k) dst[n][k] = *(const LAS bf16x8*)(lds + PG8_SB(b, h) + boff + n * 2048 + k * 1024); } while (0)
; #define PG8_MMA(ai, bj, At, Bt) do { __builtin_amdgcn_s_setprio(1); _Pragma("unroll") for (int m = 0; m < 4; ++m) _Pragma("unroll") for (int n = 0; n < 2; ++n) _Pragma("unroll") for (int k = 0; k < 2; ++k) \
;         acc[ai][bj][m][n] = __builtin_amdgcn_mfma_f32_16x16x32_bf16(Bt[n][k], At[m][k], acc[ai][bj][m][n], 0, 0, 0); __builtin_amdgcn_s_setprio(0); } while (0)
; #define PG8_BAR __builtin_amdgcn_s_barrier()
; template <class Epi, class Sched>
; __device__ __forceinline__ void gemm_phase(LAS unsigned char* lds, const Gemm g, const Sched& S, const Epi& E) {
;     ...
;         const bool has_next = S.next(ui + 1, nxt);
;         const char* nA = has_next ? (const char*)g.A + (size_t)nxt.pm * tstep : cA; const char* nB = has_next ? (const char*)g.Bt + (size_t)nxt.pn * tstep : cB;
;         for (int t = 0; t < nt; t += 2) {
;             const bool last = (t == nt - 2);
;             const char* a1 = cA + (size_t)(t + 1) * kstep;
;             const char* a2 = last ? nA : cA + (size_t)(t + 2) * kstep; const char* b2 = last ? nB : cB + (size_t)(t + 2) * kstep;
;             const char* a3 = a2 + kstep; const char* b3 = b2 + kstep;
;             if (last && has_next) S.a_ready(nxt);
;             PG8_LDB(B0, 0, 0); PG8_SCHED; PG8_LDA(At, 0, 0); PG8_STAGE(PG8_SA(1, 1), a1 + hstep, voffA);
;             PG8_WAIT_L(8); PG8_BAR; PG8_WAIT_L(0); PG8_MMA(0, 0, At, B0); PG8_BAR; PG8_SCHED;
;             PG8_LDB(B1, 0, 1); PG8_STAGE(PG8_SB(0, 0), b2, voffB);
;             PG8_BAR; PG8_WAIT_L(0); PG8_MMA(0, 1, At, B1); PG8_BAR;
;             PG8_LDA(At, 0, 1); PG8_STAGE(PG8_SA(0, 0), a2, voffA);
;             PG8_BAR; PG8_WAIT_L(0); PG8_MMA(1, 0, At, B0); PG8_BAR; PG8_SCHED;
.LBB0_1179:
	s_add_u32 s12, s12, 0x160080
	s_addc_u32 s13, s13, 0
	s_add_u32 s41, s14, 0x100
	s_addc_u32 s42, s15, 0
	s_mov_b32 s43, -2
	ds_read_b128 v[130:133], v156
	ds_read_b128 v[150:153], v156 offset:1024
	ds_read_b128 v[160:163], v156 offset:2048
	ds_read_b128 v[164:167], v156 offset:3072
	s_add_u32 s14, s12, 0xffea0080
	s_addc_u32 s15, s13, -1
	s_cmpk_eq_i32 s43, 0x54
	s_cselect_b32 s17, s7, s15
	s_cselect_b32 s16, s6, s14
	s_cselect_b32 s15, s1, s42
	s_cselect_b32 s14, s0, s41
	v_lshl_add_u64 v[200:201], s[12:13], 0, v[142:143]
	s_add_i32 m0, s25, 0xc000
	ds_read_b128 v[168:171], v157
	ds_read_b128 v[172:175], v157 offset:1024
	ds_read_b128 v[176:179], v157 offset:2048
	ds_read_b128 v[180:183], v157 offset:3072
	ds_read_b128 v[184:187], v157 offset:4096
	ds_read_b128 v[188:191], v157 offset:5120
	ds_read_b128 v[192:195], v157 offset:6144
	ds_read_b128 v[196:199], v157 offset:7168
	global_load_lds_dwordx4 v[200:201], off
	v_lshl_add_u64 v[200:201], s[12:13], 0, v[144:145]
	s_add_i32 m0, s25, 0xe000
	s_nop 0
	global_load_lds_dwordx4 v[200:201], off
	s_waitcnt lgkmcnt(8)
	s_barrier
	s_waitcnt lgkmcnt(0)
	s_setprio 1
	s_waitcnt lgkmcnt(0)
	v_mfma_f32_16x16x32_bf16 v[126:129], v[130:133], v[168:171], 0
	v_mfma_f32_16x16x32_bf16 v[122:125], v[160:163], v[168:171], 0
	v_mfma_f32_16x16x32_bf16 v[114:117], v[130:133], v[176:179], 0
	v_mfma_f32_16x16x32_bf16 v[106:109], v[160:163], v[176:179], 0
	v_mfma_f32_16x16x32_bf16 v[98:101], v[130:133], v[184:187], 0
	v_mfma_f32_16x16x32_bf16 v[90:93], v[160:163], v[184:187], 0
	v_mfma_f32_16x16x32_bf16 v[82:85], v[130:133], v[192:195], 0
	v_mfma_f32_16x16x32_bf16 v[74:77], v[160:163], v[192:195], 0
	v_mfma_f32_16x16x32_bf16 v[126:129], v[150:153], v[172:175], v[126:129]
	v_mfma_f32_16x16x32_bf16 v[122:125], v[164:167], v[172:175], v[122:125]
	v_mfma_f32_16x16x32_bf16 v[114:117], v[150:153], v[180:183], v[114:117]
	v_mfma_f32_16x16x32_bf16 v[106:109], v[164:167], v[180:183], v[106:109]
	v_mfma_f32_16x16x32_bf16 v[98:101], v[150:153], v[188:191], v[98:101]
	v_mfma_f32_16x16x32_bf16 v[90:93], v[164:167], v[188:191], v[90:93]
	v_mfma_f32_16x16x32_bf16 v[82:85], v[150:153], v[196:199], v[82:85]
	v_mfma_f32_16x16x32_bf16 v[74:77], v[164:167], v[196:199], v[74:77]
	s_setprio 0
	s_barrier
	s_add_i32 s44, s35, s23
	v_lshl_add_u64 v[204:205], s[14:15], 0, v[136:137]
	s_mov_b32 m0, s44
	ds_read_b128 v[200:203], v158
	ds_read_b128 v[208:211], v158 offset:1024
	ds_read_b128 v[212:215], v158 offset:2048
	ds_read_b128 v[216:219], v158 offset:3072
	global_load_lds_dwordx4 v[204:205], off
	v_lshl_add_u64 v[220:221], s[14:15], 0, v[140:141]
	s_add_i32 m0, s44, 0x2000
	s_nop 0
	global_load_lds_dwordx4 v[220:221], off
	s_barrier
	s_waitcnt lgkmcnt(0)
	s_setprio 1
	s_waitcnt lgkmcnt(0)
	v_mfma_f32_16x16x32_bf16 v[118:121], v[200:203], v[168:171], 0
	v_mfma_f32_16x16x32_bf16 v[110:113], v[212:215], v[168:171], 0
	v_mfma_f32_16x16x32_bf16 v[102:105], v[200:203], v[176:179], 0
	v_mfma_f32_16x16x32_bf16 v[94:97], v[212:215], v[176:179], 0
	v_mfma_f32_16x16x32_bf16 v[86:89], v[200:203], v[184:187], 0
	v_mfma_f32_16x16x32_bf16 v[78:81], v[212:215], v[184:187], 0
	v_mfma_f32_16x16x32_bf16 v[70:73], v[200:203], v[192:195], 0
	v_mfma_f32_16x16x32_bf16 v[66:69], v[212:215], v[192:195], 0
	v_mfma_f32_16x16x32_bf16 v[118:121], v[208:211], v[172:175], v[118:121]
	v_mfma_f32_16x16x32_bf16 v[110:113], v[216:219], v[172:175], v[110:113]
	v_mfma_f32_16x16x32_bf16 v[102:105], v[208:211], v[180:183], v[102:105]
	v_mfma_f32_16x16x32_bf16 v[94:97], v[216:219], v[180:183], v[94:97]
	v_mfma_f32_16x16x32_bf16 v[86:89], v[208:211], v[188:191], v[86:89]
	v_mfma_f32_16x16x32_bf16 v[78:81], v[216:219], v[188:191], v[78:81]
	v_mfma_f32_16x16x32_bf16 v[70:73], v[208:211], v[196:199], v[70:73]
	v_mfma_f32_16x16x32_bf16 v[66:69], v[216:219], v[196:199], v[66:69]
	s_setprio 0
	s_mov_b32 m0, s25
	v_lshl_add_u64 v[222:223], s[16:17], 0, v[134:135]
	s_barrier
	ds_read_b128 v[168:171], v157 offset:16384
	ds_read_b128 v[172:175], v157 offset:17408
	ds_read_b128 v[176:179], v157 offset:18432
	ds_read_b128 v[180:183], v157 offset:19456
	ds_read_b128 v[184:187], v157 offset:20480
	ds_read_b128 v[188:191], v157 offset:21504
	ds_read_b128 v[192:195], v157 offset:22528
	ds_read_b128 v[196:199], v157 offset:23552
	global_load_lds_dwordx4 v[222:223], off
	v_lshl_add_u64 v[224:225], s[16:17], 0, v[138:139]
	s_mov_b32 m0, s26
	s_nop 0
	global_load_lds_dwordx4 v[224:225], off
	s_barrier
	s_waitcnt lgkmcnt(0)
	s_setprio 1
	s_waitcnt lgkmcnt(0)
	v_mfma_f32_16x16x32_bf16 v[62:65], v[130:133], v[168:171], 0
	v_mfma_f32_16x16x32_bf16 v[58:61], v[160:163], v[168:171], 0
	v_mfma_f32_16x16x32_bf16 v[50:53], v[130:133], v[176:179], 0
	v_mfma_f32_16x16x32_bf16 v[42:45], v[160:163], v[176:179], 0
	v_mfma_f32_16x16x32_bf16 v[34:37], v[130:133], v[184:187], 0
	v_mfma_f32_16x16x32_bf16 v[26:29], v[160:163], v[184:187], 0
	v_mfma_f32_16x16x32_bf16 v[18:21], v[130:133], v[192:195], 0
	v_mfma_f32_16x16x32_bf16 v[10:13], v[160:163], v[192:195], 0
	v_mfma_f32_16x16x32_bf16 v[62:65], v[150:153], v[172:175], v[62:65]
	v_mfma_f32_16x16x32_bf16 v[58:61], v[164:167], v[172:175], v[58:61]
	v_mfma_f32_16x16x32_bf16 v[50:53], v[150:153], v[180:183], v[50:53]
	v_mfma_f32_16x16x32_bf16 v[42:45], v[164:167], v[180:183], v[42:45]
	v_mfma_f32_16x16x32_bf16 v[34:37], v[150:153], v[188:191], v[34:37]
	v_mfma_f32_16x16x32_bf16 v[26:29], v[164:167], v[188:191], v[26:29]
	v_mfma_f32_16x16x32_bf16 v[18:21], v[150:153], v[196:199], v[18:21]
	v_mfma_f32_16x16x32_bf16 v[10:13], v[164:167], v[196:199], v[10:13]
	s_setprio 0
	s_barrier
; #define PG8_STAGE(bufoff, gbase, voff) do { _Pragma("unroll") for (int _i = 0; _i < 2; ++_i) \
;         __builtin_amdgcn_global_load_lds((const unsigned*)((const char*)(gbase) + (voff)[_i]), (LAS unsigned*)(lds + (bufoff) + ldsw + _i * 8192), 16, 0, 0); } while (0)
; #define PG8_LDA(dst, b, h) do { _Pragma("unroll") for (int m = 0; m < 4; ++m) _Pragma("unroll") for (int k = 0; k < 2; ++k) dst[m][k] = *(const LAS bf16x8*)(lds + PG8_SA(b, h) + aoff + m * 2048 + k * 1024); } while (0)
; #define PG8_LDB(dst, b, h) do { _Pragma("unroll") for (int n = 0; n < 2; ++n) _Pragma("unroll") for (int k = 0; k < 2; ++k) dst[n][k] = *(const LAS bf16x8*)(lds + PG8_SB(b, h) + boff + n * 2048 + k * 1024); } while (0)
; #define PG8_MMA(ai, bj, At, Bt) do { __builtin_amdgcn_s_setprio(1); _Pragma("unroll") for (int m = 0; m < 4; ++m) _Pragma("unroll") for (int n = 0; n < 2; ++n) _Pragma("unroll") for (int k = 0; k < 2; ++k) \
;         acc[ai][bj][m][n] = __builtin_amdgcn_mfma_f32_16x16x32_bf16(Bt[n][k], At[m][k], acc[ai][bj][m][n], 0, 0, 0); __builtin_amdgcn_s_setprio(0); } while (0)
; #define PG8_WAIT_V(n) asm volatile("s_waitcnt vmcnt(" #n ")" ::: "memory")
; #define PG8_WAIT_L(n) asm volatile("s_waitcnt lgkmcnt(" #n ")" ::: "memory")
; #define PG8_BAR __builtin_amdgcn_s_barrier()
; #define PG8_SCHED __builtin_amdgcn_sched_barrier(0)
; template <class Epi, class Sched>
; __device__ __forceinline__ void gemm_phase(LAS unsigned char* lds, const Gemm g, const Sched& S, const Epi& E) {
;     ...
;             PG8_STAGE(PG8_SB(0, 1), b2 + hstep, voffB);
;             PG8_WAIT_V(6); PG8_BAR; PG8_MMA(1, 1, At, B1); PG8_BAR;
;             PG8_LDB(B0, 1, 0); PG8_SCHED; PG8_LDA(At, 1, 0); PG8_STAGE(PG8_SA(0, 1), a2 + hstep, voffA);
;             PG8_WAIT_L(8); PG8_BAR; PG8_WAIT_L(0); PG8_MMA(0, 0, At, B0); PG8_BAR; PG8_SCHED;
;             PG8_LDB(B1, 1, 1); PG8_STAGE(PG8_SB(1, 0), b3, voffB);
	s_add_u32 s44, s14, 0x160000
	s_addc_u32 s45, s15, 0
	s_add_i32 s46, s36, s23
	v_lshl_add_u64 v[130:131], s[44:45], 0, v[136:137]
	s_mov_b32 m0, s46
	s_nop 0
	global_load_lds_dwordx4 v[130:131], off
	v_lshl_add_u64 v[130:131], s[44:45], 0, v[140:141]
	s_add_i32 m0, s46, 0x2000
	s_nop 0
	global_load_lds_dwordx4 v[130:131], off
	s_waitcnt vmcnt(6)
	s_barrier
	s_setprio 1
	v_mfma_f32_16x16x32_bf16 v[54:57], v[200:203], v[168:171], 0
	v_mfma_f32_16x16x32_bf16 v[46:49], v[212:215], v[168:171], 0
	v_mfma_f32_16x16x32_bf16 v[38:41], v[200:203], v[176:179], 0
	v_mfma_f32_16x16x32_bf16 v[30:33], v[212:215], v[176:179], 0
	v_mfma_f32_16x16x32_bf16 v[22:25], v[200:203], v[184:187], 0
	v_mfma_f32_16x16x32_bf16 v[14:17], v[212:215], v[184:187], 0
	v_mfma_f32_16x16x32_bf16 v[6:9], v[200:203], v[192:195], 0
	v_mfma_f32_16x16x32_bf16 v[2:5], v[212:215], v[192:195], 0
	v_mfma_f32_16x16x32_bf16 v[54:57], v[208:211], v[172:175], v[54:57]
	v_mfma_f32_16x16x32_bf16 v[46:49], v[216:219], v[172:175], v[46:49]
	v_mfma_f32_16x16x32_bf16 v[38:41], v[208:211], v[180:183], v[38:41]
	v_mfma_f32_16x16x32_bf16 v[30:33], v[216:219], v[180:183], v[30:33]
	v_mfma_f32_16x16x32_bf16 v[22:25], v[208:211], v[188:191], v[22:25]
	v_mfma_f32_16x16x32_bf16 v[14:17], v[216:219], v[188:191], v[14:17]
	v_mfma_f32_16x16x32_bf16 v[6:9], v[208:211], v[196:199], v[6:9]
	v_mfma_f32_16x16x32_bf16 v[2:5], v[216:219], v[196:199], v[2:5]
	s_setprio 0
	s_add_i32 s44, 0, 0x18000
	v_add_u32_e32 v159, s44, v154
	s_barrier
	ds_read_b128 v[130:133], v159
	ds_read_b128 v[150:153], v159 offset:1024
	ds_read_b128 v[160:163], v159 offset:2048
	ds_read_b128 v[164:167], v159 offset:3072
	s_add_u32 s16, s16, 0x160000
	s_addc_u32 s17, s17, 0
	s_mov_b32 m0, s27
	v_lshl_add_u64 v[200:201], s[16:17], 0, v[134:135]
	ds_read_b128 v[168:171], v157 offset:32768
	ds_read_b128 v[172:175], v157 offset:33792
	ds_read_b128 v[176:179], v157 offset:34816
	ds_read_b128 v[180:183], v157 offset:35840
	ds_read_b128 v[184:187], v157 offset:36864
	ds_read_b128 v[188:191], v157 offset:37888
	ds_read_b128 v[192:195], v157 offset:38912
	ds_read_b128 v[196:199], v157 offset:39936
	global_load_lds_dwordx4 v[200:201], off
	v_lshl_add_u64 v[200:201], s[16:17], 0, v[138:139]
	s_mov_b32 m0, s28
	s_nop 0
	global_load_lds_dwordx4 v[200:201], off
	s_waitcnt lgkmcnt(8)
	s_barrier
	s_waitcnt lgkmcnt(0)
	s_setprio 1
	s_waitcnt lgkmcnt(0)
	v_mfma_f32_16x16x32_bf16 v[126:129], v[130:133], v[168:171], v[126:129]
	v_mfma_f32_16x16x32_bf16 v[122:125], v[160:163], v[168:171], v[122:125]
	v_mfma_f32_16x16x32_bf16 v[114:117], v[130:133], v[176:179], v[114:117]
	v_mfma_f32_16x16x32_bf16 v[106:109], v[160:163], v[176:179], v[106:109]
	v_mfma_f32_16x16x32_bf16 v[98:101], v[130:133], v[184:187], v[98:101]
	v_mfma_f32_16x16x32_bf16 v[90:93], v[160:163], v[184:187], v[90:93]
	v_mfma_f32_16x16x32_bf16 v[82:85], v[130:133], v[192:195], v[82:85]
	v_mfma_f32_16x16x32_bf16 v[74:77], v[160:163], v[192:195], v[74:77]
	v_mfma_f32_16x16x32_bf16 v[126:129], v[150:153], v[172:175], v[126:129]
	v_mfma_f32_16x16x32_bf16 v[122:125], v[164:167], v[172:175], v[122:125]
	v_mfma_f32_16x16x32_bf16 v[114:117], v[150:153], v[180:183], v[114:117]
	v_mfma_f32_16x16x32_bf16 v[106:109], v[164:167], v[180:183], v[106:109]
	v_mfma_f32_16x16x32_bf16 v[98:101], v[150:153], v[188:191], v[98:101]
	v_mfma_f32_16x16x32_bf16 v[90:93], v[164:167], v[188:191], v[90:93]
	v_mfma_f32_16x16x32_bf16 v[82:85], v[150:153], v[196:199], v[82:85]
	v_mfma_f32_16x16x32_bf16 v[74:77], v[164:167], v[196:199], v[74:77]
	s_setprio 0
	s_barrier
	s_add_i32 s16, 0, 0x1c000
	s_add_i32 s17, s44, s23
	v_add_u32_e32 v159, s16, v154
	v_lshl_add_u64 v[204:205], v[204:205], 0, s[10:11]
	s_mov_b32 m0, s17
	ds_read_b128 v[200:203], v159
	ds_read_b128 v[208:211], v159 offset:1024
	ds_read_b128 v[212:215], v159 offset:2048
	ds_read_b128 v[216:219], v159 offset:3072
	global_load_lds_dwordx4 v[204:205], off
	v_lshl_add_u64 v[204:205], v[220:221], 0, s[10:11]
	s_add_i32 m0, s17, 0x2000
	s_nop 0
	global_load_lds_dwordx4 v[204:205], off
	s_barrier
; #define PG8_STAGE(bufoff, gbase, voff) do { _Pragma("unroll") for (int _i = 0; _i < 2; ++_i) \
;         __builtin_amdgcn_global_load_lds((const unsigned*)((const char*)(gbase) + (voff)[_i]), (LAS unsigned*)(lds + (bufoff) + ldsw + _i * 8192), 16, 0, 0); } while (0)
; #define PG8_LDA(dst, b, h) do { _Pragma("unroll") for (int m = 0; m < 4; ++m) _Pragma("unroll") for (int k = 0; k < 2; ++k) dst[m][k] = *(const LAS bf16x8*)(lds + PG8_SA(b, h) + aoff + m * 2048 + k * 1024); } while (0)
; #define PG8_MMA(ai, bj, At, Bt) do { __builtin_amdgcn_s_setprio(1); _Pragma("unroll") for (int m = 0; m < 4; ++m) _Pragma("unroll") for (int n = 0; n < 2; ++n) _Pragma("unroll") for (int k = 0; k < 2; ++k) \
;         acc[ai][bj][m][n] = __builtin_amdgcn_mfma_f32_16x16x32_bf16(Bt[n][k], At[m][k], acc[ai][bj][m][n], 0, 0, 0); __builtin_amdgcn_s_setprio(0); } while (0)
; #define PG8_WAIT_V(n) asm volatile("s_waitcnt vmcnt(" #n ")" ::: "memory")
; #define PG8_WAIT_L(n) asm volatile("s_waitcnt lgkmcnt(" #n ")" ::: "memory")
; #define PG8_BAR __builtin_amdgcn_s_barrier()
; #define PG8_SCHED __builtin_amdgcn_sched_barrier(0)
; template <class Epi, class Sched>
; __device__ __forceinline__ void gemm_phase(LAS unsigned char* lds, const Gemm g, const Sched& S, const Epi& E) {
;     ...
;             PG8_BAR; PG8_WAIT_L(0); PG8_MMA(0, 1, At, B1); PG8_BAR;
;             PG8_LDA(At, 1, 1); PG8_STAGE(PG8_SA(1, 0), a3, voffA);
;             PG8_BAR; PG8_WAIT_L(0); PG8_MMA(1, 0, At, B0); PG8_BAR; PG8_SCHED;
;             PG8_STAGE(PG8_SB(1, 1), b3 + hstep, voffB);
;             PG8_WAIT_V(6); PG8_BAR; PG8_MMA(1, 1, At, B1); PG8_BAR;
	s_waitcnt lgkmcnt(0)
	s_setprio 1
	s_waitcnt lgkmcnt(0)
	v_mfma_f32_16x16x32_bf16 v[118:121], v[200:203], v[168:171], v[118:121]
	v_mfma_f32_16x16x32_bf16 v[110:113], v[212:215], v[168:171], v[110:113]
	v_mfma_f32_16x16x32_bf16 v[102:105], v[200:203], v[176:179], v[102:105]
	v_mfma_f32_16x16x32_bf16 v[94:97], v[212:215], v[176:179], v[94:97]
	v_mfma_f32_16x16x32_bf16 v[86:89], v[200:203], v[184:187], v[86:89]
	v_mfma_f32_16x16x32_bf16 v[78:81], v[212:215], v[184:187], v[78:81]
	v_mfma_f32_16x16x32_bf16 v[70:73], v[200:203], v[192:195], v[70:73]
	v_mfma_f32_16x16x32_bf16 v[66:69], v[212:215], v[192:195], v[66:69]
	v_mfma_f32_16x16x32_bf16 v[118:121], v[208:211], v[172:175], v[118:121]
	v_mfma_f32_16x16x32_bf16 v[110:113], v[216:219], v[172:175], v[110:113]
	v_mfma_f32_16x16x32_bf16 v[102:105], v[208:211], v[180:183], v[102:105]
	v_mfma_f32_16x16x32_bf16 v[94:97], v[216:219], v[180:183], v[94:97]
	v_mfma_f32_16x16x32_bf16 v[86:89], v[208:211], v[188:191], v[86:89]
	v_mfma_f32_16x16x32_bf16 v[78:81], v[216:219], v[188:191], v[78:81]
	v_mfma_f32_16x16x32_bf16 v[70:73], v[208:211], v[196:199], v[70:73]
	v_mfma_f32_16x16x32_bf16 v[66:69], v[216:219], v[196:199], v[66:69]
	s_setprio 0
	s_mov_b32 m0, s31
	v_lshl_add_u64 v[204:205], v[222:223], 0, s[10:11]
	s_barrier
	ds_read_b128 v[168:171], v157 offset:49152
	ds_read_b128 v[172:175], v157 offset:50176
	ds_read_b128 v[176:179], v157 offset:51200
	ds_read_b128 v[180:183], v157 offset:52224
	ds_read_b128 v[184:187], v157 offset:53248
	ds_read_b128 v[188:191], v157 offset:54272
	ds_read_b128 v[192:195], v157 offset:55296
	ds_read_b128 v[196:199], v157 offset:56320
	global_load_lds_dwordx4 v[204:205], off
	v_lshl_add_u64 v[204:205], v[224:225], 0, s[10:11]
	s_mov_b32 m0, s33
	s_nop 0
	global_load_lds_dwordx4 v[204:205], off
	s_barrier
	s_waitcnt lgkmcnt(0)
	s_setprio 1
	s_waitcnt lgkmcnt(0)
	v_mfma_f32_16x16x32_bf16 v[62:65], v[130:133], v[168:171], v[62:65]
	v_mfma_f32_16x16x32_bf16 v[58:61], v[160:163], v[168:171], v[58:61]
	v_mfma_f32_16x16x32_bf16 v[50:53], v[130:133], v[176:179], v[50:53]
	v_mfma_f32_16x16x32_bf16 v[42:45], v[160:163], v[176:179], v[42:45]
	v_mfma_f32_16x16x32_bf16 v[34:37], v[130:133], v[184:187], v[34:37]
	v_mfma_f32_16x16x32_bf16 v[26:29], v[160:163], v[184:187], v[26:29]
	v_mfma_f32_16x16x32_bf16 v[18:21], v[130:133], v[192:195], v[18:21]
	v_mfma_f32_16x16x32_bf16 v[10:13], v[160:163], v[192:195], v[10:13]
	v_mfma_f32_16x16x32_bf16 v[62:65], v[150:153], v[172:175], v[62:65]
	v_mfma_f32_16x16x32_bf16 v[58:61], v[164:167], v[172:175], v[58:61]
	v_mfma_f32_16x16x32_bf16 v[50:53], v[150:153], v[180:183], v[50:53]
	v_mfma_f32_16x16x32_bf16 v[42:45], v[164:167], v[180:183], v[42:45]
	v_mfma_f32_16x16x32_bf16 v[34:37], v[150:153], v[188:191], v[34:37]
	v_mfma_f32_16x16x32_bf16 v[26:29], v[164:167], v[188:191], v[26:29]
	v_mfma_f32_16x16x32_bf16 v[18:21], v[150:153], v[196:199], v[18:21]
	v_mfma_f32_16x16x32_bf16 v[10:13], v[164:167], v[196:199], v[10:13]
	s_setprio 0
	s_barrier
	s_add_u32 s14, s14, 0x160080
	s_addc_u32 s15, s15, 0
	s_add_i32 s16, s16, s23
	v_lshl_add_u64 v[130:131], s[14:15], 0, v[136:137]
	s_mov_b32 m0, s16
	s_nop 0
	global_load_lds_dwordx4 v[130:131], off
	v_lshl_add_u64 v[130:131], s[14:15], 0, v[140:141]
	s_add_i32 m0, s16, 0x2000
	s_nop 0
	global_load_lds_dwordx4 v[130:131], off
	s_waitcnt vmcnt(6)
	s_barrier
	s_setprio 1
	v_mfma_f32_16x16x32_bf16 v[54:57], v[200:203], v[168:171], v[54:57]
	v_mfma_f32_16x16x32_bf16 v[46:49], v[212:215], v[168:171], v[46:49]
	v_mfma_f32_16x16x32_bf16 v[38:41], v[200:203], v[176:179], v[38:41]
	v_mfma_f32_16x16x32_bf16 v[30:33], v[212:215], v[176:179], v[30:33]
	v_mfma_f32_16x16x32_bf16 v[22:25], v[200:203], v[184:187], v[22:25]
	v_mfma_f32_16x16x32_bf16 v[14:17], v[212:215], v[184:187], v[14:17]
	v_mfma_f32_16x16x32_bf16 v[6:9], v[200:203], v[192:195], v[6:9]
	v_mfma_f32_16x16x32_bf16 v[2:5], v[212:215], v[192:195], v[2:5]
	v_mfma_f32_16x16x32_bf16 v[54:57], v[208:211], v[172:175], v[54:57]
	v_mfma_f32_16x16x32_bf16 v[46:49], v[216:219], v[172:175], v[46:49]
	v_mfma_f32_16x16x32_bf16 v[38:41], v[208:211], v[180:183], v[38:41]
	v_mfma_f32_16x16x32_bf16 v[30:33], v[216:219], v[180:183], v[30:33]
	v_mfma_f32_16x16x32_bf16 v[22:25], v[208:211], v[188:191], v[22:25]
	v_mfma_f32_16x16x32_bf16 v[14:17], v[216:219], v[188:191], v[14:17]
	v_mfma_f32_16x16x32_bf16 v[6:9], v[208:211], v[196:199], v[6:9]
	v_mfma_f32_16x16x32_bf16 v[2:5], v[216:219], v[196:199], v[2:5]
	s_setprio 0
	s_add_i32 s43, s43, 2
	s_add_u32 s12, s12, 0x100
	s_addc_u32 s13, s13, 0
	s_add_u32 s41, s41, 0x100
	s_addc_u32 s42, s42, 0
	s_cmpk_gt_u32 s43, 0x55
	s_barrier
